# every unit loop (prep_scan, prep_conv, p3_qkv, chunk states, state scan, attention, SSD) renumbered by batch element = blockIdx%8 class; grid barriers 3..7 XCD-local (leader keeps its L2 writeback, sk
# speedup vs baseline: 1.0248x; 1.0051x over previous
; #define LAS __attribute__((address_space(3)))
; __device__ __forceinline__ unsigned xb_add(unsigned* p, unsigned v) { return __hip_atomic_fetch_add(p, v, __ATOMIC_RELAXED, __HIP_MEMORY_SCOPE_AGENT); }
; __device__ __forceinline__ unsigned xb_xcc_id() { return (unsigned)__builtin_amdgcn_s_getreg((3 << 11) | 20) & 0xFu; }
; __device__ __forceinline__ XcdBarrier xcd_barrier_post(unsigned* bar, volatile LAS unsigned* st) {
;     XcdBarrier b; b.bar = bar; b.x = xb_xcc_id(); b.st = st;
;     if (threadIdx.x == 0) (void)xb_add(&bar[XB_XCNT(b.x)], 1u);
;     return b;
; }
_Z14fwd_megakernel4Args:
	s_load_dwordx4 s[92:95], s[0:1], 0xc0
	s_load_dword s34, s[0:1], 0xd0
	s_add_u32 s6, s0, 0xc8
	v_and_b32_e32 v210, 0x3ff, v0
	s_addc_u32 s7, s1, 0
	v_mov_b32_e32 v1, v210
	v_cmp_gt_u32_e32 vcc, 16, v210
	v_lshl_add_u32 v170, v210, 2, 0
	s_and_saveexec_b64 s[4:5], vcc
	v_add_u32_e32 v1, 0x23000, v170
	v_mov_b32_e32 v2, 0
	ds_write_b32 v1, v2
	s_or_b64 exec, exec, s[4:5]
	s_waitcnt lgkmcnt(0)
	s_barrier
	s_add_u32 s38, s92, 0xff40000
	s_getreg_b32 s3, hwreg(HW_REG_XCC_ID, 0, 4)
	s_addc_u32 s39, s93, 0
	s_and_b32 s3, s3, 15
	s_lshl_b32 s42, s3, 6
	v_cmp_eq_u32_e64 s[8:9], 0, v210
	s_mov_b64 s[4:5], exec
	s_nop 0
	v_writelane_b32 v241, s8, 0
	s_nop 1
	v_writelane_b32 v241, s9, 1
	s_and_b64 s[8:9], s[4:5], s[8:9]
	s_mov_b64 exec, s[8:9]
	s_cbranch_execz .LBB0_5
	s_mov_b64 s[8:9], exec
	v_mbcnt_lo_u32_b32 v1, s8, 0
	v_mbcnt_hi_u32_b32 v1, s9, v1
	v_cmp_eq_u32_e32 vcc, 0, v1
	s_and_b64 s[10:11], exec, vcc
	s_mov_b64 exec, s[10:11]
	s_cbranch_execz .LBB0_5
	s_lshl_b32 s10, s42, 2
	s_bcnt1_i32_b64 s8, s[8:9]
	v_mov_b32_e32 v1, s10
	v_mov_b32_e32 v2, s8
	global_atomic_add v1, v2, s[38:39] offset:1024
	s_and_b32 s10, s2, 7
	s_lshl_b32 s10, s10, 3
	s_lshl_b64 s[10:11], 1, s10
	v_mov_b32_e32 v2, s10
	v_mov_b32_e32 v3, s11
	global_atomic_add_x2 v1, v[2:3], s[38:39] offset:1032

; __device__ __forceinline__ unsigned xb_ld(unsigned* p)              { return __hip_atomic_load(p, __ATOMIC_RELAXED, __HIP_MEMORY_SCOPE_AGENT); }
; __device__ __forceinline__ unsigned xb_add(unsigned* p, unsigned v) { return __hip_atomic_fetch_add(p, v, __ATOMIC_RELAXED, __HIP_MEMORY_SCOPE_AGENT); }
; __device__ __forceinline__ void xcd_barrier_complete(unsigned* bar, unsigned x, unsigned& nloc, unsigned& nx) {
;     const unsigned G = gridDim.x * gridDim.y * gridDim.z;
;     unsigned sum, cnt, mine, sp = 0u;
;     for (;;) {
;         sum = 0u; cnt = 0u; mine = 0u;
; #pragma unroll
;         for (unsigned j = 0; j < 16; ++j) { const unsigned c = xb_ld(&bar[XB_XCNT(j)]); sum += c; cnt += (c > 0u) ? 1u : 0u; mine = (j == x) ? c : mine; }
;         if (sum == G) break;
;         __builtin_amdgcn_s_sleep(1);
;         if ((++sp & 255u) == 0u) { if (xb_ld(&bar[XB_TMO])) break; if (sp > XB_SPIN_CAP) { atomicAdd(&bar[XB_TMO], 1u); break; } }
;     }
;     nloc = mine > 0u ? mine : 1u; nx = cnt > 0u ? cnt : 1u;
; }
; __device__ __forceinline__ void xcd_barrier(const XcdBarrier& b) {
;     asm volatile("s_waitcnt vmcnt(0)" ::: "memory");
;     __syncthreads();
;     if (threadIdx.x == 0) {
;         unsigned* bar = b.bar;
;         __builtin_amdgcn_s_waitcnt(0);
;         unsigned nloc = b.st[0], nx = b.st[1];
;         if (nloc == 0u) { xcd_barrier_complete(bar, b.x, nloc, nx); b.st[0] = nloc; b.st[1] = nx; }
;         const unsigned old = xb_add(&bar[XB_XSUB(b.x)], 1u);
;         const unsigned gen = old / nloc;
;         if (old + 1u == (gen + 1u) * nloc) {
;             __builtin_amdgcn_fence(__ATOMIC_RELEASE, "agent");
;             asm volatile("s_waitcnt vmcnt(0)" ::: "memory");
;             const unsigned og = xb_add(&bar[XB_TOP], 1u);
;             const unsigned tg = og / nx;
;             if (og + 1u == (tg + 1u) * nx) xb_add(&bar[XB_TOPGEN], 1u);
;             else XB_SPIN(xb_ld(&bar[XB_TOPGEN]) == tg, bar);
;             __builtin_amdgcn_fence(__ATOMIC_ACQUIRE, "agent");
;             xb_add(&bar[XB_XGEN(b.x)], 1u);
;             asm volatile("s_waitcnt vmcnt(0)" ::: "memory");
;         } else {
;             XB_SPIN(xb_ld(&bar[XB_XGEN(b.x)]) == gen, bar);
;             __builtin_amdgcn_fence(__ATOMIC_ACQUIRE, "agent");
;             asm volatile("s_waitcnt vmcnt(0)" ::: "memory");
;         }
;     }
;     __syncthreads();
; }
.LBB0_108:
	s_add_u32 s88, s92, 0xff40200
	s_addc_u32 s89, s93, 0
	s_add_u32 s14, s92, 0xff40400
	s_addc_u32 s15, s93, 0
	s_add_u32 s62, s92, 0xff40500
	s_addc_u32 s63, s93, 0
	s_add_u32 s36, s92, 0xff40600
	s_addc_u32 s37, s93, 0
	s_add_u32 s70, s92, 0xff40700
	s_mul_i32 s0, s95, s94
	s_addc_u32 s71, s93, 0
	s_mul_i32 s6, s0, s34
	s_add_u32 s34, s92, 0xff40800
	s_addc_u32 s35, s93, 0
	s_add_u32 s96, s92, 0xff40900
	s_addc_u32 s97, s93, 0
	s_add_u32 s56, s92, 0xff40a00
	s_addc_u32 s57, s93, 0
	s_add_u32 s0, s92, 0xff40b00
	s_addc_u32 s1, s93, 0
	v_writelane_b32 v241, s0, 26
	v_writelane_b32 v240, s18, 28
	s_waitcnt vmcnt(0)
	s_nop 0
	v_writelane_b32 v241, s1, 27
	s_add_u32 s0, s92, 0xff40c00
	s_addc_u32 s1, s93, 0
	v_writelane_b32 v241, s0, 28
	v_writelane_b32 v240, s19, 29
	s_barrier
	v_readfirstlane_b32 s100, v210
	s_nop 0
	s_lshr_b32 s100, s100, 6
	s_cmp_lg_u32 s100, 1
	s_cbranch_scc1 .Lbinv_1
	buffer_inv sc1
	s_waitcnt vmcnt(0)
	s_add_u32 s100, s92, 0xff40000
	s_addc_u32 s101, s93, 0
	v_mbcnt_lo_u32_b32 v0, -1, 0
	v_mbcnt_hi_u32_b32 v0, -1, v0
	v_and_b32_e32 v0, 15, v0
	v_lshlrev_b32_e32 v0, 8, v0
	s_mov_b32 s99, 0
.Lcen_loop:
	global_load_dwordx2 v[2:3], v0, s[100:101] offset:1032 sc1
	s_waitcnt vmcnt(0)
	v_sad_u8 v1, v2, 0, 0
	v_sad_u8 v1, v3, 0, v1
	s_nop 1
	v_add_u32_dpp v5, v1, v1 row_ror:8 row_mask:0xf bank_mask:0xf
	s_nop 1
	v_add_u32_dpp v6, v5, v5 row_ror:4 row_mask:0xf bank_mask:0xf
	s_nop 1
	v_add_u32_dpp v7, v6, v6 row_ror:2 row_mask:0xf bank_mask:0xf
	s_nop 1
	v_add_u32_dpp v8, v7, v7 row_ror:1 row_mask:0xf bank_mask:0xf
	s_nop 1
	v_readfirstlane_b32 s98, v8
	s_nop 0
	s_cmp_eq_u32 s98, s94
	s_cbranch_scc1 .Lcen_done
	s_sleep 4
	s_add_i32 s99, s99, 1
	s_cmp_lt_u32 s99, 0x100000
	s_cbranch_scc1 .Lcen_loop
	v_mov_b32_e32 v1, 0
	v_mov_b32_e32 v2, -1
	v_mov_b32_e32 v3, -1
.Lcen_done:
	v_bcnt_u32_b32 v4, v2, 0
	v_bcnt_u32_b32 v4, v3, v4
	v_cmp_eq_u32_e32 vcc, 1, v4
	s_nop 1
	s_mov_b64 s[100:101], vcc
	v_cmp_eq_u32_e32 vcc, 32, v1
	s_nop 1
	s_and_b64 s[100:101], s[100:101], vcc
	v_or_b32_e32 v4, v2, v3
	v_cmp_eq_u32_e32 vcc, 0, v4
	s_nop 1
	s_or_b64 s[100:101], s[100:101], vcc
	s_andn2_b64 s[100:101], exec, s[100:101]
	s_cmp_eq_u64 s[100:101], 0
	s_cselect_b32 s100, 1, 0
	v_mov_b32_e32 v0, 0x23030
	v_mov_b32_e32 v1, s100
	ds_write_b32 v0, v1
	s_waitcnt lgkmcnt(0)
.Lbinv_1:
	s_mov_b32 s99, 0
	v_writelane_b32 v241, s1, 29
	s_add_u32 s0, s92, 0xff40d00
	s_addc_u32 s1, s93, 0
	v_writelane_b32 v241, s0, 30
	s_nop 1
	v_writelane_b32 v241, s1, 31
	s_add_u32 s0, s92, 0xff40e00
	s_addc_u32 s1, s93, 0
	v_writelane_b32 v241, s0, 32
	s_nop 1
	v_writelane_b32 v241, s1, 33
	s_add_u32 s0, s92, 0xff40f00
	s_addc_u32 s1, s93, 0
	v_writelane_b32 v241, s0, 34
	s_nop 1
	v_writelane_b32 v241, s1, 35
	s_add_u32 s0, s92, 0xff41000
	s_addc_u32 s1, s93, 0
	v_writelane_b32 v241, s0, 36
	s_nop 1
	v_writelane_b32 v241, s1, 37
	s_add_u32 s0, s92, 0xff41100
	s_addc_u32 s1, s93, 0
	v_writelane_b32 v241, s0, 38
	s_nop 1
	v_writelane_b32 v241, s1, 39
	s_add_u32 s0, s92, 0xff41200
	s_addc_u32 s1, s93, 0
	v_writelane_b32 v241, s0, 40
	s_nop 1
	v_writelane_b32 v241, s1, 41
	s_add_u32 s0, s92, 0xff41300
	s_addc_u32 s1, s93, 0
	v_writelane_b32 v241, s0, 42
	s_cmp_eq_u32 s3, 15
	s_nop 0
	v_writelane_b32 v241, s1, 43
	s_cselect_b64 s[0:1], -1, 0
	v_writelane_b32 v240, s0, 10
	s_cmp_eq_u32 s3, 14
	s_nop 0
	v_writelane_b32 v240, s1, 11
	s_cselect_b64 s[0:1], -1, 0
	v_writelane_b32 v240, s0, 8
	s_cmp_eq_u32 s3, 13
	s_nop 0
	v_writelane_b32 v240, s1, 9
	s_cselect_b64 s[0:1], -1, 0
	v_writelane_b32 v240, s0, 6
	s_cmp_eq_u32 s3, 12
	s_nop 0
	v_writelane_b32 v240, s1, 7
	s_cselect_b64 s[0:1], -1, 0
	v_writelane_b32 v240, s0, 4
	s_cmp_eq_u32 s3, 11
	s_nop 0
	v_writelane_b32 v240, s1, 5
	s_cselect_b64 s[0:1], -1, 0
	v_writelane_b32 v240, s0, 2
	s_cmp_eq_u32 s3, 10
	s_nop 0
	v_writelane_b32 v240, s1, 3
	s_cselect_b64 s[0:1], -1, 0
	v_writelane_b32 v240, s0, 0
	s_cmp_eq_u32 s3, 9
	s_nop 0
	v_writelane_b32 v240, s1, 1
	s_cselect_b64 s[0:1], -1, 0
	v_writelane_b32 v241, s0, 62
	s_cmp_eq_u32 s3, 8
	s_nop 0
	v_writelane_b32 v241, s1, 63
	s_cselect_b64 s[0:1], -1, 0
	v_writelane_b32 v241, s0, 60
	s_cmp_eq_u32 s3, 7
	s_nop 0
	v_writelane_b32 v241, s1, 61
	s_cselect_b64 s[0:1], -1, 0
	v_writelane_b32 v241, s0, 58
	s_cmp_eq_u32 s3, 6
	s_nop 0
	v_writelane_b32 v241, s1, 59
	s_cselect_b64 s[0:1], -1, 0
	v_writelane_b32 v241, s0, 56
	s_cmp_eq_u32 s3, 5
	s_nop 0
	v_writelane_b32 v241, s1, 57
	s_cselect_b64 s[0:1], -1, 0
	v_writelane_b32 v241, s0, 54
	s_cmp_eq_u32 s3, 4
	s_nop 0
	v_writelane_b32 v241, s1, 55
	s_cselect_b64 s[0:1], -1, 0
	v_writelane_b32 v241, s0, 52
	s_cmp_eq_u32 s3, 3
	s_nop 0
	v_writelane_b32 v241, s1, 53
	s_cselect_b64 s[0:1], -1, 0
	v_writelane_b32 v241, s0, 50
	s_cmp_eq_u32 s3, 2
	s_nop 0
	v_writelane_b32 v241, s1, 51
	s_cselect_b64 s[0:1], -1, 0
	v_writelane_b32 v241, s0, 48
	s_cmp_eq_u32 s3, 1
	s_nop 0
	v_writelane_b32 v241, s1, 49
	s_cselect_b64 s[0:1], -1, 0
	v_writelane_b32 v241, s0, 46
	s_cmp_eq_u32 s3, 0
	s_nop 0
	v_writelane_b32 v241, s1, 47
	s_cselect_b64 s[0:1], -1, 0
	v_writelane_b32 v241, s0, 44
	s_nop 1
	v_writelane_b32 v241, s1, 45
	s_lshl_b32 s0, s42, 2
	s_add_u32 s0, s38, s0
	s_addc_u32 s1, s39, 0
	s_add_u32 s4, s0, 0x1400
	s_addc_u32 s5, s1, 0
	v_writelane_b32 v240, s4, 12
	s_add_u32 s0, s0, 0x2400
	s_addc_u32 s1, s1, 0
	v_writelane_b32 v240, s5, 13
	v_writelane_b32 v240, s0, 14
	v_readlane_b32 s4, v241, 0
	v_readlane_b32 s5, v241, 1
	v_writelane_b32 v240, s1, 15
	s_add_u32 s0, s92, 0xff43400
	s_addc_u32 s1, s93, 0
	v_writelane_b32 v240, s0, 16
	s_nop 1
	v_writelane_b32 v240, s1, 17
	s_add_u32 s0, s92, 0xff43500
	s_addc_u32 s1, s93, 0
	v_writelane_b32 v240, s0, 18
	s_nop 1
	v_writelane_b32 v240, s1, 19
	s_and_saveexec_b64 s[0:1], s[4:5]
	s_cbranch_execz .LBB0_160
	s_add_i32 s3, 0, 0x23020
	v_mov_b32_e32 v0, s3
	s_waitcnt vmcnt(0) expcnt(0) lgkmcnt(0)
	ds_read_b32 v2, v0
	s_add_i32 s3, 0, 0x23024
	v_mov_b32_e32 v0, s3
	ds_read_b32 v0, v0
	s_waitcnt lgkmcnt(1)
	v_cmp_ne_u32_e32 vcc, 0, v2
	s_cbranch_vccnz .LBB0_124
	s_mov_b32 s3, 1
	v_mov_b32_e32 v16, 0
	s_branch .LBB0_112

; __device__ __forceinline__ unsigned xb_ld(unsigned* p)              { return __hip_atomic_load(p, __ATOMIC_RELAXED, __HIP_MEMORY_SCOPE_AGENT); }
; __device__ __forceinline__ unsigned xb_add(unsigned* p, unsigned v) { return __hip_atomic_fetch_add(p, v, __ATOMIC_RELAXED, __HIP_MEMORY_SCOPE_AGENT); }
; #define XB_SPIN(cond, bar) do { unsigned _sp = 0; while (cond) { __builtin_amdgcn_s_sleep(1); \
;     if ((++_sp & 255u) == 0u) { if (xb_ld(&(bar)[XB_TMO])) break; if (_sp > XB_SPIN_CAP) { atomicAdd(&(bar)[XB_TMO], 1u); break; } } } } while (0)
; __device__ __forceinline__ void xcd_barrier(const XcdBarrier& b) {
;     ...
;         const unsigned old = xb_add(&bar[XB_XSUB(b.x)], 1u);
;         const unsigned gen = old / nloc;
;         if (old + 1u == (gen + 1u) * nloc) {
;             __builtin_amdgcn_fence(__ATOMIC_RELEASE, "agent");
;             asm volatile("s_waitcnt vmcnt(0)" ::: "memory");
;             const unsigned og = xb_add(&bar[XB_TOP], 1u);
;             const unsigned tg = og / nx;
;             if (og + 1u == (tg + 1u) * nx) xb_add(&bar[XB_TOPGEN], 1u);
;             else XB_SPIN(xb_ld(&bar[XB_TOPGEN]) == tg, bar);
;             __builtin_amdgcn_fence(__ATOMIC_ACQUIRE, "agent");
;             xb_add(&bar[XB_XGEN(b.x)], 1u);
;             asm volatile("s_waitcnt vmcnt(0)" ::: "memory");
;         } else {
;             XB_SPIN(xb_ld(&bar[XB_XGEN(b.x)]) == gen, bar);
.LBB0_126:
	s_or_b64 exec, exec, s[16:17]
	v_cvt_f32_u32_e32 v4, v2
	s_waitcnt vmcnt(0)
	v_readfirstlane_b32 s3, v3
	v_sub_u32_e32 v3, 0, v2
	v_rcp_iflag_f32_e32 v4, v4
	v_add_u32_e32 v5, s3, v1
	v_mul_f32_e32 v4, 0x4f7ffffe, v4
	v_cvt_u32_f32_e32 v4, v4
	v_mul_lo_u32 v1, v3, v4
	v_mul_hi_u32 v1, v4, v1
	v_add_u32_e32 v1, v4, v1
	v_mul_hi_u32 v1, v5, v1
	v_mul_lo_u32 v3, v1, v2
	v_sub_u32_e32 v3, v5, v3
	v_add_u32_e32 v4, 1, v1
	v_cmp_ge_u32_e32 vcc, v3, v2
	s_nop 1
	v_cndmask_b32_e32 v1, v1, v4, vcc
	v_sub_u32_e32 v4, v3, v2
	v_cndmask_b32_e32 v3, v3, v4, vcc
	v_add_u32_e32 v4, 1, v1
	v_cmp_ge_u32_e32 vcc, v3, v2
	v_add_u32_e32 v3, 1, v5
	s_nop 0
	v_cndmask_b32_e32 v1, v1, v4, vcc
	v_mul_lo_u32 v4, v2, v1
	v_add_u32_e32 v2, v4, v2
	v_cmp_ne_u32_e32 vcc, v3, v2
	s_and_saveexec_b64 s[16:17], vcc
	s_xor_b64 s[16:17], exec, s[16:17]
	s_cbranch_execz .LBB0_140
	v_readlane_b32 s4, v240, 14
	s_waitcnt lgkmcnt(0)
	v_mov_b32_e32 v0, 0
	v_readlane_b32 s5, v240, 15
	s_nop 4
	v_readfirstlane_b32 s98, v1
	s_mov_b32 s99, 1
	v_cmp_ne_u32_e32 vcc, v1, v1
	s_and_saveexec_b64 s[18:19], vcc
	s_cbranch_execz .LBB0_139
	s_mov_b32 s3, 1
	s_mov_b64 s[20:21], 0
	s_branch .LBB0_130

; __device__ __forceinline__ int opaque_tid() { int t = threadIdx.x; asm volatile("" : "+v"(t)); return t; }
; #define LAS __attribute__((address_space(3)))
; __device__ __forceinline__ void transpose_item(const float* W, int K, int N, bf16* WT, const float* gain, LAS float* scr, int item, int nblk, int lane) {
;     const int kb = item / nblk, nb = item % nblk, k0 = 64 * kb, n0 = 64 * nb;
;     const int kr = lane >> 4, nc = 4 * (lane & 15);
;     const bool ok = (n0 + nc) < N;
;     f32x4 v[16];
; #pragma unroll
;     for (int i = 0; i < 16; ++i) { v[i] = (f32x4){0.f, 0.f, 0.f, 0.f}; if (ok) v[i] = *(const f32x4*)(W + (size_t)(k0 + 4 * i + kr) * N + n0 + nc); }
; __device__ __forceinline__ void p0b_mlp_weights(const Args& a, LAS unsigned char* lds) {
;     const int tid = opaque_tid(), lane = tid & 63, wave = tid >> 6;
;     LAS float* scr = (LAS float*)(lds + wave * 16640);
;     const int gw = blockIdx.x * NWAVES + wave, NGW = gridDim.x * NWAVES;
;     constexpr int I_UP = (D_ / 64) * (FF / 64), I_DN = (FF / 64) * (D_ / 64);
;     for (int it = gw; it < I_UP + I_DN; it += NGW) {
;         if (it < I_UP) transpose_item(a.w_up, D_, FF, (bf16*)(a.ws + WS_WUP), a.ln_mlp_g, scr, it, FF / 64, lane);
;         else transpose_item(a.w_dn, FF, D_, (bf16*)(a.ws + WS_WDN), nullptr, scr, it - I_UP, D_ / 64, lane);
;     }
.LBB0_160:
	s_or_b64 exec, exec, s[0:1]
	s_cmpk_lt_i32 s2, 0x200
	v_mov_b32_e32 v12, v210
	s_cselect_b64 s[16:17], -1, 0
	s_waitcnt lgkmcnt(0)
	s_barrier
	v_writelane_b32 v130, s0, 0
	v_writelane_b32 v130, s10, 1
	v_writelane_b32 v130, s11, 2
	v_writelane_b32 v130, s20, 3
	v_writelane_b32 v130, s21, 4
	v_writelane_b32 v130, s22, 5
	v_writelane_b32 v130, s23, 6
	v_writelane_b32 v130, s24, 7
	v_writelane_b32 v130, s25, 8
	v_writelane_b32 v130, s26, 9
	v_writelane_b32 v130, s42, 10
	v_writelane_b32 v130, s43, 11
	v_writelane_b32 v130, s44, 12
	v_writelane_b32 v130, s45, 13
	v_writelane_b32 v130, s50, 14
	v_writelane_b32 v130, s51, 15
	v_writelane_b32 v130, s64, 16
	v_writelane_b32 v130, s65, 17
	v_writelane_b32 v130, s66, 18
	v_writelane_b32 v130, s67, 19
	v_writelane_b32 v130, s68, 20
	v_writelane_b32 v130, s69, 21
	v_writelane_b32 v130, s70, 22
	v_writelane_b32 v130, s71, 23
	v_writelane_b32 v130, s72, 24
	v_writelane_b32 v130, s73, 25
	v_writelane_b32 v130, s74, 26
	v_writelane_b32 v130, s75, 27
	v_writelane_b32 v130, s76, 28
	v_writelane_b32 v130, s77, 29
	v_writelane_b32 v130, s78, 30
	v_writelane_b32 v130, s79, 31
	v_writelane_b32 v130, s33, 32
	v_writelane_b32 v130, s40, 33
	s_lshl_b32 s40, s94, 2
	s_lshl_b32 s33, s94, 8
	s_add_u32 s10, s92, 0xf6a0000
	v_mov_b32_e32 v0, v210
	s_addc_u32 s11, s93, 0
	v_readlane_b32 s0, v241, 19
	v_ashrrev_i32_e32 v1, 6, v0
	s_add_u32 s50, s92, 0xeea0000
	v_add_u32_e32 v84, s0, v1
	v_add_u32_e32 v84, 0x400, v84
	s_lshl_b32 s100, s94, 2
	v_subrev_u32_e32 v84, s100, v84
	v_subrev_u32_e32 v2, 0x400, v84
	s_movk_i32 s20, 0x400
	s_addc_u32 s51, s93, 0
	v_cmp_gt_u32_e32 vcc, s20, v2
	s_and_saveexec_b64 s[20:21], vcc
	v_readlane_b32 s64, v241, 2
	v_readlane_b32 s72, v241, 10
	v_readlane_b32 s73, v241, 11
	v_readlane_b32 s74, v241, 12
	v_readlane_b32 s75, v241, 13
	v_readlane_b32 s76, v241, 14
	v_readlane_b32 s77, v241, 15
	v_readlane_b32 s78, v241, 16
	v_readlane_b32 s79, v241, 17
	v_readlane_b32 s65, v241, 3
	v_readlane_b32 s66, v241, 4
	v_readlane_b32 s67, v241, 5
	v_readlane_b32 s68, v241, 6
	v_readlane_b32 s69, v241, 7
	v_readlane_b32 s70, v241, 8
	v_readlane_b32 s71, v241, 9
	s_cbranch_execz .Lw1_554
	s_movk_i32 s24, 0x4100
	v_mul_lo_u32 v2, v1, s24
	v_add_u32_e32 v3, 0, v2
	v_bfe_u32 v85, v0, 4, 2
	v_lshlrev_b32_e32 v2, 2, v0
	v_bfe_u32 v87, v0, 3, 3
	v_lshlrev_b32_e32 v0, 3, v0
	v_and_b32_e32 v6, 56, v0
	v_and_b32_e32 v86, 60, v2
	v_mul_u32_u24_e32 v0, 0x104, v6
	v_lshlrev_b32_e32 v7, 2, v87
	v_lshlrev_b32_e32 v2, 2, v86
	v_add3_u32 v88, v3, v0, v7
	v_mov_b32_e32 v0, 0
	v_readlane_b32 s0, v241, 18
	v_add_u32_e32 v4, v3, v2
	v_mul_u32_u24_e32 v5, 0x104, v85
	v_mov_b32_e32 v3, v0
	v_lshl_add_u32 v96, v1, 6, s0
	v_add_u32_e32 v96, 0x10000, v96
	s_lshl_b32 s101, s94, 8
	v_subrev_u32_e32 v96, s101, v96
	v_lshlrev_b32_e32 v1, 2, v1
	s_cmp_lg_u64 s[72:73], 0
	v_lshl_add_u64 v[68:69], s[76:77], 0, v[2:3]
	v_lshl_add_u64 v[70:71], s[74:75], 0, v[2:3]
	v_lshlrev_b32_e32 v2, 1, v6
	v_lshl_add_u32 v1, s2, 5, v1
	v_add_u32_e32 v98, v4, v5
	s_mov_b64 s[22:23], 0
	s_cselect_b64 s[42:43], -1, 0
	v_or_b32_e32 v89, 8, v87
	v_or_b32_e32 v90, 16, v87
	v_or_b32_e32 v91, 24, v87
	v_or_b32_e32 v92, 32, v87
	v_or_b32_e32 v93, 40, v87
	v_or_b32_e32 v94, 48, v87
	v_or_b32_e32 v95, 56, v87
	v_lshl_add_u64 v[72:73], s[10:11], 0, v[2:3]
	v_lshl_add_u64 v[74:75], s[50:51], 0, v[2:3]
	v_add_u32_e32 v97, 0x40000, v1
	s_lshl_b32 s101, s94, 4
	v_subrev_u32_e32 v97, s101, v97
	s_lshl_b32 s26, s94, 4
	v_add_u32_e32 v99, 0x410, v98
	v_add_u32_e32 v100, 0x418, v98
	v_add_u32_e32 v101, 0x820, v98
	v_add_u32_e32 v102, 0x828, v98
	v_add_u32_e32 v103, 0xc30, v98
	v_add_u32_e32 v104, 0xc38, v98
	v_add_u32_e32 v105, 0x1040, v98
	v_add_u32_e32 v106, 0x1048, v98
	v_add_u32_e32 v107, 0x1450, v98
	v_add_u32_e32 v108, 0x1458, v98
	v_add_u32_e32 v109, 0x1860, v98
	v_add_u32_e32 v110, 0x1868, v98
	v_add_u32_e32 v111, 0x1c70, v98
	v_add_u32_e32 v112, 0x1c78, v98
	v_add_u32_e32 v113, 0x2080, v98
	v_add_u32_e32 v114, 0x2088, v98
	v_add_u32_e32 v115, 0x2490, v98
	v_add_u32_e32 v116, 0x2498, v98
	v_add_u32_e32 v117, 0x28a0, v98
	v_add_u32_e32 v118, 0x28a8, v98
	v_add_u32_e32 v119, 0x2cb0, v98
	v_add_u32_e32 v120, 0x2cb8, v98
	v_add_u32_e32 v121, 0x30c0, v98
	v_add_u32_e32 v122, 0x30c8, v98
	v_add_u32_e32 v123, 0x34d0, v98
	s_branch .Lw1_517

;     __host__ __device__ bool next(int i, Unit& u) const {
;         const long L = (long)i * G + c; if (L >= nwg) return false;
;         int wgid = (int)L; { const int q = nwg / NXCD, r = nwg % NXCD, xcd = wgid % NXCD, off = wgid / NXCD; wgid = (xcd < r ? xcd * (q + 1) : r * (q + 1) + (xcd - r) * q) + off; }
;         const int nig = WGM * nN, gid = wgid / nig, fm = gid * WGM, gsz = (nM - fm) < WGM ? (nM - fm) : WGM;
;         u.pm = fm + ((wgid % nig) % gsz); u.pn = (wgid % nig) / gsz; return true;
; __device__ __forceinline__ void xcd_barrier(const XcdBarrier& b) {
;     ...
;     __syncthreads();
; }
.Lgb1_done:
	v_mov_b32_e32 v12, v210
	s_waitcnt vmcnt(0) lgkmcnt(0)
	s_barrier
	s_movk_i32 s38, 0x400
	v_readfirstlane_b32 s24, v12
	s_and_b64 vcc, exec, s[16:17]
	v_writelane_b32 v241, s56, 24
	s_nop 1
	v_writelane_b32 v241, s57, 25
	s_cbranch_vccz .LBB0_166
	s_ashr_i32 s0, s2, 31
	s_lshr_b32 s0, s0, 29
	s_add_i32 s3, s2, s0
	s_and_b32 s0, s3, -8
	s_sub_i32 s18, s2, s0
	s_cmp_gt_i32 s18, -1
	s_cbranch_scc0 .LBB0_163
	s_lshl_b32 s19, s18, 6
	s_cbranch_execz .LBB0_164
	s_branch .LBB0_165

; __device__ __forceinline__ unsigned xb_add(unsigned* p, unsigned v) { return __hip_atomic_fetch_add(p, v, __ATOMIC_RELAXED, __HIP_MEMORY_SCOPE_AGENT); }
; __device__ __forceinline__ void xcd_barrier(const XcdBarrier& b) {
;     asm volatile("s_waitcnt vmcnt(0)" ::: "memory");
;     __syncthreads();
;     if (threadIdx.x == 0) {
;         unsigned* bar = b.bar;
;         __builtin_amdgcn_s_waitcnt(0);
;         unsigned nloc = b.st[0], nx = b.st[1];
;         if (nloc == 0u) { xcd_barrier_complete(bar, b.x, nloc, nx); b.st[0] = nloc; b.st[1] = nx; }
;         const unsigned old = xb_add(&bar[XB_XSUB(b.x)], 1u);
;         const unsigned gen = old / nloc;
;         if (old + 1u == (gen + 1u) * nloc) {
;             __builtin_amdgcn_fence(__ATOMIC_RELEASE, "agent");
.LBB0_205:
	s_waitcnt vmcnt(0)
	v_readlane_b32 s0, v241, 0
	v_readlane_b32 s1, v241, 1
	s_waitcnt vmcnt(0) lgkmcnt(0)
	s_barrier
	v_readfirstlane_b32 s100, v210
	s_nop 0
	s_lshr_b32 s100, s100, 6
	s_cmp_lg_u32 s100, 1
	s_cbranch_scc1 .Lbinv_2
	buffer_inv sc1
	s_waitcnt vmcnt(0)
.Lbinv_2:
	s_mov_b32 s99, 0
	s_and_saveexec_b64 s[16:17], s[0:1]
	s_cbranch_execz .LBB0_257
	s_add_i32 s3, 0, 0x23020
	v_mov_b32_e32 v0, s3
	s_waitcnt vmcnt(0) expcnt(0) lgkmcnt(0)
	ds_read_b32 v2, v0
	s_add_i32 s3, 0, 0x23024
	v_mov_b32_e32 v0, s3
	ds_read_b32 v0, v0
	s_waitcnt lgkmcnt(1)
	v_cmp_ne_u32_e32 vcc, 0, v2
	s_cbranch_vccnz .LBB0_221
	s_mov_b32 s3, 1
	v_mov_b32_e32 v16, 0
	s_branch .LBB0_209

; __device__ __forceinline__ int opaque_tid() { int t = threadIdx.x; asm volatile("" : "+v"(t)); return t; }
; #define LAS __attribute__((address_space(3)))
; __device__ __forceinline__ float softplus(float v) { return v > 20.f ? v : log1pf(__expf(v)); }
; __device__ __forceinline__ void prep_scan(const Args& a, LAS unsigned char* lds) {
;     const int tid = opaque_tid(), lane = tid & 63, wave = tid >> 6;
;     const float* dtraw = (const float*)(a.ws + WS_DTRAW);
;     float* vec = (float*)(a.ws + WS_VEC);
;     const size_t VS = (size_t)NB * 8 * S_;
;     LAS float* red = (LAS float*)lds;
;     for (int item = (int)gridDim.x - 1 - (int)blockIdx.x; item < NB * 8; item += gridDim.x) {
;         const int b = item >> 3, hd = item & 7;
;         float* vb = vec + ((size_t)b * 8 + hd) * S_;
;         const float af_c = -__expf(a.a_log_f[hd]) * LOG2E, ab_c = -__expf(a.a_log_b[hd]) * LOG2E;
;         const float bf_ = a.dt_bias_f[hd], bb_ = a.dt_bias_b[hd];
;         const int t0 = tid * 4;
;         float dtf[4], dtb[4], pf[4], pb[4]; float sf = 0.f, sb = 0.f;
; #pragma unroll
;         for (int i = 0; i < 4; ++i) { const float* p = dtraw + (size_t)(b * S_ + t0 + i) * 16; dtf[i] = softplus(p[hd] + bf_); dtb[i] = softplus(p[8 + hd] + bb_); }
.LBB0_302:
	s_and_b32 s76, s26, 7
	s_sub_i32 s76, 7, s76
	s_ashr_i32 s41, s26, 3
	s_lshl_b32 s24, s41, 2
	v_lshl_add_u32 v14, s76, 11, v8
	s_add_u32 s88, s20, s24
	v_ashrrev_i32_e32 v15, 31, v14
	s_addc_u32 s89, s21, 0
	v_lshlrev_b64 v[0:1], 6, v[14:15]
	v_lshl_add_u64 v[2:3], s[88:89], 0, v[0:1]
	v_readlane_b32 s56, v241, 2
	v_mov_b32_e32 v4, s24
	global_load_dword v0, v[2:3], off
	global_load_dword v11, v4, s[82:83]
	global_load_dword v18, v4, s[86:87]
	global_load_dword v16, v4, s[84:85]
	v_readlane_b32 s57, v241, 3
	v_readlane_b32 s58, v241, 4
	v_readlane_b32 s59, v241, 5
	v_readlane_b32 s60, v241, 6
	v_readlane_b32 s61, v241, 7
	v_readlane_b32 s62, v241, 8
	global_load_dword v17, v4, s[56:57]
	v_readlane_b32 s63, v241, 9
	v_readlane_b32 s64, v241, 10
	v_readlane_b32 s65, v241, 11
	v_readlane_b32 s66, v241, 12
	v_readlane_b32 s67, v241, 13
	v_readlane_b32 s68, v241, 14
	v_readlane_b32 s69, v241, 15
	v_readlane_b32 s70, v241, 16
	v_readlane_b32 s71, v241, 17
	s_waitcnt vmcnt(0)
	v_add_f32_e32 v0, v18, v0
	v_cmp_nlt_f32_e32 vcc, s27, v0
	s_and_saveexec_b64 s[24:25], vcc
	s_cbranch_execz .LBB0_304
	v_mul_f32_e32 v0, 0x3fb8aa3b, v0
	v_exp_f32_e32 v15, v0
	s_nop 0
	v_add_f32_e32 v4, 1.0, v15
	v_frexp_mant_f32_e32 v6, v4
	v_cvt_f64_f32_e32 v[0:1], v4
	v_frexp_exp_i32_f64_e32 v0, v[0:1]
	v_cmp_gt_f32_e32 vcc, s28, v6
	v_add_f32_e32 v5, -1.0, v4
	v_sub_f32_e32 v7, v5, v4
	v_subbrev_co_u32_e32 v19, vcc, 0, v0, vcc
	v_sub_u32_e32 v0, 0, v19
	v_sub_f32_e32 v5, v15, v5
	v_add_f32_e32 v7, 1.0, v7
	v_ldexp_f32 v1, v4, v0
	v_add_f32_e32 v5, v5, v7
	v_add_f32_e32 v4, -1.0, v1
	v_add_f32_e32 v6, 1.0, v1
	v_ldexp_f32 v0, v5, v0
	v_add_f32_e32 v5, 1.0, v4
	v_add_f32_e32 v7, -1.0, v6
	v_sub_f32_e32 v5, v1, v5
	v_sub_f32_e32 v1, v1, v7
	v_add_f32_e32 v5, v0, v5
	v_add_f32_e32 v0, v0, v1
	v_add_f32_e32 v13, v6, v0
	v_rcp_f32_e32 v23, v13
	v_sub_f32_e32 v1, v13, v6
	v_sub_f32_e32 v22, v0, v1
	v_add_f32_e32 v1, v4, v5
	v_mul_f32_e32 v25, v1, v23
	v_sub_f32_e32 v0, v1, v4
	v_mul_f32_e32 v4, v13, v25
	v_fma_f32 v6, v25, v13, -v4
	v_fmac_f32_e32 v6, v25, v22
	v_sub_f32_e32 v24, v5, v0
	v_add_f32_e32 v0, v4, v6
	v_sub_f32_e32 v5, v1, v0
	v_pk_add_f32 v[20:21], v[0:1], v[4:5] neg_lo:[0,1] neg_hi:[0,1]
	v_mov_b32_e32 v7, v0
	v_pk_add_f32 v[0:1], v[20:21], v[6:7] neg_lo:[0,1] neg_hi:[0,1]
	v_cmp_neq_f32_e32 vcc, s30, v15
	v_add_f32_e32 v1, v24, v1
	v_add_f32_e32 v0, v0, v1
	v_add_f32_e32 v1, v5, v0
	v_mul_f32_e32 v24, v23, v1
	v_mul_f32_e32 v4, v13, v24
	v_fma_f32 v6, v24, v13, -v4
	v_fmac_f32_e32 v6, v24, v22
	v_sub_f32_e32 v5, v5, v1
	v_add_f32_e32 v13, v0, v5
	v_add_f32_e32 v0, v4, v6
	v_sub_f32_e32 v5, v1, v0
	v_pk_add_f32 v[20:21], v[0:1], v[4:5] neg_lo:[0,1] neg_hi:[0,1]
	v_mov_b32_e32 v7, v0
	v_pk_add_f32 v[0:1], v[20:21], v[6:7] neg_lo:[0,1] neg_hi:[0,1]
	s_nop 0
	v_add_f32_e32 v1, v13, v1
	v_add_f32_e32 v0, v0, v1
	v_add_f32_e32 v1, v25, v24
	v_add_f32_e32 v0, v5, v0
	v_sub_f32_e32 v4, v1, v25
	v_mul_f32_e32 v0, v23, v0
	v_sub_f32_e32 v4, v24, v4
	v_add_f32_e32 v4, v4, v0
	v_add_f32_e32 v6, v1, v4
	v_mul_f32_e32 v7, v6, v6
	v_fmamk_f32 v0, v7, 0x3e9b6dac, v49
	v_fmaak_f32 v13, v7, v0, 0x3f2aaada
	v_cvt_f32_i32_e32 v0, v19
	v_sub_f32_e32 v1, v6, v1
	v_sub_f32_e32 v1, v4, v1
	v_ldexp_f32 v19, v1, 1
	v_mul_f32_e32 v1, v6, v7
	v_ldexp_f32 v5, v6, 1
	v_pk_mul_f32 v[6:7], v[0:1], v[12:13]
	s_nop 0
	v_fma_f32 v4, v0, s29, -v6
	v_fmac_f32_e32 v4, 0xb102e308, v0
	v_pk_add_f32 v[0:1], v[6:7], v[4:5]
	v_mov_b32_e32 v20, v6
	v_sub_f32_e32 v5, v1, v5
	v_sub_f32_e32 v5, v7, v5
	v_add_f32_e32 v21, v19, v5
	v_pk_add_f32 v[6:7], v[0:1], v[6:7] neg_lo:[0,1] neg_hi:[0,1]
	v_pk_add_f32 v[22:23], v[0:1], v[20:21]
	v_mov_b32_e32 v5, v0
	v_mov_b32_e32 v7, v23
	v_pk_add_f32 v[24:25], v[4:5], v[6:7] neg_lo:[0,1] neg_hi:[0,1]
	v_pk_add_f32 v[4:5], v[4:5], v[6:7]
	v_mov_b32_e32 v20, v21
	v_pk_add_f32 v[6:7], v[4:5], v[0:1] op_sel:[1,0] op_sel_hi:[0,1] neg_lo:[0,1] neg_hi:[0,1]
	v_pk_add_f32 v[26:27], v[22:23], v[6:7] op_sel_hi:[1,0] neg_lo:[0,1] neg_hi:[0,1]
	v_mov_b32_e32 v22, v23
	v_mov_b32_e32 v23, v5
	v_pk_mov_b32 v[6:7], v[0:1], v[6:7] op_sel:[1,0]
	v_mov_b32_e32 v21, v0
	v_pk_add_f32 v[6:7], v[22:23], v[6:7] neg_lo:[0,1] neg_hi:[0,1]
	v_mov_b32_e32 v26, v24
	v_pk_add_f32 v[0:1], v[20:21], v[6:7] neg_lo:[0,1] neg_hi:[0,1]
	v_mov_b32_e32 v25, v5
	v_pk_add_f32 v[6:7], v[26:27], v[0:1]
	s_nop 0
	v_pk_add_f32 v[20:21], v[6:7], v[6:7] op_sel:[0,1] op_sel_hi:[1,0]
	s_nop 0
	v_pk_add_f32 v[4:5], v[4:5], v[20:21] op_sel:[1,0] op_sel_hi:[0,1]
	v_mov_b32_e32 v7, v4
	v_pk_add_f32 v[22:23], v[6:7], v[24:25] neg_lo:[0,1] neg_hi:[0,1]
	v_mov_b32_e32 v1, v20
	v_sub_f32_e32 v5, v6, v22
	v_pk_add_f32 v[0:1], v[0:1], v[22:23] neg_lo:[0,1] neg_hi:[0,1]
	v_sub_f32_e32 v5, v24, v5
	v_add_f32_e32 v0, v0, v5
	v_add_f32_e32 v0, v0, v1
	v_add_f32_e32 v0, v4, v0
	v_cndmask_b32_e32 v0, v50, v0, vcc
	v_cmp_ngt_f32_e32 vcc, -1.0, v15
	s_nop 1
	v_cndmask_b32_e32 v0, v51, v0, vcc
	v_cmp_neq_f32_e32 vcc, -1.0, v15
	s_nop 1
	v_cndmask_b32_e32 v0, v52, v0, vcc
	v_cmp_lt_f32_e64 vcc, |v15|, s31
	s_nop 1
	v_cndmask_b32_e32 v0, v0, v15, vcc

; __device__ __forceinline__ void prep_conv(const Args& a, LAS unsigned char* lds) {
;     ...
;     for (int item = blockIdx.x; item < NB * 32 * 2; item += gridDim.x) {
;         const int half = (item ^ (item >> 8)) & 1, tb = (item >> 1) & 31, b = item >> 6;
;         const int ch = half * 512 + cg8 * 8, t0 = tb * 64 + tq * 8;
;         u32x4 rows[12];
; #pragma unroll
;         for (int k = 0; k < 12; ++k) { const int tt = t0 - 2 + k; rows[k] = (u32x4){0u, 0u, 0u, 0u}; if (tt >= 0 && tt < S_) rows[k] = *(const u32x4*)(proj + (size_t)(b * S_ + tt) * NPROJ + C_XBC + ch); }
.LBB0_340:
	s_lshr_b32 s20, s55, 8
	s_lshr_b32 s26, s55, 2
	s_xor_b32 s20, s20, s26
	s_and_b32 s26, s20, 1
	s_bfe_u32 s20, s55, 0x50003
	s_lshl_b32 s20, s20, 6
	v_add_u32_e32 v116, s20, v143
	s_and_b32 s46, s55, 7
	v_lshl_or_b32 v6, s26, 9, v142
	v_add_u32_e32 v0, -2, v116
	s_lshl_b32 s27, s46, 11
	v_cmp_gt_u32_e32 vcc, s53, v0
	v_lshlrev_b32_e32 v4, 1, v6
	v_mov_b32_e32 v76, 0
	v_mov_b32_e32 v77, 0
	v_mov_b32_e32 v78, 0
	v_mov_b32_e32 v79, 0
	s_and_saveexec_b64 s[24:25], vcc
	s_cbranch_execz .LBB0_342
	v_or_b32_e32 v0, s27, v0
	v_ashrrev_i32_e32 v1, 31, v0
	v_lshlrev_b64 v[0:1], 12, v[0:1]
	v_lshl_add_u64 v[0:1], s[92:93], 0, v[0:1]
	v_mov_b32_e32 v5, v97
	v_lshl_add_u64 v[0:1], v[0:1], 0, v[4:5]
	global_load_dwordx4 v[76:79], v[0:1], off offset:1856

; __device__ __forceinline__ unsigned xb_ld(unsigned* p)              { return __hip_atomic_load(p, __ATOMIC_RELAXED, __HIP_MEMORY_SCOPE_AGENT); }
; __device__ __forceinline__ unsigned xb_add(unsigned* p, unsigned v) { return __hip_atomic_fetch_add(p, v, __ATOMIC_RELAXED, __HIP_MEMORY_SCOPE_AGENT); }
; #define XB_SPIN(cond, bar) do { unsigned _sp = 0; while (cond) { __builtin_amdgcn_s_sleep(1); \
;     if ((++_sp & 255u) == 0u) { if (xb_ld(&(bar)[XB_TMO])) break; if (_sp > XB_SPIN_CAP) { atomicAdd(&(bar)[XB_TMO], 1u); break; } } } } while (0)
; __device__ __forceinline__ void xcd_barrier(const XcdBarrier& b) {
;     ...
;         if (old + 1u == (gen + 1u) * nloc) {
;             __builtin_amdgcn_fence(__ATOMIC_RELEASE, "agent");
;             asm volatile("s_waitcnt vmcnt(0)" ::: "memory");
;             const unsigned og = xb_add(&bar[XB_TOP], 1u);
;             const unsigned tg = og / nx;
;             if (og + 1u == (tg + 1u) * nx) xb_add(&bar[XB_TOPGEN], 1u);
;             else XB_SPIN(xb_ld(&bar[XB_TOPGEN]) == tg, bar);
;             __builtin_amdgcn_fence(__ATOMIC_ACQUIRE, "agent");
;             xb_add(&bar[XB_XGEN(b.x)], 1u);
.LBB0_430:
	s_andn2_saveexec_b64 s[24:25], s[24:25]
	s_cbranch_execz .LBB0_450
	s_mov_b64 s[24:25], exec
	buffer_wbl2 sc1
	s_waitcnt lgkmcnt(0)
	s_waitcnt vmcnt(0)
	v_mov_b32_e32 v3, 0x23030
	ds_read_b32 v3, v3
	s_waitcnt lgkmcnt(0)
	v_readfirstlane_b32 s100, v3
	s_nop 0
	s_cmp_lg_u32 s100, 0
	s_cbranch_scc1 .Lloc_3
	v_mbcnt_lo_u32_b32 v1, s24, 0
	v_mbcnt_hi_u32_b32 v1, s25, v1
	v_cmp_eq_u32_e32 vcc, 0, v1
	s_and_saveexec_b64 s[38:39], vcc
	s_cbranch_execz .LBB0_433
	s_bcnt1_i32_b64 s24, s[24:25]
	v_readlane_b32 s0, v240, 16
	v_mov_b32_e32 v2, 0
	v_mov_b32_e32 v3, s24
	v_readlane_b32 s1, v240, 17
	s_nop 4
	global_atomic_add v2, v2, v3, s[0:1] sc0

; __device__ __forceinline__ unsigned xb_add(unsigned* p, unsigned v) { return __hip_atomic_fetch_add(p, v, __ATOMIC_RELAXED, __HIP_MEMORY_SCOPE_AGENT); }
; __device__ __forceinline__ void xcd_barrier(const XcdBarrier& b) {
;     ...
;             xb_add(&bar[XB_XGEN(b.x)], 1u);
;             asm volatile("s_waitcnt vmcnt(0)" ::: "memory");
.Lloc_3:
	s_mov_b64 s[24:25], exec
	v_mbcnt_lo_u32_b32 v0, s24, 0
	v_mbcnt_hi_u32_b32 v0, s25, v0
	v_cmp_eq_u32_e32 vcc, 0, v0
	s_waitcnt vmcnt(0)
	s_and_saveexec_b64 s[38:39], vcc
	s_cbranch_execz .LBB0_449
	s_bcnt1_i32_b64 s24, s[24:25]
	v_readlane_b32 s0, v240, 14
	v_mov_b32_e32 v0, 0
	v_mov_b32_e32 v1, s24
	v_readlane_b32 s1, v240, 15
	s_nop 4
	global_atomic_add v0, v1, s[0:1]

; __device__ __forceinline__ void p3_qkv(const Args& a, LAS unsigned char* lds) {
;     ...
;     for (int item = blockIdx.x; item < T_ / 64; item += gridDim.x) {
;         __syncthreads();
;         for (int i0 = 0; i0 < 8; i0 += 4) {
;           u32x2 cq_[4], q0_[4], q1_[4], q2_[4], k0_[4], k1_[4], k2_[4]; unsigned ckv_[4]; u32x4 vv_[4]; int pos_[4];
; #pragma unroll
;           for (int u = 0; u < 4; ++u) {
;             const int t = item * 64 + wave * 8 + i0 + u; const bf16* pr = proj + (size_t)t * NPROJ;
;             cq_[u] = *(const u32x2*)(pr + C_CQ + 4 * lane); ckv_[u] = *(const unsigned*)(pr + C_CKV + 2 * lane);
;             q0_[u] = *(const u32x2*)(qraw + (size_t)t * 768 + hd * 96 + 4 * sub); q1_[u] = *(const u32x2*)(qraw + (size_t)t * 768 + hd * 96 + 4 * sub + 32); q2_[u] = *(const u32x2*)(qraw + (size_t)t * 768 + hd * 96 + 4 * sub + 64);
;             k0_[u] = *(const u32x2*)(kvraw + (size_t)t * 1024 + hd * 128 + 4 * sub); k1_[u] = *(const u32x2*)(kvraw + (size_t)t * 1024 + hd * 128 + 4 * sub + 32); k2_[u] = *(const u32x2*)(pr + C_KPE + 4 * sub);
;             vv_[u] = *(const u32x4*)(kvraw + (size_t)t * 1024 + hd * 128 + 64 + 8 * sub); pos_[u] = a.pos[t];
;           }
; #pragma unroll
;           for (int u = 0; u < 4; ++u) {
;             const int tl = wave * 8 + i0 + u, t = item * 64 + tl, b = t / S_, s = t % S_;
;             const u32x2 cq = cq_[u], q0 = q0_[u], q1 = q1_[u], q2 = q2_[u], k0 = k0_[u], k1 = k1_[u], k2 = k2_[u]; const unsigned ckv = ckv_[u]; const u32x4 vv = vv_[u];
;             float sq = bflo(cq.x) * bflo(cq.x) + bfhi(cq.x) * bfhi(cq.x) + bflo(cq.y) * bflo(cq.y) + bfhi(cq.y) * bfhi(cq.y);
;             float sk = bflo(ckv) * bflo(ckv) + bfhi(ckv) * bfhi(ckv);
;             const float rq = __builtin_amdgcn_rsqf(wave_sum_dpp(sq) * (1.f / 256.f) + EPS), rk = __builtin_amdgcn_rsqf(wave_sum_dpp(sk) * (1.f / 128.f) + EPS);
.LBB0_452:
	s_and_b32 s98, s46, 7
	s_lshl_b32 s98, s98, 5
	s_bfe_u32 s99, s46, 0x50003
	s_or_b32 s99, s99, s98
	s_lshl_b32 s47, s99, 6
	v_add_u32_e32 v81, s47, v157
	s_mov_b64 s[22:23], -1
	s_mov_b32 s26, 0
	s_barrier
.LBB0_453:
	v_cndmask_b32_e64 v12, 0, 1, s[22:23]
	v_cmp_ne_u32_e32 vcc, 1, v12
	v_or_b32_e32 v12, s26, v81
	v_ashrrev_i32_e32 v13, 31, v12
	v_lshlrev_b64 v[14:15], 12, v[12:13]
	v_lshl_add_u64 v[14:15], s[92:93], 0, v[14:15]
	v_lshl_add_u64 v[16:17], v[14:15], 0, v[32:33]
	global_load_dwordx2 v[130:131], v[16:17], off
	v_mov_b32_e32 v75, v33
	v_lshl_add_u64 v[16:17], v[14:15], 0, v[74:75]
	global_load_dword v132, v[16:17], off offset:512
	v_mad_i64_i32 v[16:17], s[22:23], v12, s24, v[48:49]
	global_load_dwordx2 v[140:141], v[16:17], off
	global_load_dwordx2 v[138:139], v[16:17], off offset:64
	global_load_dwordx2 v[142:143], v[16:17], off offset:128
	v_lshlrev_b64 v[16:17], 11, v[12:13]
	v_lshl_add_u64 v[16:17], v[50:51], 0, v[16:17]
	v_mov_b32_e32 v77, v33
	v_lshl_add_u64 v[18:19], v[16:17], 0, v[76:77]
	v_lshl_add_u64 v[14:15], v[14:15], 0, v[76:77]
	v_mov_b32_e32 v79, v33
	global_load_dwordx2 v[126:127], v[18:19], off
	global_load_dwordx2 v[124:125], v[18:19], off offset:64
	global_load_dwordx2 v[128:129], v[14:15], off offset:768
	v_lshl_add_u64 v[14:15], v[16:17], 0, v[78:79]
	global_load_dwordx4 v[28:31], v[14:15], off offset:128
	v_lshl_add_u64 v[14:15], v[12:13], 2, s[10:11]
	global_load_dwordx4 v[16:19], v[14:15], off
	v_or_b32_e32 v14, 1, v12
	v_ashrrev_i32_e32 v15, 31, v14
	v_lshlrev_b64 v[20:21], 12, v[14:15]
	v_lshl_add_u64 v[20:21], s[92:93], 0, v[20:21]
	v_lshl_add_u64 v[22:23], v[20:21], 0, v[32:33]
	global_load_dwordx2 v[122:123], v[22:23], off
	v_lshl_add_u64 v[22:23], v[20:21], 0, v[74:75]
	global_load_dword v165, v[22:23], off offset:512
	v_mad_i64_i32 v[22:23], s[22:23], v14, s24, v[48:49]
	v_lshlrev_b64 v[14:15], 11, v[14:15]
	v_lshl_add_u64 v[14:15], v[50:51], 0, v[14:15]
	global_load_dwordx2 v[118:119], v[22:23], off
	global_load_dwordx2 v[116:117], v[22:23], off offset:64
	global_load_dwordx2 v[120:121], v[22:23], off offset:128
	v_lshl_add_u64 v[22:23], v[14:15], 0, v[76:77]
	v_lshl_add_u64 v[20:21], v[20:21], 0, v[76:77]
	v_lshl_add_u64 v[14:15], v[14:15], 0, v[78:79]
	global_load_dwordx2 v[112:113], v[22:23], off
	global_load_dwordx2 v[110:111], v[22:23], off offset:64
	global_load_dwordx2 v[114:115], v[20:21], off offset:768
	global_load_dwordx4 v[24:27], v[14:15], off offset:128
	v_or_b32_e32 v14, 2, v12
	v_ashrrev_i32_e32 v15, 31, v14
	v_lshlrev_b64 v[20:21], 12, v[14:15]
	v_lshl_add_u64 v[20:21], s[92:93], 0, v[20:21]
	v_lshl_add_u64 v[22:23], v[20:21], 0, v[32:33]
	global_load_dwordx2 v[108:109], v[22:23], off
	v_lshl_add_u64 v[22:23], v[20:21], 0, v[74:75]
	global_load_dword v164, v[22:23], off offset:512
	v_mad_i64_i32 v[22:23], s[22:23], v14, s24, v[48:49]
	v_lshlrev_b64 v[14:15], 11, v[14:15]
	v_lshl_add_u64 v[14:15], v[50:51], 0, v[14:15]
	v_or_b32_e32 v12, 3, v12
	global_load_dwordx2 v[104:105], v[22:23], off
	global_load_dwordx2 v[102:103], v[22:23], off offset:64
	global_load_dwordx2 v[106:107], v[22:23], off offset:128
	v_lshl_add_u64 v[22:23], v[14:15], 0, v[76:77]
	v_lshl_add_u64 v[20:21], v[20:21], 0, v[76:77]
	v_lshl_add_u64 v[14:15], v[14:15], 0, v[78:79]
	v_ashrrev_i32_e32 v13, 31, v12
	global_load_dwordx2 v[98:99], v[22:23], off
	global_load_dwordx2 v[96:97], v[22:23], off offset:64
	global_load_dwordx2 v[100:101], v[20:21], off offset:768
	v_or_b32_e32 v163, s26, v157
	global_load_dwordx4 v[20:23], v[14:15], off offset:128
	v_lshlrev_b64 v[14:15], 12, v[12:13]
	v_lshl_add_u64 v[14:15], s[92:93], 0, v[14:15]
	v_lshl_add_u64 v[82:83], v[14:15], 0, v[32:33]
	global_load_dwordx2 v[94:95], v[82:83], off
	v_lshl_add_u64 v[82:83], v[14:15], 0, v[74:75]
	global_load_dword v162, v[82:83], off offset:512
	v_mad_i64_i32 v[82:83], s[22:23], v12, s24, v[48:49]
	v_lshlrev_b64 v[12:13], 11, v[12:13]
	v_lshl_add_u64 v[12:13], v[50:51], 0, v[12:13]
	global_load_dwordx2 v[90:91], v[82:83], off
	global_load_dwordx2 v[88:89], v[82:83], off offset:64
	global_load_dwordx2 v[92:93], v[82:83], off offset:128
	v_lshl_add_u64 v[82:83], v[12:13], 0, v[76:77]
	v_lshl_add_u64 v[12:13], v[12:13], 0, v[78:79]
	v_lshl_add_u64 v[14:15], v[14:15], 0, v[76:77]
	v_add_u32_e32 v77, s47, v163
	v_ashrrev_i32_e32 v75, 31, v77
	v_lshrrev_b32_e32 v75, 21, v75
	v_add_u32_e32 v75, v77, v75
	v_ashrrev_i32_e32 v75, 11, v75
	global_load_dwordx2 v[84:85], v[82:83], off
	s_nop 0
	global_load_dwordx2 v[82:83], v[82:83], off offset:64
	s_waitcnt vmcnt(34)
	v_lshlrev_b32_e32 v79, 16, v130
	v_and_b32_e32 v130, 0xffff0000, v130
	v_mul_f32_e32 v133, v130, v130
	v_and_b32_e32 v130, 0xffff0000, v131
	v_lshlrev_b32_e32 v131, 16, v131
	v_fmac_f32_e32 v133, v79, v79
	v_pk_mul_f32 v[130:131], v[130:131], v[130:131]
	s_waitcnt vmcnt(32)
	v_lshlrev_b32_e32 v176, 16, v140
	v_add_f32_e32 v79, v131, v133
	v_add_f32_e32 v79, v130, v79
	v_lshlrev_b32_e32 v130, 16, v132
	v_and_b32_e32 v131, 0xffff0000, v132
	v_add_f32_dpp v79, v79, v79 quad_perm:[1,0,3,2] row_mask:0xf bank_mask:0xf bound_ctrl:1
	v_pk_mul_f32 v[130:131], v[130:131], v[130:131]
	v_and_b32_e32 v177, 0xffff0000, v140
	v_add_f32_dpp v79, v79, v79 quad_perm:[2,3,0,1] row_mask:0xf bank_mask:0xf bound_ctrl:1
	v_add_f32_e32 v130, v130, v131
	v_mov_b32_e32 v131, v33
	v_add_f32_dpp v79, v79, v79 row_half_mirror row_mask:0xf bank_mask:0xf bound_ctrl:1
	v_add_f32_dpp v130, v130, v130 quad_perm:[1,0,3,2] row_mask:0xf bank_mask:0xf bound_ctrl:1
	s_waitcnt vmcnt(25)
; __device__ __forceinline__ void p3_qkv(const Args& a, LAS unsigned char* lds) {
;     ...
;             const float rq = __builtin_amdgcn_rsqf(wave_sum_dpp(sq) * (1.f / 256.f) + EPS), rk = __builtin_amdgcn_rsqf(wave_sum_dpp(sk) * (1.f / 128.f) + EPS);
;             const float p = (float)pos_[u];
;             float sn[4], cs[4];
; #pragma unroll
;             for (int e = 0; e < 4; ++e) sincos_rev(p * ifr[e], sn[e], cs[e]);
;             float v[12];
;             v[0] = bflo(q0.x); v[1] = bfhi(q0.x); v[2] = bflo(q0.y); v[3] = bfhi(q0.y); v[4] = bflo(q1.x); v[5] = bfhi(q1.x); v[6] = bflo(q1.y); v[7] = bfhi(q1.y);
;             v[8] = bflo(q2.x); v[9] = bfhi(q2.x); v[10] = bflo(q2.y); v[11] = bfhi(q2.y);
;             float ss = 0.f;
; #pragma unroll
;             for (int j = 0; j < 12; ++j) { v[j] *= rq; ss += v[j] * v[j]; }
;             ss = sum8_dpp(ss);
;             float rn = __builtin_amdgcn_rsqf(ss * (1.f / 96.f) + EPS);
; #pragma unroll
;             for (int j = 0; j < 12; ++j) v[j] = v[j] * rn * gq[j];
; #pragma unroll
;             for (int e = 0; e < 4; ++e) { const float x = v[8 + e], pt = xor4_dpp(x, sub < 4); v[8 + e] = x * cs[e] + sgn * pt * sn[e]; }
	v_cvt_f32_i32_e32 v16, v16
	v_add_f32_dpp v79, v79, v79 row_mirror row_mask:0xf bank_mask:0xf bound_ctrl:1
	v_add_f32_dpp v130, v130, v130 quad_perm:[2,3,0,1] row_mask:0xf bank_mask:0xf bound_ctrl:1
	v_lshlrev_b32_e32 v172, 16, v141
	v_mov_b32_dpp v131, v79 row_bcast:15 row_mask:0xa bank_mask:0xf
	v_add_f32_e32 v79, v79, v131
	v_mov_b32_e32 v131, v33
	v_add_f32_dpp v130, v130, v130 row_half_mirror row_mask:0xf bank_mask:0xf bound_ctrl:1
	v_and_b32_e32 v173, 0xffff0000, v141
	v_mov_b32_dpp v131, v79 row_bcast:31 row_mask:0xc bank_mask:0xf
	v_add_f32_e32 v79, v79, v131
	v_add_f32_dpp v130, v130, v130 row_mirror row_mask:0xf bank_mask:0xf bound_ctrl:1
	v_mov_b32_e32 v131, v33
	v_readlane_b32 s22, v79, 63
	v_and_b32_e32 v148, 0xffff0000, v142
	v_mov_b32_dpp v131, v130 row_bcast:15 row_mask:0xa bank_mask:0xf
	v_add_f32_e32 v130, v130, v131
	v_mov_b32_e32 v131, v33
	v_fma_f32 v79, s22, v160, v9
	v_lshlrev_b32_e32 v149, 16, v142
	v_mov_b32_dpp v131, v130 row_bcast:31 row_mask:0xc bank_mask:0xf
	v_add_f32_e32 v130, v130, v131
	v_and_b32_e32 v142, 0xffff0000, v143
	v_readlane_b32 s22, v130, 63
	v_mul_f32_e32 v130, v153, v16
	v_cvt_f64_f32_e32 v[130:131], v130
	v_mul_f64 v[132:133], v[130:131], s[20:21]
	v_rndne_f64_e32 v[132:133], v[132:133]
	v_fma_f64 v[130:131], v[130:131], s[20:21], -v[132:133]
	v_cvt_f32_f64_e32 v130, v[130:131]
	v_sin_f32_e32 v136, v130
	v_cos_f32_e32 v134, v130
	v_mul_f32_e32 v130, v154, v16
	v_cvt_f64_f32_e32 v[130:131], v130
	v_mul_f64 v[132:133], v[130:131], s[20:21]
	v_rndne_f64_e32 v[132:133], v[132:133]
	v_fma_f64 v[130:131], v[130:131], s[20:21], -v[132:133]
	v_cvt_f32_f64_e32 v130, v[130:131]
	v_sin_f32_e32 v137, v130
	v_cos_f32_e32 v135, v130
	v_mul_f32_e32 v130, v155, v16
	v_mul_f32_e32 v16, v156, v16
	v_cvt_f64_f32_e32 v[130:131], v130
	v_cvt_f64_f32_e32 v[144:145], v16
	v_mul_f64 v[132:133], v[130:131], s[20:21]
	v_mul_f64 v[146:147], v[144:145], s[20:21]
	v_rndne_f64_e32 v[132:133], v[132:133]
	v_rndne_f64_e32 v[146:147], v[146:147]
	v_fma_f64 v[130:131], v[130:131], s[20:21], -v[132:133]
	v_fma_f64 v[144:145], v[144:145], s[20:21], -v[146:147]
	v_cvt_f32_f64_e32 v131, v[130:131]
	v_cvt_f32_f64_e32 v16, v[144:145]
	v_sin_f32_e32 v130, v131
	v_cos_f32_e32 v132, v131
	v_sin_f32_e32 v131, v16
	v_cos_f32_e32 v133, v16
	v_rsq_f32_e32 v16, v79
	v_and_b32_e32 v144, 0xffff0000, v139
	v_lshlrev_b32_e32 v145, 16, v139
	v_lshlrev_b32_e32 v143, 16, v143
	v_pk_mul_f32 v[140:141], v[16:17], v[176:177] op_sel_hi:[0,1]
	v_pk_mul_f32 v[172:173], v[16:17], v[172:173] op_sel_hi:[0,1]
	v_pk_mul_f32 v[176:177], v[140:141], v[140:141]
	v_lshlrev_b32_e32 v178, 16, v138
	v_and_b32_e32 v179, 0xffff0000, v138
	v_pk_mul_f32 v[146:147], v[16:17], v[144:145] op_sel_hi:[0,1]
	v_pk_mul_f32 v[150:151], v[16:17], v[148:149] op_sel_hi:[0,1]
	v_pk_mul_f32 v[148:149], v[16:17], v[142:143] op_sel_hi:[0,1]
	v_pk_mul_f32 v[174:175], v[172:173], v[172:173]
	v_pk_mul_f32 v[178:179], v[16:17], v[178:179] op_sel_hi:[0,1]
	v_add_f32_e32 v16, v176, v177
	v_add_f32_e32 v16, v174, v16
	v_pk_mul_f32 v[138:139], v[178:179], v[178:179]
	v_add_f32_e32 v16, v175, v16
	v_add_f32_e32 v16, v138, v16
	v_pk_mul_f32 v[144:145], v[146:147], v[146:147]
	v_add_f32_e32 v16, v139, v16
	v_add_f32_e32 v16, v145, v16
	v_pk_mul_f32 v[166:167], v[150:151], v[150:151]
	v_add_f32_e32 v16, v144, v16
	v_add_f32_e32 v16, v167, v16
	v_pk_mul_f32 v[168:169], v[148:149], v[148:149]
	v_add_f32_e32 v16, v166, v16
	v_add_f32_e32 v16, v169, v16
	v_add_f32_e32 v16, v168, v16
	v_mul_i32_i24_e32 v79, 0x800, v75
	v_sub_u32_e32 v142, v77, v79
	v_add_f32_dpp v16, v16, v16 quad_perm:[1,0,3,2] row_mask:0xf bank_mask:0xf bound_ctrl:1
	v_mov_b32_e32 v77, v33
	v_mov_b32_e32 v79, v33
	v_add_f32_dpp v16, v16, v16 quad_perm:[2,3,0,1] row_mask:0xf bank_mask:0xf bound_ctrl:1
	v_mov_b32_e32 v143, v33
	v_mov_b32_e32 v166, v33
	v_add_f32_dpp v16, v16, v16 row_half_mirror row_mask:0xf bank_mask:0xf bound_ctrl:1
	v_fmamk_f32 v16, v16, 0x3c2aaaab, v9
	v_rsq_f32_e32 v16, v16
	v_fma_f32 v180, s22, v161, v9
	global_load_dwordx2 v[86:87], v[14:15], off offset:768
	v_lshlrev_b32_e32 v168, 16, v126
	v_pk_mul_f32 v[150:151], v[150:151], v[16:17] op_sel_hi:[1,0]
	v_pk_mul_f32 v[148:149], v[148:149], v[16:17] op_sel_hi:[1,0]
	v_pk_mul_f32 v[150:151], v[42:43], v[150:151] op_sel:[0,1] op_sel_hi:[1,0]
	v_pk_mul_f32 v[138:139], v[140:141], v[16:17] op_sel_hi:[1,0]
	v_pk_mul_f32 v[140:141], v[172:173], v[16:17] op_sel_hi:[1,0]
	v_mov_b32_dpp v77, v150 row_shl:4 row_mask:0xf bank_mask:0xf
	v_mov_b32_dpp v79, v150 row_shr:4 row_mask:0xf bank_mask:0xf
	v_mov_b32_dpp v143, v151 row_shl:4 row_mask:0xf bank_mask:0xf
	v_mov_b32_dpp v166, v151 row_shr:4 row_mask:0xf bank_mask:0xf
	v_pk_mul_f32 v[144:145], v[178:179], v[16:17] op_sel_hi:[1,0]
	v_pk_mul_f32 v[146:147], v[146:147], v[16:17] op_sel_hi:[1,0]
	v_cndmask_b32_e64 v167, v166, v143, s[42:43]
	v_cndmask_b32_e64 v166, v79, v77, s[42:43]
	v_pk_mul_f32 v[148:149], v[44:45], v[148:149] op_sel:[0,1] op_sel_hi:[1,0]
	v_mov_b32_e32 v16, v33
	v_mov_b32_e32 v77, v33
	v_mov_b32_e32 v79, v33
	v_mov_b32_e32 v143, v33
	v_pk_mul_f32 v[150:151], v[134:135], v[150:151]
	v_pk_mul_f32 v[166:167], v[46:47], v[166:167]
	v_mov_b32_dpp v16, v148 row_shl:4 row_mask:0xf bank_mask:0xf
	v_mov_b32_dpp v77, v148 row_shr:4 row_mask:0xf bank_mask:0xf
	v_mov_b32_dpp v79, v149 row_shl:4 row_mask:0xf bank_mask:0xf
	v_mov_b32_dpp v143, v149 row_shr:4 row_mask:0xf bank_mask:0xf
	v_pk_fma_f32 v[150:151], v[136:137], v[166:167], v[150:151]
	v_cndmask_b32_e64 v167, v143, v79, s[42:43]
	v_cndmask_b32_e64 v166, v77, v16, s[42:43]
	v_pk_mul_f32 v[148:149], v[132:133], v[148:149]
	v_pk_mul_f32 v[166:167], v[46:47], v[166:167]
; __device__ __forceinline__ unsigned pk2(float lo, float hi) { f32x2 v = {lo, hi}; bf16x2_t b = __builtin_convertvector(v, bf16x2_t); return __builtin_bit_cast(unsigned, b); }
; __device__ __forceinline__ void p3_qkv(const Args& a, LAS unsigned char* lds) {
;     ...
;             for (int j = 0; j < 12; ++j) v[j] = v[j] * rn * gq[j];
; #pragma unroll
;             for (int e = 0; e < 4; ++e) { const float x = v[8 + e], pt = xor4_dpp(x, sub < 4); v[8 + e] = x * cs[e] + sgn * pt * sn[e]; }
;             { bf16* qo = Q + ((size_t)(b * 8 + hd) * S_ + s) * 96 + 4 * sub;
; #pragma unroll
;               for (int jj = 0; jj < 3; ++jj) { u32x2 o; o.x = pk2(v[4 * jj], v[4 * jj + 1]); o.y = pk2(v[4 * jj + 2], v[4 * jj + 3]); *(u32x2*)(qo + 32 * jj) = o; } }
;             v[0] = bflo(k0.x) * rk; v[1] = bfhi(k0.x) * rk; v[2] = bflo(k0.y) * rk; v[3] = bfhi(k0.y) * rk; v[4] = bflo(k1.x) * rk; v[5] = bfhi(k1.x) * rk; v[6] = bflo(k1.y) * rk; v[7] = bfhi(k1.y) * rk;
;             v[8] = bflo(k2.x); v[9] = bfhi(k2.x); v[10] = bflo(k2.y); v[11] = bfhi(k2.y);
;             ss = 0.f;
; #pragma unroll
;             for (int j = 0; j < 12; ++j) ss += v[j] * v[j];
;             ss = sum8_dpp(ss);
;             rn = __builtin_amdgcn_rsqf(ss * (1.f / 96.f) + EPS);
; #pragma unroll
;             for (int j = 0; j < 12; ++j) v[j] = v[j] * rn * gk[j];
; #pragma unroll
;             for (int e = 0; e < 4; ++e) { const float x = v[8 + e], pt = xor4_dpp(x, sub < 4); v[8 + e] = x * cs[e] + sgn * pt * sn[e]; }
;             { bf16* ko = Kk + ((size_t)(b * 8 + hd) * S_ + s) * 96 + 4 * sub;
; #pragma unroll
;               for (int jj = 0; jj < 3; ++jj) { u32x2 o; o.x = pk2(v[4 * jj], v[4 * jj + 1]); o.y = pk2(v[4 * jj + 2], v[4 * jj + 3]); *(u32x2*)(ko + 32 * jj) = o; } }
	v_ashrrev_i32_e32 v143, 31, v142
	v_pk_fma_f32 v[148:149], v[130:131], v[166:167], v[148:149]
	v_lshl_or_b32 v166, v75, 3, v152
	v_ashrrev_i32_e32 v167, 31, v166
	v_lshlrev_b64 v[166:167], 11, v[166:167]
	v_lshl_add_u64 v[142:143], v[166:167], 0, v[142:143]
	v_rsq_f32_e32 v16, v180
	v_pk_mul_f32 v[138:139], v[34:35], v[138:139]
	v_pk_mul_f32 v[140:141], v[36:37], v[140:141]
	v_mad_u64_u32 v[166:167], s[22:23], v142, s25, v[52:53]
	v_pk_mul_f32 v[144:145], v[38:39], v[144:145]
	v_pk_mul_f32 v[146:147], v[40:41], v[146:147] op_sel:[0,1] op_sel_hi:[1,0]
	v_mad_i32_i24 v167, v143, s25, v167
	v_cvt_pk_bf16_f32 v138, v138, v139
	v_cvt_pk_bf16_f32 v139, v140, v141
	global_load_dwordx4 v[12:15], v[12:13], off offset:128
	v_and_b32_e32 v169, 0xffff0000, v126
	global_store_dwordx2 v[166:167], v[138:139], off
	v_cvt_pk_bf16_f32 v138, v144, v145
	v_cvt_pk_bf16_f32 v139, v146, v147
	global_store_dwordx2 v[166:167], v[138:139], off offset:64
	v_cvt_pk_bf16_f32 v138, v150, v151
	v_lshlrev_b32_e32 v150, 16, v127
	v_and_b32_e32 v151, 0xffff0000, v127
	v_pk_mul_f32 v[126:127], v[16:17], v[168:169] op_sel_hi:[0,1]
	v_cvt_pk_bf16_f32 v139, v148, v149
	v_pk_mul_f32 v[150:151], v[16:17], v[150:151] op_sel_hi:[0,1]
	v_pk_mul_f32 v[168:169], v[126:127], v[126:127]
	global_store_dwordx2 v[166:167], v[138:139], off offset:128
	v_pk_mul_f32 v[166:167], v[150:151], v[150:151]
	v_lshlrev_b32_e32 v172, 16, v124
	v_and_b32_e32 v173, 0xffff0000, v124
	v_add_f32_e32 v75, v168, v169
	v_pk_mul_f32 v[172:173], v[16:17], v[172:173] op_sel_hi:[0,1]
	v_add_f32_e32 v75, v166, v75
	v_and_b32_e32 v138, 0xffff0000, v125
	v_lshlrev_b32_e32 v139, 16, v125
	v_pk_mul_f32 v[124:125], v[172:173], v[172:173]
	v_add_f32_e32 v75, v167, v75
	v_pk_mul_f32 v[140:141], v[16:17], v[138:139] op_sel_hi:[0,1]
	v_add_f32_e32 v75, v124, v75
	v_pk_mul_f32 v[138:139], v[140:141], v[140:141]
	v_add_f32_e32 v75, v125, v75
	v_and_b32_e32 v146, 0xffff0000, v128
	v_lshlrev_b32_e32 v147, 16, v128
	v_add_f32_e32 v75, v139, v75
	v_pk_mul_f32 v[144:145], v[146:147], v[146:147]
	v_add_f32_e32 v75, v138, v75
	v_and_b32_e32 v128, 0xffff0000, v129
	v_lshlrev_b32_e32 v129, 16, v129
	v_add_f32_e32 v75, v145, v75
	v_pk_mul_f32 v[148:149], v[128:129], v[128:129]
	v_add_f32_e32 v75, v144, v75
	v_add_f32_e32 v75, v149, v75
	v_add_f32_e32 v75, v148, v75
	v_mov_b32_e32 v77, v33
	v_mov_b32_e32 v79, v33
	v_add_f32_dpp v75, v75, v75 quad_perm:[1,0,3,2] row_mask:0xf bank_mask:0xf bound_ctrl:1
	v_cvt_f32_i32_e32 v18, v18
	s_mov_b32 s26, 4
	v_add_f32_dpp v75, v75, v75 quad_perm:[2,3,0,1] row_mask:0xf bank_mask:0xf bound_ctrl:1
	s_and_b64 vcc, exec, vcc
	s_nop 0
	v_add_f32_dpp v75, v75, v75 row_half_mirror row_mask:0xf bank_mask:0xf bound_ctrl:1
	v_fmamk_f32 v75, v75, 0x3c2aaaab, v9
	v_rsq_f32_e32 v144, v75
	s_nop 0
	v_mul_f32_e32 v75, v144, v147
	v_mul_f32_e32 v149, v144, v146
	v_mul_f32_e32 v146, v8, v75
	v_mov_b32_e32 v75, v33
	v_pk_mul_f32 v[128:129], v[144:145], v[128:129] op_sel_hi:[0,1]
	v_mov_b32_dpp v77, v146 row_shr:4 row_mask:0xf bank_mask:0xf
	v_mov_b32_dpp v75, v146 row_shl:4 row_mask:0xf bank_mask:0xf
	v_cndmask_b32_e64 v148, v77, v75, s[42:43]
	v_pk_mul_f32 v[148:149], v[72:73], v[148:149]
	v_mov_b32_e32 v75, v33
	v_mov_b32_e32 v77, v33
	v_pk_mul_f32 v[124:125], v[126:127], v[144:145] op_sel_hi:[1,0]
	v_mov_b32_dpp v75, v149 row_shl:4 row_mask:0xf bank_mask:0xf
	v_mov_b32_dpp v77, v149 row_shr:4 row_mask:0xf bank_mask:0xf
	v_cndmask_b32_e64 v75, v77, v75, s[42:43]
	v_pk_mul_f32 v[126:127], v[150:151], v[144:145] op_sel_hi:[1,0]
	v_mov_b32_e32 v150, v136
	v_mul_f32_e32 v147, v46, v75
	v_pk_mul_f32 v[128:129], v[10:11], v[128:129] op_sel:[0,1] op_sel_hi:[1,0]
	v_mov_b32_e32 v75, v33
	v_mov_b32_e32 v77, v33
	v_mov_b32_e32 v136, v33
	v_mov_b32_dpp v75, v128 row_shl:4 row_mask:0xf bank_mask:0xf
	v_mov_b32_dpp v77, v128 row_shr:4 row_mask:0xf bank_mask:0xf
	v_mov_b32_dpp v79, v129 row_shl:4 row_mask:0xf bank_mask:0xf
	v_mov_b32_dpp v136, v129 row_shr:4 row_mask:0xf bank_mask:0xf
	v_mov_b32_e32 v151, v135
	v_mov_b32_e32 v135, v137
	v_cndmask_b32_e64 v137, v136, v79, s[42:43]
	v_cndmask_b32_e64 v136, v77, v75, s[42:43]
	v_pk_mul_f32 v[136:137], v[46:47], v[136:137]
	v_pk_mul_f32 v[124:125], v[0:1], v[124:125]
	v_pk_mul_f32 v[130:131], v[130:131], v[136:137]
	v_pk_mul_f32 v[126:127], v[2:3], v[126:127]
	v_pk_mul_f32 v[138:139], v[172:173], v[144:145] op_sel_hi:[1,0]
	v_pk_mul_f32 v[140:141], v[140:141], v[144:145] op_sel_hi:[1,0]
	v_pk_fma_f32 v[128:129], v[132:133], v[128:129], v[130:131]
	v_mad_u64_u32 v[130:131], s[22:23], v142, s25, v[54:55]
	v_pk_mul_f32 v[138:139], v[4:5], v[138:139]
	v_pk_mul_f32 v[140:141], v[6:7], v[140:141] op_sel:[0,1] op_sel_hi:[1,0]
	v_pk_mul_f32 v[134:135], v[134:135], v[146:147]
	v_mad_i32_i24 v131, v143, s25, v131
	v_cvt_pk_bf16_f32 v124, v124, v125
	v_cvt_pk_bf16_f32 v125, v126, v127
	v_pk_fma_f32 v[134:135], v[150:151], v[148:149], v[134:135]
	global_store_dwordx2 v[130:131], v[124:125], off
	v_cvt_pk_bf16_f32 v124, v138, v139
	v_cvt_pk_bf16_f32 v125, v140, v141
	global_store_dwordx2 v[130:131], v[124:125], off offset:64
	v_cvt_pk_bf16_f32 v124, v134, v135
	v_cvt_pk_bf16_f32 v125, v128, v129
	global_store_dwordx2 v[130:131], v[124:125], off offset:128
	v_lshlrev_b32_e32 v124, 16, v28
	v_and_b32_e32 v125, 0xffff0000, v28
	v_lshlrev_b32_e32 v28, 16, v29
	v_and_b32_e32 v29, 0xffff0000, v29
	v_pk_mul_f32 v[124:125], v[16:17], v[124:125] op_sel_hi:[0,1]
	v_pk_mul_f32 v[28:29], v[16:17], v[28:29] op_sel_hi:[0,1]
	v_cvt_pk_bf16_f32 v126, v124, v125
	v_cvt_pk_bf16_f32 v125, v28, v29
	v_lshlrev_b32_e32 v28, 16, v30
	v_and_b32_e32 v29, 0xffff0000, v30
	v_pk_mul_f32 v[28:29], v[16:17], v[28:29] op_sel_hi:[0,1]
	v_cvt_pk_bf16_f32 v124, v28, v29
	v_lshlrev_b32_e32 v28, 16, v31
	v_and_b32_e32 v29, 0xffff0000, v31
	v_pk_mul_f32 v[28:29], v[16:17], v[28:29] op_sel_hi:[0,1]
	v_or_b32_e32 v16, 1, v163
	v_add_u32_e32 v79, s47, v16
	v_ashrrev_i32_e32 v16, 31, v79
	v_lshrrev_b32_e32 v16, 21, v16
	v_cvt_pk_bf16_f32 v77, v28, v29
	v_add_u32_e32 v16, v79, v16
	s_waitcnt vmcnt(32)
; __device__ __forceinline__ void p3_qkv(const Args& a, LAS unsigned char* lds) {
;     ...
;             float sq = bflo(cq.x) * bflo(cq.x) + bfhi(cq.x) * bfhi(cq.x) + bflo(cq.y) * bflo(cq.y) + bfhi(cq.y) * bfhi(cq.y);
;             float sk = bflo(ckv) * bflo(ckv) + bfhi(ckv) * bfhi(ckv);
;             const float rq = __builtin_amdgcn_rsqf(wave_sum_dpp(sq) * (1.f / 256.f) + EPS), rk = __builtin_amdgcn_rsqf(wave_sum_dpp(sk) * (1.f / 128.f) + EPS);
;             const float p = (float)pos_[u];
;             float sn[4], cs[4];
; #pragma unroll
;             for (int e = 0; e < 4; ++e) sincos_rev(p * ifr[e], sn[e], cs[e]);
;             float v[12];
;             v[0] = bflo(q0.x); v[1] = bfhi(q0.x); v[2] = bflo(q0.y); v[3] = bfhi(q0.y); v[4] = bflo(q1.x); v[5] = bfhi(q1.x); v[6] = bflo(q1.y); v[7] = bfhi(q1.y);
;             v[8] = bflo(q2.x); v[9] = bfhi(q2.x); v[10] = bflo(q2.y); v[11] = bfhi(q2.y);
;             float ss = 0.f;
; #pragma unroll
;             for (int j = 0; j < 12; ++j) { v[j] *= rq; ss += v[j] * v[j]; }
;             ss = sum8_dpp(ss);
;             float rn = __builtin_amdgcn_rsqf(ss * (1.f / 96.f) + EPS);
; #pragma unroll
;             for (int j = 0; j < 12; ++j) v[j] = v[j] * rn * gq[j];
	v_and_b32_e32 v28, 0xffff0000, v122
	v_ashrrev_i32_e32 v127, 11, v16
	v_lshlrev_b32_e32 v16, 16, v122
	v_mul_f32_e32 v30, v28, v28
	v_and_b32_e32 v28, 0xffff0000, v123
	v_lshlrev_b32_e32 v29, 16, v123
	v_fmac_f32_e32 v30, v16, v16
	v_pk_mul_f32 v[28:29], v[28:29], v[28:29]
	v_cvt_f32_i32_e32 v128, v17
	v_add_f32_e32 v16, v29, v30
	v_add_f32_e32 v16, v28, v16
	s_waitcnt vmcnt(31)
	v_lshlrev_b32_e32 v28, 16, v165
	v_and_b32_e32 v29, 0xffff0000, v165
	v_add_f32_dpp v16, v16, v16 quad_perm:[1,0,3,2] row_mask:0xf bank_mask:0xf bound_ctrl:1
	v_pk_mul_f32 v[28:29], v[28:29], v[28:29]
	s_waitcnt vmcnt(30)
	v_lshlrev_b32_e32 v146, 16, v118
	v_add_f32_dpp v16, v16, v16 quad_perm:[2,3,0,1] row_mask:0xf bank_mask:0xf bound_ctrl:1
	v_add_f32_e32 v28, v28, v29
	v_mov_b32_e32 v29, v33
	v_add_f32_dpp v16, v16, v16 row_half_mirror row_mask:0xf bank_mask:0xf bound_ctrl:1
	v_and_b32_e32 v147, 0xffff0000, v118
	v_lshlrev_b32_e32 v142, 16, v119
	v_add_f32_dpp v16, v16, v16 row_mirror row_mask:0xf bank_mask:0xf bound_ctrl:1
	v_and_b32_e32 v143, 0xffff0000, v119
	s_waitcnt vmcnt(29)
	v_lshlrev_b32_e32 v148, 16, v116
	v_mov_b32_dpp v29, v16 row_bcast:15 row_mask:0xa bank_mask:0xf
	v_add_f32_e32 v16, v16, v29
	v_mov_b32_e32 v29, v33
	v_and_b32_e32 v149, 0xffff0000, v116
	s_waitcnt vmcnt(28)
	v_and_b32_e32 v134, 0xffff0000, v120
	v_mov_b32_dpp v29, v16 row_bcast:31 row_mask:0xc bank_mask:0xf
	v_add_f32_e32 v16, v16, v29
	v_lshlrev_b32_e32 v135, 16, v120
	v_readlane_b32 s22, v16, 63
	v_add_f32_dpp v16, v28, v28 quad_perm:[1,0,3,2] row_mask:0xf bank_mask:0xf bound_ctrl:1
	v_mov_b32_e32 v28, v33
	v_fma_f32 v132, s22, v160, v9
	v_add_f32_dpp v16, v16, v16 quad_perm:[2,3,0,1] row_mask:0xf bank_mask:0xf bound_ctrl:1
	v_and_b32_e32 v120, 0xffff0000, v121
	v_lshlrev_b32_e32 v121, 16, v121
	v_add_f32_dpp v16, v16, v16 row_half_mirror row_mask:0xf bank_mask:0xf bound_ctrl:1
	v_lshl_add_u32 v75, v163, 1, v158
	s_nop 0
	v_add_f32_dpp v16, v16, v16 row_mirror row_mask:0xf bank_mask:0xf bound_ctrl:1
	s_nop 1
	v_mov_b32_dpp v28, v16 row_bcast:15 row_mask:0xa bank_mask:0xf
	v_add_f32_e32 v16, v16, v28
	v_mov_b32_e32 v28, v33
	s_nop 1
	v_mov_b32_dpp v28, v16 row_bcast:31 row_mask:0xc bank_mask:0xf
	v_add_f32_e32 v16, v16, v28
	s_nop 0
	v_readlane_b32 s22, v16, 63
	v_mul_f32_e32 v16, v153, v128
	v_cvt_f64_f32_e32 v[16:17], v16
	v_mul_f64 v[28:29], v[16:17], s[20:21]
	v_rndne_f64_e32 v[28:29], v[28:29]
	v_fma_f64 v[16:17], v[16:17], s[20:21], -v[28:29]
	v_cvt_f32_f64_e32 v17, v[16:17]
	v_sin_f32_e32 v16, v17
	v_cos_f32_e32 v28, v17
	v_mul_f32_e32 v17, v154, v128
	v_cvt_f64_f32_e32 v[30:31], v17
	v_mul_f64 v[122:123], v[30:31], s[20:21]
	v_rndne_f64_e32 v[122:123], v[122:123]
	v_fma_f64 v[30:31], v[30:31], s[20:21], -v[122:123]
	v_cvt_f32_f64_e32 v29, v[30:31]
	v_mul_f32_e32 v30, v155, v128
	v_cvt_f64_f32_e32 v[30:31], v30
	v_mul_f64 v[122:123], v[30:31], s[20:21]
	v_rndne_f64_e32 v[122:123], v[122:123]
	v_fma_f64 v[30:31], v[30:31], s[20:21], -v[122:123]
	v_cvt_f32_f64_e32 v31, v[30:31]
	v_sin_f32_e32 v30, v31
	v_cos_f32_e32 v122, v31
	v_mul_f32_e32 v31, v156, v128
	v_cvt_f64_f32_e32 v[128:129], v31
	v_mul_f64 v[130:131], v[128:129], s[20:21]
	v_rndne_f64_e32 v[130:131], v[130:131]
	v_fma_f64 v[128:129], v[128:129], s[20:21], -v[130:131]
	v_cvt_f32_f64_e32 v123, v[128:129]
	v_rsq_f32_e32 v128, v132
	v_and_b32_e32 v130, 0xffff0000, v117
	v_lshlrev_b32_e32 v131, 16, v117
	v_mul_i32_i24_e32 v117, 0x800, v127
	v_pk_mul_f32 v[118:119], v[128:129], v[146:147] op_sel_hi:[0,1]
	v_pk_mul_f32 v[142:143], v[128:129], v[142:143] op_sel_hi:[0,1]
	v_pk_mul_f32 v[146:147], v[118:119], v[118:119]
	v_sub_u32_e32 v140, v79, v117
	v_pk_mul_f32 v[144:145], v[142:143], v[142:143]
	v_add_f32_e32 v79, v146, v147
	v_pk_mul_f32 v[116:117], v[128:129], v[148:149] op_sel_hi:[0,1]
	v_add_f32_e32 v79, v144, v79
	v_pk_mul_f32 v[130:131], v[128:129], v[130:131] op_sel_hi:[0,1]
	v_pk_mul_f32 v[134:135], v[128:129], v[134:135] op_sel_hi:[0,1]
	v_pk_mul_f32 v[120:121], v[128:129], v[120:121] op_sel_hi:[0,1]
	v_pk_mul_f32 v[128:129], v[116:117], v[116:117]
	v_add_f32_e32 v79, v145, v79
	v_add_f32_e32 v79, v128, v79
	v_pk_mul_f32 v[132:133], v[130:131], v[130:131]
	v_add_f32_e32 v79, v129, v79
	v_add_f32_e32 v79, v133, v79
	v_pk_mul_f32 v[136:137], v[134:135], v[134:135]
	v_add_f32_e32 v79, v132, v79
	v_add_f32_e32 v79, v137, v79
	v_pk_mul_f32 v[138:139], v[120:121], v[120:121]
	v_add_f32_e32 v79, v136, v79
	v_add_f32_e32 v79, v139, v79
	v_add_f32_e32 v79, v138, v79
	v_sin_f32_e32 v17, v29
	v_cos_f32_e32 v29, v29
	v_add_f32_dpp v79, v79, v79 quad_perm:[1,0,3,2] row_mask:0xf bank_mask:0xf bound_ctrl:1
	v_mov_b32_e32 v136, v33
	v_mov_b32_e32 v137, v33
	v_add_f32_dpp v79, v79, v79 quad_perm:[2,3,0,1] row_mask:0xf bank_mask:0xf bound_ctrl:1
	v_sin_f32_e32 v31, v123
	v_cos_f32_e32 v123, v123
	v_add_f32_dpp v79, v79, v79 row_half_mirror row_mask:0xf bank_mask:0xf bound_ctrl:1
	v_fmamk_f32 v79, v79, 0x3c2aaaab, v9
	v_rsq_f32_e32 v128, v79
	v_mov_b32_e32 v79, v33
	v_ashrrev_i32_e32 v141, 31, v140
	v_fma_f32 v150, s22, v161, v9
	v_pk_mul_f32 v[134:135], v[134:135], v[128:129] op_sel_hi:[1,0]
	v_pk_mul_f32 v[118:119], v[118:119], v[128:129] op_sel_hi:[1,0]
	v_pk_mul_f32 v[132:133], v[142:143], v[128:129] op_sel_hi:[1,0]
	v_pk_mul_f32 v[116:117], v[116:117], v[128:129] op_sel_hi:[1,0]
	v_pk_mul_f32 v[130:131], v[130:131], v[128:129] op_sel_hi:[1,0]
	v_pk_mul_f32 v[134:135], v[42:43], v[134:135] op_sel:[0,1] op_sel_hi:[1,0]
	v_mov_b32_e32 v129, v33
	v_pk_mul_f32 v[116:117], v[38:39], v[116:117]
	v_mov_b32_dpp v79, v134 row_shl:4 row_mask:0xf bank_mask:0xf
	v_mov_b32_dpp v129, v134 row_shr:4 row_mask:0xf bank_mask:0xf
; __device__ __forceinline__ unsigned pk2(float lo, float hi) { f32x2 v = {lo, hi}; bf16x2_t b = __builtin_convertvector(v, bf16x2_t); return __builtin_bit_cast(unsigned, b); }
; __device__ __forceinline__ void p3_qkv(const Args& a, LAS unsigned char* lds) {
;     ...
;             for (int j = 0; j < 12; ++j) v[j] = v[j] * rn * gq[j];
; #pragma unroll
;             for (int e = 0; e < 4; ++e) { const float x = v[8 + e], pt = xor4_dpp(x, sub < 4); v[8 + e] = x * cs[e] + sgn * pt * sn[e]; }
;             { bf16* qo = Q + ((size_t)(b * 8 + hd) * S_ + s) * 96 + 4 * sub;
; #pragma unroll
;               for (int jj = 0; jj < 3; ++jj) { u32x2 o; o.x = pk2(v[4 * jj], v[4 * jj + 1]); o.y = pk2(v[4 * jj + 2], v[4 * jj + 3]); *(u32x2*)(qo + 32 * jj) = o; } }
;             v[0] = bflo(k0.x) * rk; v[1] = bfhi(k0.x) * rk; v[2] = bflo(k0.y) * rk; v[3] = bfhi(k0.y) * rk; v[4] = bflo(k1.x) * rk; v[5] = bfhi(k1.x) * rk; v[6] = bflo(k1.y) * rk; v[7] = bfhi(k1.y) * rk;
;             v[8] = bflo(k2.x); v[9] = bfhi(k2.x); v[10] = bflo(k2.y); v[11] = bfhi(k2.y);
;             ss = 0.f;
; #pragma unroll
;             for (int j = 0; j < 12; ++j) ss += v[j] * v[j];
;             ss = sum8_dpp(ss);
;             rn = __builtin_amdgcn_rsqf(ss * (1.f / 96.f) + EPS);
; #pragma unroll
;             for (int j = 0; j < 12; ++j) v[j] = v[j] * rn * gk[j];
; #pragma unroll
;             for (int e = 0; e < 4; ++e) { const float x = v[8 + e], pt = xor4_dpp(x, sub < 4); v[8 + e] = x * cs[e] + sgn * pt * sn[e]; }
	v_mov_b32_dpp v136, v135 row_shl:4 row_mask:0xf bank_mask:0xf
	v_mov_b32_dpp v137, v135 row_shr:4 row_mask:0xf bank_mask:0xf
	v_cndmask_b32_e64 v137, v137, v136, s[42:43]
	v_cndmask_b32_e64 v136, v129, v79, s[42:43]
	v_pk_mul_f32 v[134:135], v[28:29], v[134:135]
	v_pk_mul_f32 v[136:137], v[46:47], v[136:137]
	v_pk_mul_f32 v[120:121], v[120:121], v[128:129] op_sel_hi:[1,0]
	v_pk_fma_f32 v[134:135], v[16:17], v[136:137], v[134:135]
	v_pk_mul_f32 v[120:121], v[44:45], v[120:121] op_sel:[0,1] op_sel_hi:[1,0]
	v_mov_b32_e32 v79, v33
	v_mov_b32_e32 v128, v33
	v_mov_b32_e32 v129, v33
	v_mov_b32_e32 v136, v33
	v_mov_b32_dpp v79, v120 row_shl:4 row_mask:0xf bank_mask:0xf
	v_mov_b32_dpp v128, v120 row_shr:4 row_mask:0xf bank_mask:0xf
	v_mov_b32_dpp v129, v121 row_shl:4 row_mask:0xf bank_mask:0xf
	v_mov_b32_dpp v136, v121 row_shr:4 row_mask:0xf bank_mask:0xf
	v_cndmask_b32_e64 v129, v136, v129, s[42:43]
	v_cndmask_b32_e64 v128, v128, v79, s[42:43]
	v_pk_mul_f32 v[120:121], v[122:123], v[120:121]
	v_pk_mul_f32 v[128:129], v[46:47], v[128:129]
	v_pk_mul_f32 v[130:131], v[40:41], v[130:131] op_sel:[0,1] op_sel_hi:[1,0]
	v_pk_fma_f32 v[120:121], v[30:31], v[128:129], v[120:121]
	v_lshl_or_b32 v128, v127, 3, v152
	v_ashrrev_i32_e32 v129, 31, v128
	v_lshlrev_b64 v[128:129], 11, v[128:129]
	v_lshl_add_u64 v[128:129], v[128:129], 0, v[140:141]
	v_mad_u64_u32 v[136:137], s[22:23], v128, s25, v[52:53]
	v_mad_i32_i24 v137, v129, s25, v137
	v_cvt_pk_bf16_f32 v116, v116, v117
	v_cvt_pk_bf16_f32 v117, v130, v131
	global_store_dwordx2 v[136:137], v[116:117], off offset:64
	v_cvt_pk_bf16_f32 v116, v134, v135
	v_cvt_pk_bf16_f32 v117, v120, v121
	global_store_dwordx2 v[136:137], v[116:117], off offset:128
	v_rsq_f32_e32 v116, v150
	v_pk_mul_f32 v[118:119], v[34:35], v[118:119]
	v_pk_mul_f32 v[132:133], v[36:37], v[132:133]
	v_cvt_pk_bf16_f32 v118, v118, v119
	v_cvt_pk_bf16_f32 v119, v132, v133
	s_waitcnt vmcnt(29)
	v_lshlrev_b32_e32 v140, 16, v112
	v_and_b32_e32 v141, 0xffff0000, v112
	global_store_dwordx2 v[136:137], v[118:119], off
	v_lshlrev_b32_e32 v136, 16, v113
	v_and_b32_e32 v137, 0xffff0000, v113
	v_pk_mul_f32 v[112:113], v[116:117], v[140:141] op_sel_hi:[0,1]
	v_pk_mul_f32 v[136:137], v[116:117], v[136:137] op_sel_hi:[0,1]
	v_pk_mul_f32 v[140:141], v[112:113], v[112:113]
	v_pk_mul_f32 v[138:139], v[136:137], v[136:137]
	s_waitcnt vmcnt(29)
	v_lshlrev_b32_e32 v142, 16, v110
	v_and_b32_e32 v143, 0xffff0000, v110
	v_add_f32_e32 v79, v140, v141
	v_and_b32_e32 v118, 0xffff0000, v111
	v_lshlrev_b32_e32 v119, 16, v111
	v_pk_mul_f32 v[110:111], v[116:117], v[142:143] op_sel_hi:[0,1]
	v_add_f32_e32 v79, v138, v79
	v_pk_mul_f32 v[142:143], v[110:111], v[110:111]
	v_add_f32_e32 v79, v139, v79
	v_pk_mul_f32 v[118:119], v[116:117], v[118:119] op_sel_hi:[0,1]
	v_add_f32_e32 v79, v142, v79
	v_pk_mul_f32 v[120:121], v[118:119], v[118:119]
	v_add_f32_e32 v79, v143, v79
	s_waitcnt vmcnt(28)
	v_and_b32_e32 v130, 0xffff0000, v114
	v_lshlrev_b32_e32 v131, 16, v114
	v_add_f32_e32 v79, v121, v79
	v_pk_mul_f32 v[132:133], v[130:131], v[130:131]
	v_add_f32_e32 v79, v120, v79
	v_and_b32_e32 v114, 0xffff0000, v115
	v_lshlrev_b32_e32 v115, 16, v115
	v_add_f32_e32 v79, v133, v79
	v_pk_mul_f32 v[134:135], v[114:115], v[114:115]
	v_add_f32_e32 v79, v132, v79
	v_add_f32_e32 v79, v135, v79
	v_add_f32_e32 v79, v134, v79
	v_mov_b32_e32 v117, v33
	s_nop 0
	v_add_f32_dpp v79, v79, v79 quad_perm:[1,0,3,2] row_mask:0xf bank_mask:0xf bound_ctrl:1
	s_nop 1
	v_add_f32_dpp v79, v79, v79 quad_perm:[2,3,0,1] row_mask:0xf bank_mask:0xf bound_ctrl:1
	s_nop 1
	v_add_f32_dpp v79, v79, v79 row_half_mirror row_mask:0xf bank_mask:0xf bound_ctrl:1
	v_fmamk_f32 v79, v79, 0x3c2aaaab, v9
	v_rsq_f32_e32 v120, v79
	s_nop 0
	v_mul_f32_e32 v79, v120, v131
	v_mul_f32_e32 v134, v8, v79
	v_mov_b32_e32 v79, v33
	v_mul_f32_e32 v131, v120, v130
	v_mov_b32_dpp v117, v134 row_shr:4 row_mask:0xf bank_mask:0xf
	v_mov_b32_dpp v79, v134 row_shl:4 row_mask:0xf bank_mask:0xf
	v_cndmask_b32_e64 v130, v117, v79, s[42:43]
	v_pk_mul_f32 v[130:131], v[72:73], v[130:131]
	v_mov_b32_e32 v79, v33
	v_mov_b32_e32 v117, v33
	v_pk_mul_f32 v[132:133], v[136:137], v[120:121] op_sel_hi:[1,0]
	v_mov_b32_dpp v79, v131 row_shl:4 row_mask:0xf bank_mask:0xf
	v_mov_b32_dpp v117, v131 row_shr:4 row_mask:0xf bank_mask:0xf
	v_cndmask_b32_e64 v79, v117, v79, s[42:43]
	v_mov_b32_e32 v137, v29
	v_mul_f32_e32 v135, v46, v79
	v_mov_b32_e32 v29, v17
	v_mov_b32_e32 v136, v16
	v_pk_mul_f32 v[16:17], v[28:29], v[134:135]
	v_pk_mul_f32 v[28:29], v[120:121], v[114:115] op_sel_hi:[0,1]
	v_pk_mul_f32 v[28:29], v[10:11], v[28:29] op_sel:[0,1] op_sel_hi:[1,0]
	v_mov_b32_e32 v79, v33
	v_mov_b32_e32 v114, v33
	v_mov_b32_e32 v115, v33
	v_mov_b32_e32 v117, v33
	v_mov_b32_dpp v79, v28 row_shl:4 row_mask:0xf bank_mask:0xf
	v_mov_b32_dpp v114, v28 row_shr:4 row_mask:0xf bank_mask:0xf
	v_mov_b32_dpp v115, v29 row_shl:4 row_mask:0xf bank_mask:0xf
	v_mov_b32_dpp v117, v29 row_shr:4 row_mask:0xf bank_mask:0xf
	v_cndmask_b32_e64 v115, v117, v115, s[42:43]
	v_cndmask_b32_e64 v114, v114, v79, s[42:43]
	v_pk_mul_f32 v[114:115], v[46:47], v[114:115]
	v_pk_fma_f32 v[16:17], v[136:137], v[130:131], v[16:17]
	v_pk_mul_f32 v[30:31], v[30:31], v[114:115]
	v_pk_mul_f32 v[112:113], v[112:113], v[120:121] op_sel_hi:[1,0]
	v_pk_fma_f32 v[28:29], v[122:123], v[28:29], v[30:31]
	v_mad_u64_u32 v[30:31], s[22:23], v128, s25, v[54:55]
	v_mad_i32_i24 v31, v129, s25, v31
	v_cvt_pk_bf16_f32 v16, v16, v17
	v_cvt_pk_bf16_f32 v17, v28, v29
	v_pk_mul_f32 v[112:113], v[0:1], v[112:113]
	v_pk_mul_f32 v[132:133], v[2:3], v[132:133]
	global_store_dwordx2 v[30:31], v[16:17], off offset:128
	s_waitcnt vmcnt(28)
; #define LAS __attribute__((address_space(3)))
; __device__ __forceinline__ void p3_qkv(const Args& a, LAS unsigned char* lds) {
;     ...
;             float sq = bflo(cq.x) * bflo(cq.x) + bfhi(cq.x) * bfhi(cq.x) + bflo(cq.y) * bflo(cq.y) + bfhi(cq.y) * bfhi(cq.y);
;             float sk = bflo(ckv) * bflo(ckv) + bfhi(ckv) * bfhi(ckv);
;             const float rq = __builtin_amdgcn_rsqf(wave_sum_dpp(sq) * (1.f / 256.f) + EPS), rk = __builtin_amdgcn_rsqf(wave_sum_dpp(sk) * (1.f / 128.f) + EPS);
;             const float p = (float)pos_[u];
;             float sn[4], cs[4];
; #pragma unroll
;             for (int e = 0; e < 4; ++e) sincos_rev(p * ifr[e], sn[e], cs[e]);
;     ...
;             v[0] = bflo(k0.x) * rk; v[1] = bfhi(k0.x) * rk; v[2] = bflo(k0.y) * rk; v[3] = bfhi(k0.y) * rk; v[4] = bflo(k1.x) * rk; v[5] = bfhi(k1.x) * rk; v[6] = bflo(k1.y) * rk; v[7] = bfhi(k1.y) * rk;
;             v[8] = bflo(k2.x); v[9] = bfhi(k2.x); v[10] = bflo(k2.y); v[11] = bfhi(k2.y);
;             ss = 0.f;
; #pragma unroll
;             for (int j = 0; j < 12; ++j) ss += v[j] * v[j];
;             ss = sum8_dpp(ss);
;             rn = __builtin_amdgcn_rsqf(ss * (1.f / 96.f) + EPS);
; #pragma unroll
;             for (int j = 0; j < 12; ++j) v[j] = v[j] * rn * gk[j];
; #pragma unroll
;             for (int e = 0; e < 4; ++e) { const float x = v[8 + e], pt = xor4_dpp(x, sub < 4); v[8 + e] = x * cs[e] + sgn * pt * sn[e]; }
;             { bf16* ko = Kk + ((size_t)(b * 8 + hd) * S_ + s) * 96 + 4 * sub;
; #pragma unroll
;               for (int jj = 0; jj < 3; ++jj) { u32x2 o; o.x = pk2(v[4 * jj], v[4 * jj + 1]); o.y = pk2(v[4 * jj + 2], v[4 * jj + 3]); *(u32x2*)(ko + 32 * jj) = o; } }
;             { LAS bf16* vt = vtile + (hd * 64 + 8 * sub) * 66 + tl;
;               const unsigned p0 = pk2(bflo(vv.x) * rk, bfhi(vv.x) * rk), p1 = pk2(bflo(vv.y) * rk, bfhi(vv.y) * rk), p2 = pk2(bflo(vv.z) * rk, bfhi(vv.z) * rk), p3 = pk2(bflo(vv.w) * rk, bfhi(vv.w) * rk);
;               vt[0 * 66] = (bf16)(p0 & 0xffffu); vt[1 * 66] = (bf16)(p0 >> 16); vt[2 * 66] = (bf16)(p1 & 0xffffu); vt[3 * 66] = (bf16)(p1 >> 16);
;               vt[4 * 66] = (bf16)(p2 & 0xffffu); vt[5 * 66] = (bf16)(p2 >> 16); vt[6 * 66] = (bf16)(p3 & 0xffffu); vt[7 * 66] = (bf16)(p3 >> 16); }
	v_lshlrev_b32_e32 v16, 16, v24
	v_and_b32_e32 v17, 0xffff0000, v24
	v_pk_mul_f32 v[110:111], v[110:111], v[120:121] op_sel_hi:[1,0]
	v_pk_mul_f32 v[118:119], v[118:119], v[120:121] op_sel_hi:[1,0]
	v_cvt_pk_bf16_f32 v112, v112, v113
	v_cvt_pk_bf16_f32 v113, v132, v133
	v_pk_mul_f32 v[16:17], v[116:117], v[16:17] op_sel_hi:[0,1]
	v_pk_mul_f32 v[110:111], v[4:5], v[110:111]
	v_pk_mul_f32 v[118:119], v[6:7], v[118:119] op_sel:[0,1] op_sel_hi:[1,0]
	global_store_dwordx2 v[30:31], v[112:113], off
	v_cvt_pk_bf16_f32 v112, v16, v17
	v_lshlrev_b32_e32 v16, 16, v25
	v_and_b32_e32 v17, 0xffff0000, v25
	v_cvt_pk_bf16_f32 v110, v110, v111
	v_cvt_pk_bf16_f32 v111, v118, v119
	v_pk_mul_f32 v[16:17], v[116:117], v[16:17] op_sel_hi:[0,1]
	global_store_dwordx2 v[30:31], v[110:111], off offset:64
	v_cvt_pk_bf16_f32 v111, v16, v17
	v_lshlrev_b32_e32 v16, 16, v26
	v_and_b32_e32 v17, 0xffff0000, v26
	v_pk_mul_f32 v[16:17], v[116:117], v[16:17] op_sel_hi:[0,1]
	v_cvt_pk_bf16_f32 v110, v16, v17
	v_lshlrev_b32_e32 v16, 16, v27
	v_and_b32_e32 v17, 0xffff0000, v27
	v_pk_mul_f32 v[16:17], v[116:117], v[16:17] op_sel_hi:[0,1]
	v_cvt_pk_bf16_f32 v79, v16, v17
	v_or_b32_e32 v16, 2, v163
	v_add_u32_e32 v113, s47, v16
	v_ashrrev_i32_e32 v16, 31, v113
	v_lshrrev_b32_e32 v16, 21, v16
	v_add_u32_e32 v16, v113, v16
	s_waitcnt vmcnt(29)
	v_and_b32_e32 v17, 0xffff0000, v108
	v_ashrrev_i32_e32 v121, 11, v16
	v_lshlrev_b32_e32 v16, 16, v108
	v_mul_f32_e32 v24, v17, v17
	v_fmac_f32_e32 v24, v16, v16
	v_and_b32_e32 v16, 0xffff0000, v109
	v_lshlrev_b32_e32 v17, 16, v109
	v_pk_mul_f32 v[16:17], v[16:17], v[16:17]
	s_waitcnt vmcnt(27)
	v_lshlrev_b32_e32 v130, 16, v104
	v_add_f32_e32 v17, v17, v24
	v_add_f32_e32 v24, v16, v17
	v_lshlrev_b32_e32 v16, 16, v164
	v_and_b32_e32 v17, 0xffff0000, v164
	v_pk_mul_f32 v[16:17], v[16:17], v[16:17]
	v_and_b32_e32 v131, 0xffff0000, v104
	v_add_f32_e32 v16, v16, v17
	v_add_f32_dpp v17, v24, v24 quad_perm:[1,0,3,2] row_mask:0xf bank_mask:0xf bound_ctrl:1
	v_mov_b32_e32 v24, v33
	v_add_f32_dpp v16, v16, v16 quad_perm:[1,0,3,2] row_mask:0xf bank_mask:0xf bound_ctrl:1
	v_add_f32_dpp v17, v17, v17 quad_perm:[2,3,0,1] row_mask:0xf bank_mask:0xf bound_ctrl:1
	v_lshlrev_b32_e32 v122, 16, v105
	v_add_f32_dpp v16, v16, v16 quad_perm:[2,3,0,1] row_mask:0xf bank_mask:0xf bound_ctrl:1
	v_add_f32_dpp v17, v17, v17 row_half_mirror row_mask:0xf bank_mask:0xf bound_ctrl:1
	v_and_b32_e32 v123, 0xffff0000, v105
	v_add_f32_dpp v16, v16, v16 row_half_mirror row_mask:0xf bank_mask:0xf bound_ctrl:1
	v_add_f32_dpp v17, v17, v17 row_mirror row_mask:0xf bank_mask:0xf bound_ctrl:1
	s_waitcnt vmcnt(25)
	v_lshlrev_b32_e32 v115, 16, v106
	v_add_f32_dpp v16, v16, v16 row_mirror row_mask:0xf bank_mask:0xf bound_ctrl:1
	v_mov_b32_dpp v24, v17 row_bcast:15 row_mask:0xa bank_mask:0xf
	v_add_f32_e32 v17, v17, v24
	v_mov_b32_e32 v24, v33
	v_lshlrev_b32_e32 v132, 16, v102
	v_and_b32_e32 v133, 0xffff0000, v102
	v_mov_b32_dpp v24, v17 row_bcast:31 row_mask:0xc bank_mask:0xf
	v_add_f32_e32 v17, v17, v24
	s_nop 0
	v_readlane_b32 s22, v17, 63
	v_mov_b32_e32 v17, v33
	s_nop 0
	v_fma_f32 v114, s22, v160, v9
	v_mov_b32_dpp v17, v16 row_bcast:15 row_mask:0xa bank_mask:0xf
	v_add_f32_e32 v16, v16, v17
	v_mov_b32_e32 v17, v33
	s_nop 1
	v_mov_b32_dpp v17, v16 row_bcast:31 row_mask:0xc bank_mask:0xf
	v_add_f32_e32 v16, v16, v17
	s_nop 0
	v_readlane_b32 s22, v16, 63
	v_mul_f32_e32 v16, v153, v18
	v_cvt_f64_f32_e32 v[16:17], v16
	v_mul_f64 v[24:25], v[16:17], s[20:21]
	v_rndne_f64_e32 v[24:25], v[24:25]
	v_fma_f64 v[16:17], v[16:17], s[20:21], -v[24:25]
	v_cvt_f32_f64_e32 v17, v[16:17]
	v_sin_f32_e32 v16, v17
	v_cos_f32_e32 v24, v17
	v_mul_f32_e32 v17, v154, v18
	v_cvt_f64_f32_e32 v[26:27], v17
	v_mul_f64 v[28:29], v[26:27], s[20:21]
	v_rndne_f64_e32 v[28:29], v[28:29]
	v_fma_f64 v[26:27], v[26:27], s[20:21], -v[28:29]
	v_cvt_f32_f64_e32 v25, v[26:27]
	v_mul_f32_e32 v26, v155, v18
	v_mul_f32_e32 v18, v156, v18
	v_cvt_f64_f32_e32 v[26:27], v26
	v_cvt_f64_f32_e32 v[30:31], v18
	v_mul_f64 v[28:29], v[26:27], s[20:21]
	v_mul_f64 v[108:109], v[30:31], s[20:21]
	v_rndne_f64_e32 v[28:29], v[28:29]
	v_rndne_f64_e32 v[108:109], v[108:109]
	v_fma_f64 v[26:27], v[26:27], s[20:21], -v[28:29]
	v_fma_f64 v[30:31], v[30:31], s[20:21], -v[108:109]
	v_cvt_f32_f64_e32 v27, v[26:27]
	v_cvt_f32_f64_e32 v18, v[30:31]
	v_sin_f32_e32 v26, v27
	v_cos_f32_e32 v28, v27
	v_sin_f32_e32 v27, v18
	v_cos_f32_e32 v29, v18
	v_rsq_f32_e32 v18, v114
	v_and_b32_e32 v30, 0xffff0000, v103
	v_lshlrev_b32_e32 v31, 16, v103
	v_and_b32_e32 v114, 0xffff0000, v106
	v_pk_mul_f32 v[104:105], v[18:19], v[130:131] op_sel_hi:[0,1]
	v_and_b32_e32 v106, 0xffff0000, v107
	v_lshlrev_b32_e32 v107, 16, v107
	v_mul_i32_i24_e32 v103, 0x800, v121
	v_pk_mul_f32 v[122:123], v[18:19], v[122:123] op_sel_hi:[0,1]
	v_pk_mul_f32 v[130:131], v[104:105], v[104:105]
	v_pk_mul_f32 v[30:31], v[18:19], v[30:31] op_sel_hi:[0,1]
	v_pk_mul_f32 v[114:115], v[18:19], v[114:115] op_sel_hi:[0,1]
	v_pk_mul_f32 v[106:107], v[18:19], v[106:107] op_sel_hi:[0,1]
	v_sub_u32_e32 v120, v113, v103
	v_pk_mul_f32 v[128:129], v[122:123], v[122:123]
	v_pk_mul_f32 v[102:103], v[18:19], v[132:133] op_sel_hi:[0,1]
	v_add_f32_e32 v18, v130, v131
	v_add_f32_e32 v18, v128, v18
	v_pk_mul_f32 v[132:133], v[102:103], v[102:103]
	v_add_f32_e32 v18, v129, v18
	v_add_f32_e32 v18, v132, v18
	v_pk_mul_f32 v[108:109], v[30:31], v[30:31]
	v_add_f32_e32 v18, v133, v18
	v_add_f32_e32 v18, v109, v18
	v_pk_mul_f32 v[116:117], v[114:115], v[114:115]
	v_add_f32_e32 v18, v108, v18
	v_add_f32_e32 v18, v117, v18
	v_pk_mul_f32 v[118:119], v[106:107], v[106:107]
	v_add_f32_e32 v18, v116, v18
	v_add_f32_e32 v18, v119, v18
; __device__ __forceinline__ unsigned pk2(float lo, float hi) { f32x2 v = {lo, hi}; bf16x2_t b = __builtin_convertvector(v, bf16x2_t); return __builtin_bit_cast(unsigned, b); }
; __device__ __forceinline__ void p3_qkv(const Args& a, LAS unsigned char* lds) {
;     ...
;             float ss = 0.f;
; #pragma unroll
;             for (int j = 0; j < 12; ++j) { v[j] *= rq; ss += v[j] * v[j]; }
;             ss = sum8_dpp(ss);
;             float rn = __builtin_amdgcn_rsqf(ss * (1.f / 96.f) + EPS);
; #pragma unroll
;             for (int j = 0; j < 12; ++j) v[j] = v[j] * rn * gq[j];
; #pragma unroll
;             for (int e = 0; e < 4; ++e) { const float x = v[8 + e], pt = xor4_dpp(x, sub < 4); v[8 + e] = x * cs[e] + sgn * pt * sn[e]; }
;             { bf16* qo = Q + ((size_t)(b * 8 + hd) * S_ + s) * 96 + 4 * sub;
; #pragma unroll
;               for (int jj = 0; jj < 3; ++jj) { u32x2 o; o.x = pk2(v[4 * jj], v[4 * jj + 1]); o.y = pk2(v[4 * jj + 2], v[4 * jj + 3]); *(u32x2*)(qo + 32 * jj) = o; } }
;             v[0] = bflo(k0.x) * rk; v[1] = bfhi(k0.x) * rk; v[2] = bflo(k0.y) * rk; v[3] = bfhi(k0.y) * rk; v[4] = bflo(k1.x) * rk; v[5] = bfhi(k1.x) * rk; v[6] = bflo(k1.y) * rk; v[7] = bfhi(k1.y) * rk;
;             v[8] = bflo(k2.x); v[9] = bfhi(k2.x); v[10] = bflo(k2.y); v[11] = bfhi(k2.y);
;             ss = 0.f;
; #pragma unroll
;             for (int j = 0; j < 12; ++j) ss += v[j] * v[j];
;             ss = sum8_dpp(ss);
;             rn = __builtin_amdgcn_rsqf(ss * (1.f / 96.f) + EPS);
; #pragma unroll
;             for (int j = 0; j < 12; ++j) v[j] = v[j] * rn * gk[j];
; #pragma unroll
;             for (int e = 0; e < 4; ++e) { const float x = v[8 + e], pt = xor4_dpp(x, sub < 4); v[8 + e] = x * cs[e] + sgn * pt * sn[e]; }
;             { bf16* ko = Kk + ((size_t)(b * 8 + hd) * S_ + s) * 96 + 4 * sub;
; #pragma unroll
;               for (int jj = 0; jj < 3; ++jj) { u32x2 o; o.x = pk2(v[4 * jj], v[4 * jj + 1]); o.y = pk2(v[4 * jj + 2], v[4 * jj + 3]); *(u32x2*)(ko + 32 * jj) = o; } }
	v_add_f32_e32 v18, v118, v18
	v_sin_f32_e32 v17, v25
	v_cos_f32_e32 v25, v25
	v_add_f32_dpp v18, v18, v18 quad_perm:[1,0,3,2] row_mask:0xf bank_mask:0xf bound_ctrl:1
	v_mov_b32_e32 v113, v33
	v_mov_b32_e32 v116, v33
	v_add_f32_dpp v18, v18, v18 quad_perm:[2,3,0,1] row_mask:0xf bank_mask:0xf bound_ctrl:1
	v_mov_b32_e32 v117, v33
	v_mov_b32_e32 v118, v33
	v_add_f32_dpp v18, v18, v18 row_half_mirror row_mask:0xf bank_mask:0xf bound_ctrl:1
	v_fmamk_f32 v18, v18, 0x3c2aaaab, v9
	v_rsq_f32_e32 v18, v18
	v_fma_f32 v127, s22, v161, v9
	v_pk_mul_f32 v[114:115], v[114:115], v[18:19] op_sel_hi:[1,0]
	s_nop 0
	v_pk_mul_f32 v[114:115], v[42:43], v[114:115] op_sel:[0,1] op_sel_hi:[1,0]
	v_pk_mul_f32 v[106:107], v[106:107], v[18:19] op_sel_hi:[1,0]
	v_pk_mul_f32 v[104:105], v[104:105], v[18:19] op_sel_hi:[1,0]
	v_mov_b32_dpp v113, v114 row_shl:4 row_mask:0xf bank_mask:0xf
	v_mov_b32_dpp v116, v114 row_shr:4 row_mask:0xf bank_mask:0xf
	v_mov_b32_dpp v117, v115 row_shl:4 row_mask:0xf bank_mask:0xf
	v_mov_b32_dpp v118, v115 row_shr:4 row_mask:0xf bank_mask:0xf
	v_cndmask_b32_e64 v117, v118, v117, s[42:43]
	v_cndmask_b32_e64 v116, v116, v113, s[42:43]
	v_pk_mul_f32 v[114:115], v[24:25], v[114:115]
	v_pk_mul_f32 v[116:117], v[46:47], v[116:117]
	v_pk_mul_f32 v[108:109], v[122:123], v[18:19] op_sel_hi:[1,0]
	v_pk_mul_f32 v[102:103], v[102:103], v[18:19] op_sel_hi:[1,0]
	v_pk_mul_f32 v[30:31], v[30:31], v[18:19] op_sel_hi:[1,0]
	v_pk_fma_f32 v[114:115], v[16:17], v[116:117], v[114:115]
	v_pk_mul_f32 v[106:107], v[44:45], v[106:107] op_sel:[0,1] op_sel_hi:[1,0]
	v_mov_b32_e32 v18, v33
	v_mov_b32_e32 v113, v33
	v_mov_b32_e32 v116, v33
	v_mov_b32_e32 v117, v33
	v_mov_b32_dpp v18, v106 row_shl:4 row_mask:0xf bank_mask:0xf
	v_mov_b32_dpp v113, v106 row_shr:4 row_mask:0xf bank_mask:0xf
	v_mov_b32_dpp v116, v107 row_shl:4 row_mask:0xf bank_mask:0xf
	v_mov_b32_dpp v117, v107 row_shr:4 row_mask:0xf bank_mask:0xf
	v_cndmask_b32_e64 v117, v117, v116, s[42:43]
	v_cndmask_b32_e64 v116, v113, v18, s[42:43]
	v_pk_mul_f32 v[106:107], v[28:29], v[106:107]
	v_pk_mul_f32 v[116:117], v[46:47], v[116:117]
	v_rsq_f32_e32 v18, v127
	v_pk_fma_f32 v[106:107], v[26:27], v[116:117], v[106:107]
	v_lshl_or_b32 v116, v121, 3, v152
	v_ashrrev_i32_e32 v117, 31, v116
	v_lshlrev_b64 v[116:117], 11, v[116:117]
	v_ashrrev_i32_e32 v121, 31, v120
	v_pk_mul_f32 v[102:103], v[38:39], v[102:103]
	v_pk_mul_f32 v[30:31], v[40:41], v[30:31] op_sel:[0,1] op_sel_hi:[1,0]
	v_lshl_add_u64 v[116:117], v[116:117], 0, v[120:121]
	s_waitcnt vmcnt(24)
	v_lshlrev_b32_e32 v120, 16, v98
	v_and_b32_e32 v121, 0xffff0000, v98
	v_pk_mul_f32 v[104:105], v[34:35], v[104:105]
	v_pk_mul_f32 v[108:109], v[36:37], v[108:109]
	v_mad_u64_u32 v[118:119], s[22:23], v116, s25, v[52:53]
	v_cvt_pk_bf16_f32 v102, v102, v103
	v_cvt_pk_bf16_f32 v103, v30, v31
	v_cvt_pk_bf16_f32 v30, v114, v115
	v_lshlrev_b32_e32 v114, 16, v99
	v_and_b32_e32 v115, 0xffff0000, v99
	v_pk_mul_f32 v[98:99], v[18:19], v[120:121] op_sel_hi:[0,1]
	v_mad_i32_i24 v119, v117, s25, v119
	v_cvt_pk_bf16_f32 v104, v104, v105
	v_cvt_pk_bf16_f32 v105, v108, v109
	v_cvt_pk_bf16_f32 v31, v106, v107
	v_pk_mul_f32 v[114:115], v[18:19], v[114:115] op_sel_hi:[0,1]
	v_pk_mul_f32 v[120:121], v[98:99], v[98:99]
	global_store_dwordx2 v[118:119], v[104:105], off
	global_store_dwordx2 v[118:119], v[102:103], off offset:64
	global_store_dwordx2 v[118:119], v[30:31], off offset:128
	v_pk_mul_f32 v[118:119], v[114:115], v[114:115]
	s_waitcnt vmcnt(26)
	v_lshlrev_b32_e32 v122, 16, v96
	v_and_b32_e32 v123, 0xffff0000, v96
	v_add_f32_e32 v113, v120, v121
	v_and_b32_e32 v30, 0xffff0000, v97
	v_lshlrev_b32_e32 v31, 16, v97
	v_pk_mul_f32 v[96:97], v[18:19], v[122:123] op_sel_hi:[0,1]
	v_add_f32_e32 v113, v118, v113
	v_pk_mul_f32 v[122:123], v[96:97], v[96:97]
	v_add_f32_e32 v113, v119, v113
	v_pk_mul_f32 v[30:31], v[18:19], v[30:31] op_sel_hi:[0,1]
	v_add_f32_e32 v113, v122, v113
	v_pk_mul_f32 v[102:103], v[30:31], v[30:31]
	v_add_f32_e32 v113, v123, v113
	s_waitcnt vmcnt(25)
	v_and_b32_e32 v104, 0xffff0000, v100
	v_lshlrev_b32_e32 v105, 16, v100
	v_add_f32_e32 v103, v103, v113
	v_pk_mul_f32 v[106:107], v[104:105], v[104:105]
	v_add_f32_e32 v102, v102, v103
	v_and_b32_e32 v100, 0xffff0000, v101
	v_lshlrev_b32_e32 v101, 16, v101
	v_add_f32_e32 v102, v107, v102
	v_pk_mul_f32 v[108:109], v[100:101], v[100:101]
	v_add_f32_e32 v102, v106, v102
	v_add_f32_e32 v102, v109, v102
	v_add_f32_e32 v102, v108, v102
	v_mov_b32_e32 v109, v33
	s_nop 0
	v_add_f32_dpp v102, v102, v102 quad_perm:[1,0,3,2] row_mask:0xf bank_mask:0xf bound_ctrl:1
	s_nop 1
	v_add_f32_dpp v102, v102, v102 quad_perm:[2,3,0,1] row_mask:0xf bank_mask:0xf bound_ctrl:1
	s_nop 1
	v_add_f32_dpp v102, v102, v102 row_half_mirror row_mask:0xf bank_mask:0xf bound_ctrl:1
	v_fmamk_f32 v102, v102, 0x3c2aaaab, v9
	v_rsq_f32_e32 v102, v102
	s_nop 0
	v_pk_mul_f32 v[98:99], v[98:99], v[102:103] op_sel_hi:[1,0]
	v_pk_mul_f32 v[106:107], v[114:115], v[102:103] op_sel_hi:[1,0]
	v_pk_mul_f32 v[96:97], v[96:97], v[102:103] op_sel_hi:[1,0]
	v_pk_mul_f32 v[30:31], v[30:31], v[102:103] op_sel_hi:[1,0]
	v_mul_f32_e32 v103, v102, v105
	v_mul_f32_e32 v105, v102, v104
	v_mul_f32_e32 v108, v8, v103
	v_mov_b32_e32 v103, v33
	v_mov_b32_e32 v104, v33
	v_mov_b32_e32 v115, v25
	v_mov_b32_dpp v103, v108 row_shl:4 row_mask:0xf bank_mask:0xf
	v_mov_b32_dpp v104, v108 row_shr:4 row_mask:0xf bank_mask:0xf
	v_cndmask_b32_e64 v104, v104, v103, s[42:43]
	v_pk_mul_f32 v[104:105], v[72:73], v[104:105]
	v_mov_b32_e32 v103, v33
	v_mov_b32_e32 v25, v17
	v_mov_b32_dpp v109, v105 row_shr:4 row_mask:0xf bank_mask:0xf
	v_mov_b32_dpp v103, v105 row_shl:4 row_mask:0xf bank_mask:0xf
	v_cndmask_b32_e64 v103, v109, v103, s[42:43]
	v_mul_f32_e32 v109, v46, v103
	v_mov_b32_e32 v114, v16
	v_pk_mul_f32 v[16:17], v[24:25], v[108:109]
	v_pk_mul_f32 v[24:25], v[102:103], v[100:101] op_sel_hi:[0,1]
	v_pk_mul_f32 v[24:25], v[10:11], v[24:25] op_sel:[0,1] op_sel_hi:[1,0]
	v_mov_b32_e32 v100, v33
	v_mov_b32_e32 v102, v33
	v_mov_b32_e32 v101, v33
	v_mov_b32_e32 v103, v33
	v_mov_b32_dpp v100, v24 row_shl:4 row_mask:0xf bank_mask:0xf
	v_mov_b32_dpp v102, v24 row_shr:4 row_mask:0xf bank_mask:0xf
	v_mov_b32_dpp v101, v25 row_shl:4 row_mask:0xf bank_mask:0xf
	v_mov_b32_dpp v103, v25 row_shr:4 row_mask:0xf bank_mask:0xf
	v_cndmask_b32_e64 v101, v103, v101, s[42:43]
	v_cndmask_b32_e64 v100, v102, v100, s[42:43]
	v_pk_mul_f32 v[100:101], v[46:47], v[100:101]
	v_pk_fma_f32 v[16:17], v[114:115], v[104:105], v[16:17]
	v_pk_mul_f32 v[26:27], v[26:27], v[100:101]
	v_cvt_pk_bf16_f32 v16, v16, v17
	v_pk_fma_f32 v[24:25], v[28:29], v[24:25], v[26:27]
	v_mad_u64_u32 v[26:27], s[22:23], v116, s25, v[54:55]
	v_mad_i32_i24 v27, v117, s25, v27
	v_cvt_pk_bf16_f32 v17, v24, v25
	global_store_dwordx2 v[26:27], v[16:17], off offset:128
	s_waitcnt vmcnt(25)
; __device__ __forceinline__ unsigned pk2(float lo, float hi) { f32x2 v = {lo, hi}; bf16x2_t b = __builtin_convertvector(v, bf16x2_t); return __builtin_bit_cast(unsigned, b); }
; __device__ __forceinline__ void p3_qkv(const Args& a, LAS unsigned char* lds) {
;     ...
;             float sq = bflo(cq.x) * bflo(cq.x) + bfhi(cq.x) * bfhi(cq.x) + bflo(cq.y) * bflo(cq.y) + bfhi(cq.y) * bfhi(cq.y);
;             float sk = bflo(ckv) * bflo(ckv) + bfhi(ckv) * bfhi(ckv);
;             const float rq = __builtin_amdgcn_rsqf(wave_sum_dpp(sq) * (1.f / 256.f) + EPS), rk = __builtin_amdgcn_rsqf(wave_sum_dpp(sk) * (1.f / 128.f) + EPS);
;             const float p = (float)pos_[u];
;             float sn[4], cs[4];
; #pragma unroll
;             for (int e = 0; e < 4; ++e) sincos_rev(p * ifr[e], sn[e], cs[e]);
;             float v[12];
;             v[0] = bflo(q0.x); v[1] = bfhi(q0.x); v[2] = bflo(q0.y); v[3] = bfhi(q0.y); v[4] = bflo(q1.x); v[5] = bfhi(q1.x); v[6] = bflo(q1.y); v[7] = bfhi(q1.y);
;             v[8] = bflo(q2.x); v[9] = bfhi(q2.x); v[10] = bflo(q2.y); v[11] = bfhi(q2.y);
;             float ss = 0.f;
; #pragma unroll
;             for (int j = 0; j < 12; ++j) { v[j] *= rq; ss += v[j] * v[j]; }
;             ss = sum8_dpp(ss);
;             float rn = __builtin_amdgcn_rsqf(ss * (1.f / 96.f) + EPS);
; #pragma unroll
;             for (int j = 0; j < 12; ++j) v[j] = v[j] * rn * gq[j];
;     ...
;               const unsigned p0 = pk2(bflo(vv.x) * rk, bfhi(vv.x) * rk), p1 = pk2(bflo(vv.y) * rk, bfhi(vv.y) * rk), p2 = pk2(bflo(vv.z) * rk, bfhi(vv.z) * rk), p3 = pk2(bflo(vv.w) * rk, bfhi(vv.w) * rk);
	v_lshlrev_b32_e32 v16, 16, v20
	v_and_b32_e32 v17, 0xffff0000, v20
	v_pk_mul_f32 v[16:17], v[18:19], v[16:17] op_sel_hi:[0,1]
	v_cvt_pk_bf16_f32 v102, v16, v17
	v_lshlrev_b32_e32 v16, 16, v21
	v_and_b32_e32 v17, 0xffff0000, v21
	v_pk_mul_f32 v[16:17], v[18:19], v[16:17] op_sel_hi:[0,1]
	v_cvt_pk_bf16_f32 v101, v16, v17
	v_lshlrev_b32_e32 v16, 16, v22
	v_and_b32_e32 v17, 0xffff0000, v22
	v_pk_mul_f32 v[16:17], v[18:19], v[16:17] op_sel_hi:[0,1]
	v_cvt_pk_bf16_f32 v100, v16, v17
	v_lshlrev_b32_e32 v16, 16, v23
	v_and_b32_e32 v17, 0xffff0000, v23
	s_waitcnt vmcnt(24)
	v_and_b32_e32 v20, 0xffff0000, v94
	v_pk_mul_f32 v[16:17], v[18:19], v[16:17] op_sel_hi:[0,1]
	v_lshlrev_b32_e32 v18, 16, v94
	v_mul_f32_e32 v22, v20, v20
	v_and_b32_e32 v20, 0xffff0000, v95
	v_lshlrev_b32_e32 v21, 16, v95
	v_fmac_f32_e32 v22, v18, v18
	v_pk_mul_f32 v[20:21], v[20:21], v[20:21]
	v_pk_mul_f32 v[98:99], v[0:1], v[98:99]
	v_add_f32_e32 v18, v21, v22
	v_add_f32_e32 v18, v20, v18
	s_waitcnt vmcnt(23)
	v_lshlrev_b32_e32 v20, 16, v162
	v_and_b32_e32 v21, 0xffff0000, v162
	v_add_f32_dpp v18, v18, v18 quad_perm:[1,0,3,2] row_mask:0xf bank_mask:0xf bound_ctrl:1
	v_pk_mul_f32 v[20:21], v[20:21], v[20:21]
	v_pk_mul_f32 v[106:107], v[2:3], v[106:107]
	v_add_f32_dpp v18, v18, v18 quad_perm:[2,3,0,1] row_mask:0xf bank_mask:0xf bound_ctrl:1
	v_add_f32_e32 v20, v20, v21
	v_mov_b32_e32 v21, v33
	v_add_f32_dpp v18, v18, v18 row_half_mirror row_mask:0xf bank_mask:0xf bound_ctrl:1
	v_pk_mul_f32 v[96:97], v[4:5], v[96:97]
	v_pk_mul_f32 v[30:31], v[6:7], v[30:31] op_sel:[0,1] op_sel_hi:[1,0]
	v_add_f32_dpp v18, v18, v18 row_mirror row_mask:0xf bank_mask:0xf bound_ctrl:1
	v_cvt_pk_bf16_f32 v28, v98, v99
	v_cvt_pk_bf16_f32 v29, v106, v107
	v_mov_b32_dpp v21, v18 row_bcast:15 row_mask:0xa bank_mask:0xf
	v_add_f32_e32 v18, v18, v21
	v_mov_b32_e32 v21, v33
	global_store_dwordx2 v[26:27], v[28:29], off
	v_cvt_pk_bf16_f32 v28, v96, v97
	v_mov_b32_dpp v21, v18 row_bcast:31 row_mask:0xc bank_mask:0xf
	v_add_f32_e32 v18, v18, v21
	v_cvt_pk_bf16_f32 v29, v30, v31
	v_readlane_b32 s22, v18, 63
	v_add_f32_dpp v18, v20, v20 quad_perm:[1,0,3,2] row_mask:0xf bank_mask:0xf bound_ctrl:1
	v_mov_b32_e32 v20, v33
	global_store_dwordx2 v[26:27], v[28:29], off offset:64
	v_add_f32_dpp v18, v18, v18 quad_perm:[2,3,0,1] row_mask:0xf bank_mask:0xf bound_ctrl:1
	v_cvt_f32_i32_e32 v26, v19
	v_fma_f32 v30, s22, v160, v9
	v_add_f32_dpp v18, v18, v18 row_half_mirror row_mask:0xf bank_mask:0xf bound_ctrl:1
	v_cvt_pk_bf16_f32 v99, v16, v17
	v_or_b32_e32 v16, 3, v163
	v_add_f32_dpp v18, v18, v18 row_mirror row_mask:0xf bank_mask:0xf bound_ctrl:1
	v_add_u32_e32 v16, s47, v16
	v_rsq_f32_e32 v98, v30
	v_mov_b32_dpp v20, v18 row_bcast:15 row_mask:0xa bank_mask:0xf
	v_add_f32_e32 v18, v18, v20
	v_mov_b32_e32 v20, v33
	v_ashrrev_i32_e32 v17, 31, v16
	v_lshrrev_b32_e32 v17, 21, v17
	v_mov_b32_dpp v20, v18 row_bcast:31 row_mask:0xc bank_mask:0xf
	v_add_f32_e32 v18, v18, v20
	v_add_u32_e32 v17, v16, v17
	v_readlane_b32 s22, v18, 63
	v_mul_f32_e32 v18, v153, v26
	v_cvt_f64_f32_e32 v[18:19], v18
	v_mul_f64 v[20:21], v[18:19], s[20:21]
	v_rndne_f64_e32 v[20:21], v[20:21]
	v_fma_f64 v[18:19], v[18:19], s[20:21], -v[20:21]
	v_cvt_f32_f64_e32 v18, v[18:19]
	v_mul_f32_e32 v19, v154, v26
	v_cvt_f64_f32_e32 v[20:21], v19
	v_mul_f64 v[22:23], v[20:21], s[20:21]
	v_rndne_f64_e32 v[22:23], v[22:23]
	v_fma_f64 v[20:21], v[20:21], s[20:21], -v[22:23]
	v_cvt_f32_f64_e32 v19, v[20:21]
	v_mul_f32_e32 v20, v155, v26
	v_cvt_f64_f32_e32 v[20:21], v20
	v_mul_f64 v[22:23], v[20:21], s[20:21]
	v_rndne_f64_e32 v[22:23], v[22:23]
	v_fma_f64 v[20:21], v[20:21], s[20:21], -v[22:23]
	v_cvt_f32_f64_e32 v21, v[20:21]
	v_sin_f32_e32 v20, v21
	v_cos_f32_e32 v22, v21
	v_mul_f32_e32 v21, v156, v26
	v_cvt_f64_f32_e32 v[26:27], v21
	v_mul_f64 v[28:29], v[26:27], s[20:21]
	v_rndne_f64_e32 v[28:29], v[28:29]
	v_fma_f64 v[26:27], v[26:27], s[20:21], -v[28:29]
	v_cvt_f32_f64_e32 v23, v[26:27]
	s_waitcnt vmcnt(23)
	v_and_b32_e32 v26, 0xffff0000, v89
	v_lshlrev_b32_e32 v27, 16, v89
	v_lshlrev_b32_e32 v108, 16, v90
	v_and_b32_e32 v109, 0xffff0000, v90
	v_ashrrev_i32_e32 v17, 11, v17
	v_pk_mul_f32 v[94:95], v[98:99], v[26:27] op_sel_hi:[0,1]
	s_waitcnt vmcnt(22)
	v_and_b32_e32 v26, 0xffff0000, v92
	v_lshlrev_b32_e32 v27, 16, v92
	v_lshlrev_b32_e32 v104, 16, v91
	v_and_b32_e32 v105, 0xffff0000, v91
	v_pk_mul_f32 v[90:91], v[98:99], v[108:109] op_sel_hi:[0,1]
	v_pk_mul_f32 v[96:97], v[98:99], v[26:27] op_sel_hi:[0,1]
	v_and_b32_e32 v26, 0xffff0000, v93
	v_lshlrev_b32_e32 v27, 16, v93
	v_mul_i32_i24_e32 v89, 0x800, v17
	v_pk_mul_f32 v[104:105], v[98:99], v[104:105] op_sel_hi:[0,1]
	v_pk_mul_f32 v[108:109], v[90:91], v[90:91]
	v_lshlrev_b32_e32 v114, 16, v88
	v_and_b32_e32 v115, 0xffff0000, v88
	v_pk_mul_f32 v[26:27], v[98:99], v[26:27] op_sel_hi:[0,1]
	v_sub_u32_e32 v16, v16, v89
	v_pk_mul_f32 v[106:107], v[104:105], v[104:105]
	v_pk_mul_f32 v[88:89], v[98:99], v[114:115] op_sel_hi:[0,1]
	v_add_f32_e32 v98, v108, v109
	v_add_f32_e32 v98, v106, v98
	v_pk_mul_f32 v[114:115], v[88:89], v[88:89]
	v_add_f32_e32 v98, v107, v98
	v_add_f32_e32 v98, v114, v98
	v_pk_mul_f32 v[28:29], v[94:95], v[94:95]
	v_add_f32_e32 v98, v115, v98
	v_add_f32_e32 v29, v29, v98
	v_pk_mul_f32 v[30:31], v[96:97], v[96:97]
	v_add_f32_e32 v28, v28, v29
	v_add_f32_e32 v28, v31, v28
	v_pk_mul_f32 v[92:93], v[26:27], v[26:27]
	v_add_f32_e32 v28, v30, v28
	v_add_f32_e32 v28, v93, v28
	v_add_f32_e32 v28, v92, v28
	v_sin_f32_e32 v24, v18
	v_cos_f32_e32 v18, v18
	v_add_f32_dpp v28, v28, v28 quad_perm:[1,0,3,2] row_mask:0xf bank_mask:0xf bound_ctrl:1
	v_sin_f32_e32 v25, v19
	v_cos_f32_e32 v19, v19
	v_add_f32_dpp v28, v28, v28 quad_perm:[2,3,0,1] row_mask:0xf bank_mask:0xf bound_ctrl:1
	v_sin_f32_e32 v21, v23
	v_cos_f32_e32 v23, v23
	v_add_f32_dpp v28, v28, v28 row_half_mirror row_mask:0xf bank_mask:0xf bound_ctrl:1
	v_fmamk_f32 v28, v28, 0x3c2aaaab, v9
	v_rsq_f32_e32 v98, v28
	v_fma_f32 v103, s22, v161, v9
	s_waitcnt vmcnt(20)
; __device__ __forceinline__ unsigned pk2(float lo, float hi) { f32x2 v = {lo, hi}; bf16x2_t b = __builtin_convertvector(v, bf16x2_t); return __builtin_bit_cast(unsigned, b); }
; __device__ __forceinline__ void p3_qkv(const Args& a, LAS unsigned char* lds) {
;     ...
;             for (int j = 0; j < 12; ++j) v[j] = v[j] * rn * gq[j];
; #pragma unroll
;             for (int e = 0; e < 4; ++e) { const float x = v[8 + e], pt = xor4_dpp(x, sub < 4); v[8 + e] = x * cs[e] + sgn * pt * sn[e]; }
;             { bf16* qo = Q + ((size_t)(b * 8 + hd) * S_ + s) * 96 + 4 * sub;
; #pragma unroll
;               for (int jj = 0; jj < 3; ++jj) { u32x2 o; o.x = pk2(v[4 * jj], v[4 * jj + 1]); o.y = pk2(v[4 * jj + 2], v[4 * jj + 3]); *(u32x2*)(qo + 32 * jj) = o; } }
;             v[0] = bflo(k0.x) * rk; v[1] = bfhi(k0.x) * rk; v[2] = bflo(k0.y) * rk; v[3] = bfhi(k0.y) * rk; v[4] = bflo(k1.x) * rk; v[5] = bfhi(k1.x) * rk; v[6] = bflo(k1.y) * rk; v[7] = bfhi(k1.y) * rk;
;             v[8] = bflo(k2.x); v[9] = bfhi(k2.x); v[10] = bflo(k2.y); v[11] = bfhi(k2.y);
;             ss = 0.f;
; #pragma unroll
;             for (int j = 0; j < 12; ++j) ss += v[j] * v[j];
;             ss = sum8_dpp(ss);
;             rn = __builtin_amdgcn_rsqf(ss * (1.f / 96.f) + EPS);
; #pragma unroll
;             for (int j = 0; j < 12; ++j) v[j] = v[j] * rn * gk[j];
; #pragma unroll
;             for (int e = 0; e < 4; ++e) { const float x = v[8 + e], pt = xor4_dpp(x, sub < 4); v[8 + e] = x * cs[e] + sgn * pt * sn[e]; }
;             { bf16* ko = Kk + ((size_t)(b * 8 + hd) * S_ + s) * 96 + 4 * sub;
; #pragma unroll
;               for (int jj = 0; jj < 3; ++jj) { u32x2 o; o.x = pk2(v[4 * jj], v[4 * jj + 1]); o.y = pk2(v[4 * jj + 2], v[4 * jj + 3]); *(u32x2*)(ko + 32 * jj) = o; } }
	v_lshlrev_b32_e32 v106, 16, v82
	v_and_b32_e32 v107, 0xffff0000, v82
	v_pk_mul_f32 v[92:93], v[96:97], v[98:99] op_sel_hi:[1,0]
	v_pk_mul_f32 v[28:29], v[90:91], v[98:99] op_sel_hi:[1,0]
	v_pk_mul_f32 v[90:91], v[94:95], v[98:99] op_sel_hi:[1,0]
	v_pk_mul_f32 v[92:93], v[42:43], v[92:93] op_sel:[0,1] op_sel_hi:[1,0]
	v_mov_b32_e32 v94, v33
	v_mov_b32_e32 v96, v33
	v_mov_b32_e32 v95, v33
	v_mov_b32_e32 v97, v33
	v_mov_b32_dpp v94, v92 row_shl:4 row_mask:0xf bank_mask:0xf
	v_mov_b32_dpp v96, v92 row_shr:4 row_mask:0xf bank_mask:0xf
	v_mov_b32_dpp v95, v93 row_shl:4 row_mask:0xf bank_mask:0xf
	v_mov_b32_dpp v97, v93 row_shr:4 row_mask:0xf bank_mask:0xf
	v_cndmask_b32_e64 v95, v97, v95, s[42:43]
	v_cndmask_b32_e64 v94, v96, v94, s[42:43]
	v_pk_mul_f32 v[92:93], v[18:19], v[92:93]
	v_pk_mul_f32 v[94:95], v[46:47], v[94:95]
	v_pk_mul_f32 v[26:27], v[26:27], v[98:99] op_sel_hi:[1,0]
	v_pk_fma_f32 v[92:93], v[24:25], v[94:95], v[92:93]
	v_pk_mul_f32 v[26:27], v[44:45], v[26:27] op_sel:[0,1] op_sel_hi:[1,0]
	v_mov_b32_e32 v94, v33
	v_mov_b32_e32 v96, v33
	v_mov_b32_e32 v95, v33
	v_mov_b32_e32 v97, v33
	v_mov_b32_dpp v94, v26 row_shl:4 row_mask:0xf bank_mask:0xf
	v_mov_b32_dpp v96, v26 row_shr:4 row_mask:0xf bank_mask:0xf
	v_mov_b32_dpp v95, v27 row_shl:4 row_mask:0xf bank_mask:0xf
	v_mov_b32_dpp v97, v27 row_shr:4 row_mask:0xf bank_mask:0xf
	v_cndmask_b32_e64 v95, v97, v95, s[42:43]
	v_cndmask_b32_e64 v94, v96, v94, s[42:43]
	v_pk_mul_f32 v[26:27], v[22:23], v[26:27]
	v_pk_mul_f32 v[94:95], v[46:47], v[94:95]
	v_pk_mul_f32 v[30:31], v[104:105], v[98:99] op_sel_hi:[1,0]
	v_pk_fma_f32 v[94:95], v[20:21], v[94:95], v[26:27]
	v_lshl_or_b32 v26, v17, 3, v152
	v_ashrrev_i32_e32 v27, 31, v26
	v_lshlrev_b64 v[26:27], 11, v[26:27]
	v_ashrrev_i32_e32 v17, 31, v16
	v_lshl_add_u64 v[26:27], v[26:27], 0, v[16:17]
	v_pk_mul_f32 v[28:29], v[34:35], v[28:29]
	v_pk_mul_f32 v[30:31], v[36:37], v[30:31]
	v_pk_mul_f32 v[88:89], v[88:89], v[98:99] op_sel_hi:[1,0]
	v_mad_u64_u32 v[16:17], s[22:23], v26, s25, v[52:53]
	v_pk_mul_f32 v[88:89], v[38:39], v[88:89]
	v_pk_mul_f32 v[90:91], v[40:41], v[90:91] op_sel:[0,1] op_sel_hi:[1,0]
	v_mad_i32_i24 v17, v27, s25, v17
	v_cvt_pk_bf16_f32 v28, v28, v29
	v_cvt_pk_bf16_f32 v29, v30, v31
	global_store_dwordx2 v[16:17], v[28:29], off
	v_cvt_pk_bf16_f32 v28, v88, v89
	v_cvt_pk_bf16_f32 v29, v90, v91
	global_store_dwordx2 v[16:17], v[28:29], off offset:64
	v_cvt_pk_bf16_f32 v28, v92, v93
	v_cvt_pk_bf16_f32 v29, v94, v95
	global_store_dwordx2 v[16:17], v[28:29], off offset:128
	v_rsq_f32_e32 v16, v103
	v_lshlrev_b32_e32 v104, 16, v84
	v_and_b32_e32 v105, 0xffff0000, v84
	v_lshlrev_b32_e32 v94, 16, v85
	v_and_b32_e32 v95, 0xffff0000, v85
	v_pk_mul_f32 v[84:85], v[16:17], v[104:105] op_sel_hi:[0,1]
	v_and_b32_e32 v28, 0xffff0000, v83
	v_lshlrev_b32_e32 v29, 16, v83
	v_pk_mul_f32 v[94:95], v[16:17], v[94:95] op_sel_hi:[0,1]
	v_pk_mul_f32 v[104:105], v[84:85], v[84:85]
	v_pk_mul_f32 v[88:89], v[16:17], v[28:29] op_sel_hi:[0,1]
	v_pk_mul_f32 v[96:97], v[94:95], v[94:95]
	v_pk_mul_f32 v[82:83], v[16:17], v[106:107] op_sel_hi:[0,1]
	v_add_f32_e32 v17, v104, v105
	v_add_f32_e32 v17, v96, v17
	v_pk_mul_f32 v[106:107], v[82:83], v[82:83]
	v_add_f32_e32 v17, v97, v17
	v_add_f32_e32 v17, v106, v17
	v_pk_mul_f32 v[28:29], v[88:89], v[88:89]
	v_add_f32_e32 v17, v107, v17
	s_waitcnt vmcnt(22)
	v_and_b32_e32 v90, 0xffff0000, v86
	v_lshlrev_b32_e32 v91, 16, v86
	v_add_f32_e32 v17, v29, v17
	v_pk_mul_f32 v[30:31], v[90:91], v[90:91]
	v_add_f32_e32 v17, v28, v17
	v_and_b32_e32 v86, 0xffff0000, v87
	v_lshlrev_b32_e32 v87, 16, v87
	v_add_f32_e32 v17, v31, v17
	v_pk_mul_f32 v[92:93], v[86:87], v[86:87]
	v_add_f32_e32 v17, v30, v17
	v_add_f32_e32 v17, v93, v17
	v_add_f32_e32 v17, v92, v17
	s_nop 1
	v_add_f32_dpp v17, v17, v17 quad_perm:[1,0,3,2] row_mask:0xf bank_mask:0xf bound_ctrl:1
	s_nop 1
	v_add_f32_dpp v17, v17, v17 quad_perm:[2,3,0,1] row_mask:0xf bank_mask:0xf bound_ctrl:1
	s_nop 1
	v_add_f32_dpp v17, v17, v17 row_half_mirror row_mask:0xf bank_mask:0xf bound_ctrl:1
	v_fmamk_f32 v17, v17, 0x3c2aaaab, v9
	v_rsq_f32_e32 v92, v17
	s_nop 0
	v_mul_f32_e32 v17, v92, v91
	v_pk_mul_f32 v[28:29], v[84:85], v[92:93] op_sel_hi:[1,0]
	v_pk_mul_f32 v[84:85], v[88:89], v[92:93] op_sel_hi:[1,0]
	v_mul_f32_e32 v89, v92, v90
	v_mul_f32_e32 v90, v8, v17
	v_mov_b32_e32 v17, v33
	v_mov_b32_e32 v88, v33
	v_mov_b32_e32 v91, v33
	v_mov_b32_dpp v17, v90 row_shl:4 row_mask:0xf bank_mask:0xf
	v_mov_b32_dpp v88, v90 row_shr:4 row_mask:0xf bank_mask:0xf
	v_cndmask_b32_e64 v88, v88, v17, s[42:43]
	v_pk_mul_f32 v[88:89], v[72:73], v[88:89]
	v_mov_b32_e32 v17, v33
	v_pk_mul_f32 v[30:31], v[94:95], v[92:93] op_sel_hi:[1,0]
	v_mov_b32_dpp v91, v89 row_shr:4 row_mask:0xf bank_mask:0xf
	v_mov_b32_dpp v17, v89 row_shl:4 row_mask:0xf bank_mask:0xf
	v_cndmask_b32_e64 v17, v91, v17, s[42:43]
	v_mov_b32_e32 v95, v19
	v_mul_f32_e32 v91, v46, v17
	v_mov_b32_e32 v19, v25
	v_mov_b32_e32 v94, v24
	v_pk_mul_f32 v[18:19], v[18:19], v[90:91]
	v_pk_mul_f32 v[24:25], v[92:93], v[86:87] op_sel_hi:[0,1]
	v_pk_fma_f32 v[18:19], v[94:95], v[88:89], v[18:19]
	v_pk_mul_f32 v[24:25], v[10:11], v[24:25] op_sel:[0,1] op_sel_hi:[1,0]
	v_mov_b32_e32 v17, v33
	v_mov_b32_e32 v86, v33
	v_mov_b32_e32 v87, v33
	v_mov_b32_e32 v88, v33
	v_mov_b32_dpp v17, v24 row_shl:4 row_mask:0xf bank_mask:0xf
	v_mov_b32_dpp v86, v24 row_shr:4 row_mask:0xf bank_mask:0xf
	v_mov_b32_dpp v87, v25 row_shl:4 row_mask:0xf bank_mask:0xf
	v_mov_b32_dpp v88, v25 row_shr:4 row_mask:0xf bank_mask:0xf
	v_cndmask_b32_e64 v87, v88, v87, s[42:43]
	v_cndmask_b32_e64 v86, v86, v17, s[42:43]
	v_pk_mul_f32 v[86:87], v[46:47], v[86:87]
	v_cvt_pk_bf16_f32 v18, v18, v19
	v_pk_mul_f32 v[20:21], v[20:21], v[86:87]
	v_pk_mul_f32 v[28:29], v[0:1], v[28:29]
	v_pk_fma_f32 v[20:21], v[22:23], v[24:25], v[20:21]
	v_mad_u64_u32 v[22:23], s[22:23], v26, s25, v[54:55]
	v_mad_i32_i24 v23, v27, s25, v23
	v_cvt_pk_bf16_f32 v19, v20, v21
	global_store_dwordx2 v[22:23], v[18:19], off offset:128
	s_waitcnt vmcnt(22)
; #define LAS __attribute__((address_space(3)))
; __device__ __forceinline__ unsigned pk2(float lo, float hi) { f32x2 v = {lo, hi}; bf16x2_t b = __builtin_convertvector(v, bf16x2_t); return __builtin_bit_cast(unsigned, b); }
; __device__ __forceinline__ void p3_qkv(const Args& a, LAS unsigned char* lds) {
;     ...
;             { LAS bf16* vt = vtile + (hd * 64 + 8 * sub) * 66 + tl;
;               const unsigned p0 = pk2(bflo(vv.x) * rk, bfhi(vv.x) * rk), p1 = pk2(bflo(vv.y) * rk, bfhi(vv.y) * rk), p2 = pk2(bflo(vv.z) * rk, bfhi(vv.z) * rk), p3 = pk2(bflo(vv.w) * rk, bfhi(vv.w) * rk);
;               vt[0 * 66] = (bf16)(p0 & 0xffffu); vt[1 * 66] = (bf16)(p0 >> 16); vt[2 * 66] = (bf16)(p1 & 0xffffu); vt[3 * 66] = (bf16)(p1 >> 16);
;               vt[4 * 66] = (bf16)(p2 & 0xffffu); vt[5 * 66] = (bf16)(p2 >> 16); vt[6 * 66] = (bf16)(p3 & 0xffffu); vt[7 * 66] = (bf16)(p3 >> 16); }
;           }
;         }
;         __syncthreads();
;         { const int b = (item * 64) / S_, s0 = (item * 64) % S_; const int c8 = tid & 7;
; #pragma unroll
;           for (int k = 0; k < 8; ++k) { const int row = (tid >> 3) + 64 * k;
;               const LAS unsigned* src = (const LAS unsigned*)(vtile + row * 66 + c8 * 8);
;               u32x4 o; o.x = src[0]; o.y = src[1]; o.z = src[2]; o.w = src[3];
;               *(u32x4*)(Vt + ((size_t)b * 512 + row) * S_ + s0 + 8 * c8) = o; } }
	v_lshlrev_b32_e32 v18, 16, v12
	v_and_b32_e32 v19, 0xffff0000, v12
	v_pk_mul_f32 v[18:19], v[16:17], v[18:19] op_sel_hi:[0,1]
	v_cvt_pk_bf16_f32 v17, v18, v19
	v_lshlrev_b32_e32 v12, 16, v13
	v_and_b32_e32 v13, 0xffff0000, v13
	v_pk_mul_f32 v[12:13], v[16:17], v[12:13] op_sel_hi:[0,1]
	v_cvt_pk_bf16_f32 v18, v12, v13
	v_lshlrev_b32_e32 v12, 16, v14
	v_and_b32_e32 v13, 0xffff0000, v14
	v_pk_mul_f32 v[12:13], v[16:17], v[12:13] op_sel_hi:[0,1]
	v_cvt_pk_bf16_f32 v19, v12, v13
	v_lshlrev_b32_e32 v12, 16, v15
	v_and_b32_e32 v13, 0xffff0000, v15
	v_pk_mul_f32 v[12:13], v[16:17], v[12:13] op_sel_hi:[0,1]
	v_cvt_pk_bf16_f32 v12, v12, v13
	v_perm_b32 v13, v112, v126, s45
	v_perm_b32 v16, v17, v102, s45
	v_perm_b32 v15, v17, v102, s44
	v_perm_b32 v14, v112, v126, s44
	ds_write2_b32 v75, v13, v16 offset0:33 offset1:34
	v_perm_b32 v17, v18, v101, s44
	v_perm_b32 v16, v111, v125, s44
	v_pk_mul_f32 v[30:31], v[2:3], v[30:31]
	v_pk_mul_f32 v[82:83], v[82:83], v[92:93] op_sel_hi:[1,0]
	ds_write2_b64 v75, v[14:15], v[16:17] offset1:33
	v_perm_b32 v13, v111, v125, s45
	v_perm_b32 v14, v18, v101, s45
	v_pk_mul_f32 v[82:83], v[4:5], v[82:83]
	v_pk_mul_f32 v[84:85], v[6:7], v[84:85] op_sel:[0,1] op_sel_hi:[1,0]
	v_cvt_pk_bf16_f32 v24, v28, v29
	v_cvt_pk_bf16_f32 v25, v30, v31
	ds_write2_b32 v75, v13, v14 offset0:99 offset1:100
	v_perm_b32 v13, v110, v124, s45
	v_perm_b32 v16, v19, v100, s45
	global_store_dwordx2 v[22:23], v[24:25], off
	v_cvt_pk_bf16_f32 v24, v82, v83
	v_cvt_pk_bf16_f32 v25, v84, v85
	v_perm_b32 v15, v19, v100, s44
	v_perm_b32 v14, v110, v124, s44
	ds_write2_b32 v75, v13, v16 offset0:165 offset1:166
	v_perm_b32 v17, v12, v99, s44
	v_perm_b32 v16, v79, v77, s44
	v_perm_b32 v13, v79, v77, s45
	v_perm_b32 v12, v12, v99, s45
	s_mov_b64 s[22:23], 0
	global_store_dwordx2 v[22:23], v[24:25], off offset:64
	ds_write2_b64 v75, v[14:15], v[16:17] offset0:66 offset1:99
	ds_write2_b32 v75, v13, v12 offset0:231 offset1:232
	s_cbranch_vccz .LBB0_453
	s_and_b32 s98, s46, 7
	s_lshl_b32 s98, s98, 5
	s_bfe_u32 s99, s46, 0x50003
	s_or_b32 s99, s99, s98
	s_ashr_i32 s22, s99, 31
	s_ashr_i32 s23, s47, 31
	s_lshr_b32 s22, s22, 27
	s_lshr_b32 s23, s23, 21
	s_add_i32 s22, s99, s22
	s_add_i32 s23, s47, s23
	s_ashr_i32 s22, s22, 5
	s_and_b32 s23, s23, 0xfffff800
	s_sub_i32 s26, s47, s23
	s_ashr_i32 s23, s22, 31
	s_lshl_b64 s[22:23], s[22:23], 21
	s_add_u32 s28, s52, s22
	s_addc_u32 s29, s53, s23
	s_ashr_i32 s27, s26, 31
	s_waitcnt lgkmcnt(0)
	s_barrier
	s_lshl_b64 s[22:23], s[26:27], 1
	ds_read2_b32 v[12:13], v159 offset1:1
	ds_read2_b32 v[14:15], v159 offset0:2 offset1:3
	s_add_u32 s22, s28, s22
	s_addc_u32 s23, s29, s23
	v_mov_b32_e32 v81, v33
	v_lshl_add_u64 v[16:17], s[22:23], 0, v[80:81]
	v_lshl_add_u64 v[18:19], v[16:17], 0, v[56:57]
	s_waitcnt lgkmcnt(0)
	global_store_dwordx4 v[18:19], v[12:15], off
	v_lshl_add_u64 v[18:19], v[16:17], 0, v[58:59]
	s_add_i32 s46, s46, s94
	v_add_u32_e32 v12, 0x2100, v159
	v_add_u32_e32 v14, 0x2108, v159
	ds_read2_b32 v[12:13], v12 offset1:1
	ds_read2_b32 v[14:15], v14 offset1:1
	s_cmpk_gt_i32 s46, 0xff
	s_waitcnt lgkmcnt(0)
	global_store_dwordx4 v[18:19], v[12:15], off
	s_nop 1
	v_add_u32_e32 v12, 0x4200, v159
	v_add_u32_e32 v14, 0x4208, v159
	ds_read2_b32 v[12:13], v12 offset1:1
	ds_read2_b32 v[14:15], v14 offset1:1
	v_lshl_add_u64 v[18:19], v[16:17], 0, v[60:61]
	s_waitcnt lgkmcnt(0)
	global_store_dwordx4 v[18:19], v[12:15], off
	s_nop 1
	v_add_u32_e32 v12, 0x6300, v159
	v_add_u32_e32 v14, 0x6308, v159
	ds_read2_b32 v[12:13], v12 offset1:1
	ds_read2_b32 v[14:15], v14 offset1:1
	v_lshl_add_u64 v[18:19], v[16:17], 0, v[62:63]
	s_waitcnt lgkmcnt(0)
	global_store_dwordx4 v[18:19], v[12:15], off
	s_nop 1
	v_add_u32_e32 v12, 0x8400, v159
	v_add_u32_e32 v14, 0x8408, v159
	ds_read2_b32 v[12:13], v12 offset1:1
	ds_read2_b32 v[14:15], v14 offset1:1
	v_lshl_add_u64 v[18:19], v[16:17], 0, v[64:65]
	s_waitcnt lgkmcnt(0)
	global_store_dwordx4 v[18:19], v[12:15], off
	s_nop 1
	v_add_u32_e32 v12, 0xa500, v159
	v_add_u32_e32 v14, 0xa508, v159
	ds_read2_b32 v[12:13], v12 offset1:1
	ds_read2_b32 v[14:15], v14 offset1:1
	v_lshl_add_u64 v[18:19], v[16:17], 0, v[66:67]
	s_waitcnt lgkmcnt(0)
	global_store_dwordx4 v[18:19], v[12:15], off
	s_nop 1
	v_add_u32_e32 v12, 0xc600, v159
	v_add_u32_e32 v14, 0xc608, v159
	ds_read2_b32 v[12:13], v12 offset1:1
	ds_read2_b32 v[14:15], v14 offset1:1
	v_lshl_add_u64 v[18:19], v[16:17], 0, v[68:69]
	v_lshl_add_u64 v[16:17], v[16:17], 0, v[70:71]
	s_waitcnt lgkmcnt(0)
	global_store_dwordx4 v[18:19], v[12:15], off
	s_nop 1
	v_add_u32_e32 v12, 0xe700, v159
	v_add_u32_e32 v14, 0xe708, v159
	ds_read2_b32 v[12:13], v12 offset1:1
	ds_read2_b32 v[14:15], v14 offset1:1
	s_waitcnt lgkmcnt(0)
	global_store_dwordx4 v[16:17], v[12:15], off
	s_cbranch_scc0 .LBB0_452

; #define LAS __attribute__((address_space(3)))
; #define MFMA32(a, b, c) __builtin_amdgcn_mfma_f32_32x32x16_bf16((a), (b), (c), 0, 0, 0)
; __device__ __forceinline__ void ssd_chunk_states(const Args& a, LAS unsigned char* lds) {
;     ...
;     for (int item = blockIdx.x; item < NB * 8 * 8; item += gridDim.x) {
;         const int qb = item & 7, head = (item >> 3) & 7, b = item >> 6, g = head >> 2;
;         const int L0 = qb * 256;
;         const bf16* Ab = Bt + (size_t)(b * 2 + g) * 128 * S_ + L0;
;         const bf16* Xb = Xt + (size_t)(b * 8 + head) * 64 * S_ + L0;
;         u32x4 st[12];
; #pragma unroll
;         for (int i = 0; i < 8; ++i) st[i] = *(const u32x4*)(Ab + (size_t)(16 * i + crow) * S_ + 8 * cc);
; #pragma unroll
;         for (int i = 0; i < 4; ++i) st[8 + i] = *(const u32x4*)(Xb + (size_t)(16 * i + crow) * S_ + 8 * cc);
;         const float wv = vec[(6 + (tid >> 8)) * VS + ((size_t)b * 8 + head) * S_ + L0 + (tid & 255)];
;         __syncthreads();
; #pragma unroll
;         for (int i = 0; i < 8; ++i) *(LAS u32x4*)(lds + (16 * i + crow) * ROWB + 16 * cc) = st[i];
; #pragma unroll
;         for (int i = 0; i < 4; ++i) *(LAS u32x4*)(lds + XOFF + (16 * i + crow) * ROWB + 16 * cc) = st[8 + i];
;         wl[tid] = wv;
;         __syncthreads();
;         f32x16 accf, accb;
; #pragma unroll
;         for (int i = 0; i < 16; ++i) { accf[i] = 0.f; accb[i] = 0.f; }
;         const LAS unsigned char* ap = lds + (32 * nblk + r) * ROWB + 16 * hh;
;         const LAS unsigned char* xp = lds + XOFF + (32 * pblk + r) * ROWB + 16 * hh;
; #pragma unroll
;         for (int u = 0; u < 16; ++u) {
;             const bf16x8 A = *(const LAS bf16x8*)(ap + 32 * u), X = *(const LAS bf16x8*)(xp + 32 * u);
;             const f32x4 F0 = *(const LAS f32x4*)(wl + 16 * u + 8 * hh), F1 = *(const LAS f32x4*)(wl + 16 * u + 8 * hh + 4);
;             const f32x4 G0 = *(const LAS f32x4*)(wl + 256 + 16 * u + 8 * hh), G1 = *(const LAS f32x4*)(wl + 256 + 16 * u + 8 * hh + 4);
;             accf = MFMA32(A, scale8(X, F0, F1), accf); accb = MFMA32(A, scale8(X, G0, G1), accb);
.LBB0_457:
	s_and_b32 s98, s22, 7
	s_lshl_b32 s98, s98, 6
	s_bfe_u32 s99, s22, 0x50003
	s_or_b32 s98, s98, s99
	s_bfe_u32 s99, s22, 0x10008
	s_lshl_b32 s99, s99, 5
	s_or_b32 s99, s99, s98
	s_lshr_b32 s10, s99, 3
	s_ashr_i32 s24, s99, 6
	s_bfe_u32 s10, s10, 0x10002
	s_lshl_b32 s20, s24, 1
	s_or_b32 s20, s10, s20
	s_ashr_i32 s21, s20, 31
	s_and_b32 s23, s99, 7
	s_bfe_u32 s28, s99, 0x30003
	s_lshl_b64 s[20:21], s[20:21], 19
	s_add_u32 s10, s41, s20
	s_addc_u32 s20, s54, s21
	s_lshl_b32 s25, s23, 9
	s_add_u32 s26, s10, s25
	s_addc_u32 s27, s20, 0
	s_lshl_b32 s10, s24, 3
	v_lshl_add_u64 v[28:29], s[26:27], 0, v[32:33]
	s_or_b32 s20, s10, s28
	v_lshl_add_u64 v[0:1], v[28:29], 0, v[40:41]
	s_ashr_i32 s21, s20, 31
	global_load_dwordx4 v[0:3], v[0:1], off
	v_lshl_add_u64 v[4:5], v[28:29], 0, v[42:43]
	s_lshl_b64 s[20:21], s[20:21], 18
	global_load_dwordx4 v[4:7], v[4:5], off
	v_lshl_add_u64 v[8:9], v[28:29], 0, v[44:45]
	s_add_u32 s10, s4, s20
	global_load_dwordx4 v[8:11], v[8:9], off
	v_lshl_add_u64 v[12:13], v[28:29], 0, v[46:47]
	s_addc_u32 s29, s5, s21
	global_load_dwordx4 v[12:15], v[12:13], off
	v_lshl_add_u64 v[16:17], v[28:29], 0, v[48:49]
	global_load_dwordx4 v[16:19], v[16:17], off
	v_lshl_add_u64 v[20:21], v[28:29], 0, v[50:51]
	s_add_u32 s26, s10, s25
	global_load_dwordx4 v[20:23], v[20:21], off
	v_lshl_add_u64 v[24:25], v[28:29], 0, v[52:53]
	s_addc_u32 s27, s29, 0
	global_load_dwordx4 v[24:27], v[24:25], off
	v_lshl_add_u64 v[28:29], v[28:29], 0, v[54:55]
	v_lshl_add_u64 v[58:59], s[26:27], 0, v[32:33]
	s_ashr_i32 s25, s24, 31
	global_load_dwordx4 v[28:31], v[28:29], off
	v_lshl_add_u64 v[68:69], v[58:59], 0, v[40:41]
	v_lshl_add_u64 v[72:73], v[58:59], 0, v[42:43]
	v_lshl_add_u64 v[76:77], v[58:59], 0, v[44:45]
	v_lshl_add_u64 v[58:59], v[58:59], 0, v[46:47]
	s_lshl_b64 s[24:25], s[24:25], 16
	global_load_dwordx4 v[68:71], v[68:69], off
	s_lshl_b32 s10, s28, 13
	global_load_dwordx4 v[80:83], v[58:59], off
	v_lshl_add_u64 v[58:59], v[34:35], 0, s[24:25]
	global_load_dwordx4 v[72:75], v[72:73], off
	v_lshl_add_u64 v[58:59], v[58:59], 0, s[10:11]
	global_load_dwordx4 v[76:79], v[76:77], off
	v_lshl_add_u64 v[58:59], v[58:59], 0, v[56:57]
	s_lshl_b32 s10, s23, 10
	v_lshl_add_u64 v[58:59], v[58:59], 0, s[10:11]
	global_load_dword v58, v[58:59], off
	s_barrier
	s_lshl_b32 s10, s23, 6
	s_add_i32 s22, s22, s94
	s_cmpk_lt_i32 s22, 0x200
	s_waitcnt vmcnt(12)
	ds_write_b128 v63, v[0:3]
	s_waitcnt vmcnt(11)
	ds_write_b128 v63, v[4:7] offset:8448
	s_waitcnt vmcnt(10)
	ds_write_b128 v63, v[8:11] offset:16896
	s_waitcnt vmcnt(9)
	ds_write_b128 v63, v[12:15] offset:25344
	s_waitcnt vmcnt(8)
	ds_write_b128 v63, v[16:19] offset:33792
	s_waitcnt vmcnt(7)
	ds_write_b128 v63, v[20:23] offset:42240
	s_waitcnt vmcnt(6)
	ds_write_b128 v63, v[24:27] offset:50688
	s_waitcnt vmcnt(5)
	ds_write_b128 v63, v[28:31] offset:59136
	s_waitcnt vmcnt(4)
	ds_write_b128 v64, v[68:71]
	s_waitcnt vmcnt(2)
	ds_write_b128 v64, v[72:75] offset:8448
	s_waitcnt vmcnt(1)
	ds_write_b128 v64, v[76:79] offset:16896
	ds_write_b128 v64, v[80:83] offset:25344
	s_waitcnt vmcnt(0)
	ds_write_b32 v60, v58
	s_waitcnt lgkmcnt(0)
	s_barrier
	ds_read_b128 v[0:3], v66
	ds_read_b128 v[68:71], v66 offset:32
	ds_read_b128 v[4:7], v61
	ds_read_b128 v[8:11], v61 offset:16
	ds_read_b128 v[12:15], v62
	ds_read_b128 v[16:19], v62 offset:16
	s_waitcnt lgkmcnt(5)
	v_lshlrev_b32_e32 v20, 16, v0
	v_and_b32_e32 v21, 0xffff0000, v0
	s_waitcnt lgkmcnt(3)
	v_pk_mul_f32 v[4:5], v[4:5], v[20:21]
	ds_read_b128 v[24:27], v65
	ds_read_b128 v[72:75], v65 offset:32
	v_cvt_pk_bf16_f32 v0, v4, v5
	s_waitcnt lgkmcnt(3)
	v_pk_mul_f32 v[4:5], v[12:13], v[20:21]
	ds_read_b128 v[76:79], v61 offset:64
	ds_read_b128 v[80:83], v61 offset:80
	ds_read_b128 v[84:87], v62 offset:64
	ds_read_b128 v[88:91], v62 offset:80
	v_cvt_pk_bf16_f32 v20, v4, v5
	v_lshlrev_b32_e32 v4, 16, v1
	v_and_b32_e32 v5, 0xffff0000, v1
	v_pk_mul_f32 v[6:7], v[6:7], v[4:5]
	v_pk_mul_f32 v[4:5], v[14:15], v[4:5]
	v_cvt_pk_bf16_f32 v1, v6, v7
	v_cvt_pk_bf16_f32 v21, v4, v5
	v_lshlrev_b32_e32 v4, 16, v2
	v_and_b32_e32 v5, 0xffff0000, v2
	v_pk_mul_f32 v[6:7], v[8:9], v[4:5]
	s_waitcnt lgkmcnt(6)
	v_pk_mul_f32 v[4:5], v[16:17], v[4:5]
	v_lshlrev_b32_e32 v16, 16, v3
	v_and_b32_e32 v17, 0xffff0000, v3
	v_cvt_pk_bf16_f32 v22, v4, v5
	v_pk_mul_f32 v[4:5], v[10:11], v[16:17]
	v_pk_mul_f32 v[16:17], v[18:19], v[16:17]
	v_cvt_pk_bf16_f32 v2, v6, v7
	v_cvt_pk_bf16_f32 v3, v4, v5
	v_cvt_pk_bf16_f32 v23, v16, v17
	v_lshlrev_b32_e32 v58, 16, v68
	v_and_b32_e32 v59, 0xffff0000, v68
	s_waitcnt lgkmcnt(5)
	v_mfma_f32_32x32x16_bf16 v[0:15], v[24:27], v[0:3], 0
	s_waitcnt lgkmcnt(3)
	v_mul_f32_e64 v76, v76, v58
	v_mul_f32_e64 v77, v77, v59
	s_waitcnt lgkmcnt(1)
	v_mul_f32_e64 v58, v84, v58
	v_mul_f32_e64 v59, v85, v59
	v_cvt_pk_bf16_f32 v68, v76, v77
	v_cvt_pk_bf16_f32 v76, v58, v59
	v_lshlrev_b32_e32 v58, 16, v69
	v_and_b32_e32 v59, 0xffff0000, v69
	v_pk_mul_f32 v[78:79], v[78:79], v[58:59]
	v_mfma_f32_32x32x16_bf16 v[16:31], v[24:27], v[20:23], 0
	v_mul_f32_e64 v58, v86, v58
	v_mul_f32_e64 v59, v87, v59
	v_cvt_pk_bf16_f32 v69, v78, v79
	v_cvt_pk_bf16_f32 v77, v58, v59
	v_lshlrev_b32_e32 v58, 16, v70
	v_and_b32_e32 v59, 0xffff0000, v70
	v_pk_mul_f32 v[78:79], v[80:81], v[58:59]
	s_waitcnt lgkmcnt(0)
	v_pk_mul_f32 v[58:59], v[88:89], v[58:59]
	v_cvt_pk_bf16_f32 v70, v78, v79
	v_cvt_pk_bf16_f32 v78, v58, v59
	v_lshlrev_b32_e32 v58, 16, v71
	v_and_b32_e32 v59, 0xffff0000, v71
	v_pk_mul_f32 v[80:81], v[82:83], v[58:59]
	v_pk_mul_f32 v[58:59], v[90:91], v[58:59]
	v_cvt_pk_bf16_f32 v71, v80, v81
	v_cvt_pk_bf16_f32 v79, v58, v59
	s_nop 0
	v_mfma_f32_32x32x16_bf16 v[0:15], v[72:75], v[68:71], v[0:15]
	v_mfma_f32_32x32x16_bf16 v[16:31], v[72:75], v[76:79], v[16:31]
	ds_read_b128 v[68:71], v65 offset:64
	ds_read_b128 v[72:75], v66 offset:64
	ds_read_b128 v[76:79], v61 offset:128
	ds_read_b128 v[80:83], v61 offset:144
	ds_read_b128 v[84:87], v62 offset:128
	ds_read_b128 v[88:91], v62 offset:144
	s_waitcnt lgkmcnt(4)
; #define LAS __attribute__((address_space(3)))
; #define MFMA32(a, b, c) __builtin_amdgcn_mfma_f32_32x32x16_bf16((a), (b), (c), 0, 0, 0)
; __device__ __forceinline__ unsigned pk2(float lo, float hi) { f32x2 v = {lo, hi}; bf16x2_t b = __builtin_convertvector(v, bf16x2_t); return __builtin_bit_cast(unsigned, b); }
; __device__ __forceinline__ short __attribute__((ext_vector_type(8))) scale8(const short __attribute__((ext_vector_type(8))) x, const f32x4 w0, const f32x4 w1) {
;     const u32x4 v = __builtin_bit_cast(u32x4, x); u32x4 o;
;     o.x = pk2(bflo(v.x) * w0.x, bfhi(v.x) * w0.y); o.y = pk2(bflo(v.y) * w0.z, bfhi(v.y) * w0.w); o.z = pk2(bflo(v.z) * w1.x, bfhi(v.z) * w1.y); o.w = pk2(bflo(v.w) * w1.z, bfhi(v.w) * w1.w);
;     return __builtin_bit_cast(short __attribute__((ext_vector_type(8))), o);
; __device__ __forceinline__ void ssd_chunk_states(const Args& a, LAS unsigned char* lds) {
;     ...
; #pragma unroll
;         for (int u = 0; u < 16; ++u) {
;             const bf16x8 A = *(const LAS bf16x8*)(ap + 32 * u), X = *(const LAS bf16x8*)(xp + 32 * u);
;             const f32x4 F0 = *(const LAS f32x4*)(wl + 16 * u + 8 * hh), F1 = *(const LAS f32x4*)(wl + 16 * u + 8 * hh + 4);
;             const f32x4 G0 = *(const LAS f32x4*)(wl + 256 + 16 * u + 8 * hh), G1 = *(const LAS f32x4*)(wl + 256 + 16 * u + 8 * hh + 4);
;             accf = MFMA32(A, scale8(X, F0, F1), accf); accb = MFMA32(A, scale8(X, G0, G1), accb);
	v_lshlrev_b32_e32 v58, 16, v72
	v_and_b32_e32 v59, 0xffff0000, v72
	s_waitcnt lgkmcnt(3)
	v_pk_mul_f32 v[76:77], v[76:77], v[58:59]
	s_waitcnt lgkmcnt(1)
	v_pk_mul_f32 v[58:59], v[84:85], v[58:59]
	v_cvt_pk_bf16_f32 v72, v76, v77
	v_cvt_pk_bf16_f32 v76, v58, v59
	v_lshlrev_b32_e32 v58, 16, v73
	v_and_b32_e32 v59, 0xffff0000, v73
	v_pk_mul_f32 v[78:79], v[78:79], v[58:59]
	v_pk_mul_f32 v[58:59], v[86:87], v[58:59]
	v_cvt_pk_bf16_f32 v73, v78, v79
	v_cvt_pk_bf16_f32 v77, v58, v59
	v_lshlrev_b32_e32 v58, 16, v74
	v_and_b32_e32 v59, 0xffff0000, v74
	v_pk_mul_f32 v[78:79], v[80:81], v[58:59]
	s_waitcnt lgkmcnt(0)
	v_pk_mul_f32 v[58:59], v[88:89], v[58:59]
	v_cvt_pk_bf16_f32 v74, v78, v79
	v_cvt_pk_bf16_f32 v78, v58, v59
	v_lshlrev_b32_e32 v58, 16, v75
	v_and_b32_e32 v59, 0xffff0000, v75
	v_pk_mul_f32 v[80:81], v[82:83], v[58:59]
	v_pk_mul_f32 v[58:59], v[90:91], v[58:59]
	v_cvt_pk_bf16_f32 v75, v80, v81
	v_cvt_pk_bf16_f32 v79, v58, v59
	s_nop 0
	v_mfma_f32_32x32x16_bf16 v[0:15], v[68:71], v[72:75], v[0:15]
	v_mfma_f32_32x32x16_bf16 v[16:31], v[68:71], v[76:79], v[16:31]
	ds_read_b128 v[68:71], v65 offset:96
	ds_read_b128 v[72:75], v66 offset:96
	ds_read_b128 v[76:79], v61 offset:192
	ds_read_b128 v[80:83], v61 offset:208
	ds_read_b128 v[84:87], v62 offset:192
	ds_read_b128 v[88:91], v62 offset:208
	s_waitcnt lgkmcnt(4)
	v_lshlrev_b32_e32 v58, 16, v72
	v_and_b32_e32 v59, 0xffff0000, v72
	s_waitcnt lgkmcnt(3)
	v_pk_mul_f32 v[76:77], v[76:77], v[58:59]
	s_waitcnt lgkmcnt(1)
	v_pk_mul_f32 v[58:59], v[84:85], v[58:59]
	v_cvt_pk_bf16_f32 v72, v76, v77
	v_cvt_pk_bf16_f32 v76, v58, v59
	v_lshlrev_b32_e32 v58, 16, v73
	v_and_b32_e32 v59, 0xffff0000, v73
	v_pk_mul_f32 v[78:79], v[78:79], v[58:59]
	v_pk_mul_f32 v[58:59], v[86:87], v[58:59]
	v_cvt_pk_bf16_f32 v73, v78, v79
	v_cvt_pk_bf16_f32 v77, v58, v59
	v_lshlrev_b32_e32 v58, 16, v74
	v_and_b32_e32 v59, 0xffff0000, v74
	v_pk_mul_f32 v[78:79], v[80:81], v[58:59]
	s_waitcnt lgkmcnt(0)
	v_pk_mul_f32 v[58:59], v[88:89], v[58:59]
	v_cvt_pk_bf16_f32 v74, v78, v79
	v_cvt_pk_bf16_f32 v78, v58, v59
	v_lshlrev_b32_e32 v58, 16, v75
	v_and_b32_e32 v59, 0xffff0000, v75
	v_pk_mul_f32 v[80:81], v[82:83], v[58:59]
	v_pk_mul_f32 v[58:59], v[90:91], v[58:59]
	v_cvt_pk_bf16_f32 v75, v80, v81
	v_cvt_pk_bf16_f32 v79, v58, v59
	s_nop 0
	v_mfma_f32_32x32x16_bf16 v[0:15], v[68:71], v[72:75], v[0:15]
	v_mfma_f32_32x32x16_bf16 v[16:31], v[68:71], v[76:79], v[16:31]
	ds_read_b128 v[68:71], v65 offset:128
	ds_read_b128 v[72:75], v66 offset:128
	ds_read_b128 v[76:79], v61 offset:256
	ds_read_b128 v[80:83], v61 offset:272
	ds_read_b128 v[84:87], v62 offset:256
	ds_read_b128 v[88:91], v62 offset:272
	s_waitcnt lgkmcnt(4)
	v_lshlrev_b32_e32 v58, 16, v72
	v_and_b32_e32 v59, 0xffff0000, v72
	s_waitcnt lgkmcnt(3)
	v_pk_mul_f32 v[76:77], v[76:77], v[58:59]
	s_waitcnt lgkmcnt(1)
	v_pk_mul_f32 v[58:59], v[84:85], v[58:59]
	v_cvt_pk_bf16_f32 v72, v76, v77
	v_cvt_pk_bf16_f32 v76, v58, v59
	v_lshlrev_b32_e32 v58, 16, v73
	v_and_b32_e32 v59, 0xffff0000, v73
	v_pk_mul_f32 v[78:79], v[78:79], v[58:59]
	v_pk_mul_f32 v[58:59], v[86:87], v[58:59]
	v_cvt_pk_bf16_f32 v73, v78, v79
	v_cvt_pk_bf16_f32 v77, v58, v59
	v_lshlrev_b32_e32 v58, 16, v74
	v_and_b32_e32 v59, 0xffff0000, v74
	v_pk_mul_f32 v[78:79], v[80:81], v[58:59]
	s_waitcnt lgkmcnt(0)
	v_pk_mul_f32 v[58:59], v[88:89], v[58:59]
	v_cvt_pk_bf16_f32 v74, v78, v79
	v_cvt_pk_bf16_f32 v78, v58, v59
	v_lshlrev_b32_e32 v58, 16, v75
	v_and_b32_e32 v59, 0xffff0000, v75
	v_pk_mul_f32 v[80:81], v[82:83], v[58:59]
	v_pk_mul_f32 v[58:59], v[90:91], v[58:59]
	v_cvt_pk_bf16_f32 v75, v80, v81
	v_cvt_pk_bf16_f32 v79, v58, v59
	s_nop 0
	v_mfma_f32_32x32x16_bf16 v[0:15], v[68:71], v[72:75], v[0:15]
	v_mfma_f32_32x32x16_bf16 v[16:31], v[68:71], v[76:79], v[16:31]
	ds_read_b128 v[68:71], v65 offset:160
	ds_read_b128 v[72:75], v66 offset:160
	ds_read_b128 v[76:79], v61 offset:320
	ds_read_b128 v[80:83], v61 offset:336
	ds_read_b128 v[84:87], v62 offset:320
	ds_read_b128 v[88:91], v62 offset:336
	s_waitcnt lgkmcnt(4)
	v_lshlrev_b32_e32 v58, 16, v72
	v_and_b32_e32 v59, 0xffff0000, v72
	s_waitcnt lgkmcnt(3)
	v_pk_mul_f32 v[76:77], v[76:77], v[58:59]
	s_waitcnt lgkmcnt(1)
	v_pk_mul_f32 v[58:59], v[84:85], v[58:59]
	v_cvt_pk_bf16_f32 v72, v76, v77
	v_cvt_pk_bf16_f32 v76, v58, v59
	v_lshlrev_b32_e32 v58, 16, v73
	v_and_b32_e32 v59, 0xffff0000, v73
	v_pk_mul_f32 v[78:79], v[78:79], v[58:59]
	v_pk_mul_f32 v[58:59], v[86:87], v[58:59]
	v_cvt_pk_bf16_f32 v73, v78, v79
	v_cvt_pk_bf16_f32 v77, v58, v59
	v_lshlrev_b32_e32 v58, 16, v74
	v_and_b32_e32 v59, 0xffff0000, v74
	v_pk_mul_f32 v[78:79], v[80:81], v[58:59]
	s_waitcnt lgkmcnt(0)
	v_pk_mul_f32 v[58:59], v[88:89], v[58:59]
	v_cvt_pk_bf16_f32 v74, v78, v79
	v_cvt_pk_bf16_f32 v78, v58, v59
	v_lshlrev_b32_e32 v58, 16, v75
	v_and_b32_e32 v59, 0xffff0000, v75
	v_pk_mul_f32 v[80:81], v[82:83], v[58:59]
	v_pk_mul_f32 v[58:59], v[90:91], v[58:59]
	v_cvt_pk_bf16_f32 v75, v80, v81
	v_cvt_pk_bf16_f32 v79, v58, v59
	s_nop 0
	v_mfma_f32_32x32x16_bf16 v[0:15], v[68:71], v[72:75], v[0:15]
	v_mfma_f32_32x32x16_bf16 v[16:31], v[68:71], v[76:79], v[16:31]
	ds_read_b128 v[68:71], v65 offset:192
	ds_read_b128 v[72:75], v66 offset:192
	ds_read_b128 v[76:79], v61 offset:384
	ds_read_b128 v[80:83], v61 offset:400
	ds_read_b128 v[84:87], v62 offset:384
	ds_read_b128 v[88:91], v62 offset:400
	s_waitcnt lgkmcnt(4)
	v_lshlrev_b32_e32 v58, 16, v72
	v_and_b32_e32 v59, 0xffff0000, v72
	s_waitcnt lgkmcnt(3)
	v_pk_mul_f32 v[76:77], v[76:77], v[58:59]
	s_waitcnt lgkmcnt(1)
; #define LAS __attribute__((address_space(3)))
; #define MFMA32(a, b, c) __builtin_amdgcn_mfma_f32_32x32x16_bf16((a), (b), (c), 0, 0, 0)
; __device__ __forceinline__ unsigned pk2(float lo, float hi) { f32x2 v = {lo, hi}; bf16x2_t b = __builtin_convertvector(v, bf16x2_t); return __builtin_bit_cast(unsigned, b); }
; __device__ __forceinline__ short __attribute__((ext_vector_type(8))) scale8(const short __attribute__((ext_vector_type(8))) x, const f32x4 w0, const f32x4 w1) {
;     const u32x4 v = __builtin_bit_cast(u32x4, x); u32x4 o;
;     o.x = pk2(bflo(v.x) * w0.x, bfhi(v.x) * w0.y); o.y = pk2(bflo(v.y) * w0.z, bfhi(v.y) * w0.w); o.z = pk2(bflo(v.z) * w1.x, bfhi(v.z) * w1.y); o.w = pk2(bflo(v.w) * w1.z, bfhi(v.w) * w1.w);
;     return __builtin_bit_cast(short __attribute__((ext_vector_type(8))), o);
; __device__ __forceinline__ void ssd_chunk_states(const Args& a, LAS unsigned char* lds) {
;     ...
; #pragma unroll
;         for (int u = 0; u < 16; ++u) {
;             const bf16x8 A = *(const LAS bf16x8*)(ap + 32 * u), X = *(const LAS bf16x8*)(xp + 32 * u);
;             const f32x4 F0 = *(const LAS f32x4*)(wl + 16 * u + 8 * hh), F1 = *(const LAS f32x4*)(wl + 16 * u + 8 * hh + 4);
;             const f32x4 G0 = *(const LAS f32x4*)(wl + 256 + 16 * u + 8 * hh), G1 = *(const LAS f32x4*)(wl + 256 + 16 * u + 8 * hh + 4);
;             accf = MFMA32(A, scale8(X, F0, F1), accf); accb = MFMA32(A, scale8(X, G0, G1), accb);
	v_pk_mul_f32 v[58:59], v[84:85], v[58:59]
	v_cvt_pk_bf16_f32 v72, v76, v77
	v_cvt_pk_bf16_f32 v76, v58, v59
	v_lshlrev_b32_e32 v58, 16, v73
	v_and_b32_e32 v59, 0xffff0000, v73
	v_pk_mul_f32 v[78:79], v[78:79], v[58:59]
	v_pk_mul_f32 v[58:59], v[86:87], v[58:59]
	v_cvt_pk_bf16_f32 v73, v78, v79
	v_cvt_pk_bf16_f32 v77, v58, v59
	v_lshlrev_b32_e32 v58, 16, v74
	v_and_b32_e32 v59, 0xffff0000, v74
	v_pk_mul_f32 v[78:79], v[80:81], v[58:59]
	s_waitcnt lgkmcnt(0)
	v_pk_mul_f32 v[58:59], v[88:89], v[58:59]
	v_cvt_pk_bf16_f32 v74, v78, v79
	v_cvt_pk_bf16_f32 v78, v58, v59
	v_lshlrev_b32_e32 v58, 16, v75
	v_and_b32_e32 v59, 0xffff0000, v75
	v_pk_mul_f32 v[80:81], v[82:83], v[58:59]
	v_pk_mul_f32 v[58:59], v[90:91], v[58:59]
	v_cvt_pk_bf16_f32 v75, v80, v81
	v_cvt_pk_bf16_f32 v79, v58, v59
	s_nop 0
	v_mfma_f32_32x32x16_bf16 v[0:15], v[68:71], v[72:75], v[0:15]
	v_mfma_f32_32x32x16_bf16 v[16:31], v[68:71], v[76:79], v[16:31]
	ds_read_b128 v[68:71], v65 offset:224
	ds_read_b128 v[72:75], v66 offset:224
	ds_read_b128 v[76:79], v61 offset:448
	ds_read_b128 v[80:83], v61 offset:464
	ds_read_b128 v[84:87], v62 offset:448
	ds_read_b128 v[88:91], v62 offset:464
	s_waitcnt lgkmcnt(4)
	v_lshlrev_b32_e32 v58, 16, v72
	v_and_b32_e32 v59, 0xffff0000, v72
	s_waitcnt lgkmcnt(3)
	v_pk_mul_f32 v[76:77], v[76:77], v[58:59]
	s_waitcnt lgkmcnt(1)
	v_pk_mul_f32 v[58:59], v[84:85], v[58:59]
	v_cvt_pk_bf16_f32 v72, v76, v77
	v_cvt_pk_bf16_f32 v76, v58, v59
	v_lshlrev_b32_e32 v58, 16, v73
	v_and_b32_e32 v59, 0xffff0000, v73
	v_pk_mul_f32 v[78:79], v[78:79], v[58:59]
	v_pk_mul_f32 v[58:59], v[86:87], v[58:59]
	v_cvt_pk_bf16_f32 v73, v78, v79
	v_cvt_pk_bf16_f32 v77, v58, v59
	v_lshlrev_b32_e32 v58, 16, v74
	v_and_b32_e32 v59, 0xffff0000, v74
	v_pk_mul_f32 v[78:79], v[80:81], v[58:59]
	s_waitcnt lgkmcnt(0)
	v_pk_mul_f32 v[58:59], v[88:89], v[58:59]
	v_cvt_pk_bf16_f32 v74, v78, v79
	v_cvt_pk_bf16_f32 v78, v58, v59
	v_lshlrev_b32_e32 v58, 16, v75
	v_and_b32_e32 v59, 0xffff0000, v75
	v_pk_mul_f32 v[80:81], v[82:83], v[58:59]
	v_pk_mul_f32 v[58:59], v[90:91], v[58:59]
	v_cvt_pk_bf16_f32 v75, v80, v81
	v_cvt_pk_bf16_f32 v79, v58, v59
	s_nop 0
	v_mfma_f32_32x32x16_bf16 v[0:15], v[68:71], v[72:75], v[0:15]
	v_mfma_f32_32x32x16_bf16 v[16:31], v[68:71], v[76:79], v[16:31]
	ds_read_b128 v[68:71], v65 offset:256
	ds_read_b128 v[72:75], v66 offset:256
	ds_read_b128 v[76:79], v61 offset:512
	ds_read_b128 v[80:83], v61 offset:528
	ds_read_b128 v[84:87], v62 offset:512
	ds_read_b128 v[88:91], v62 offset:528
	s_waitcnt lgkmcnt(4)
	v_lshlrev_b32_e32 v58, 16, v72
	v_and_b32_e32 v59, 0xffff0000, v72
	s_waitcnt lgkmcnt(3)
	v_pk_mul_f32 v[76:77], v[76:77], v[58:59]
	s_waitcnt lgkmcnt(1)
	v_pk_mul_f32 v[58:59], v[84:85], v[58:59]
	v_cvt_pk_bf16_f32 v72, v76, v77
	v_cvt_pk_bf16_f32 v76, v58, v59
	v_lshlrev_b32_e32 v58, 16, v73
	v_and_b32_e32 v59, 0xffff0000, v73
	v_pk_mul_f32 v[78:79], v[78:79], v[58:59]
	v_pk_mul_f32 v[58:59], v[86:87], v[58:59]
	v_cvt_pk_bf16_f32 v73, v78, v79
	v_cvt_pk_bf16_f32 v77, v58, v59
	v_lshlrev_b32_e32 v58, 16, v74
	v_and_b32_e32 v59, 0xffff0000, v74
	v_pk_mul_f32 v[78:79], v[80:81], v[58:59]
	s_waitcnt lgkmcnt(0)
	v_pk_mul_f32 v[58:59], v[88:89], v[58:59]
	v_cvt_pk_bf16_f32 v74, v78, v79
	v_cvt_pk_bf16_f32 v78, v58, v59
	v_lshlrev_b32_e32 v58, 16, v75
	v_and_b32_e32 v59, 0xffff0000, v75
	v_pk_mul_f32 v[80:81], v[82:83], v[58:59]
	v_pk_mul_f32 v[58:59], v[90:91], v[58:59]
	v_cvt_pk_bf16_f32 v75, v80, v81
	v_cvt_pk_bf16_f32 v79, v58, v59
	s_nop 0
	v_mfma_f32_32x32x16_bf16 v[0:15], v[68:71], v[72:75], v[0:15]
	v_mfma_f32_32x32x16_bf16 v[16:31], v[68:71], v[76:79], v[16:31]
	ds_read_b128 v[68:71], v65 offset:288
	ds_read_b128 v[72:75], v66 offset:288
	ds_read_b128 v[76:79], v61 offset:576
	ds_read_b128 v[80:83], v61 offset:592
	ds_read_b128 v[84:87], v62 offset:576
	ds_read_b128 v[88:91], v62 offset:592
	s_waitcnt lgkmcnt(4)
	v_lshlrev_b32_e32 v58, 16, v72
	v_and_b32_e32 v59, 0xffff0000, v72
	s_waitcnt lgkmcnt(3)
	v_pk_mul_f32 v[76:77], v[76:77], v[58:59]
	s_waitcnt lgkmcnt(1)
	v_pk_mul_f32 v[58:59], v[84:85], v[58:59]
	v_cvt_pk_bf16_f32 v72, v76, v77
	v_cvt_pk_bf16_f32 v76, v58, v59
	v_lshlrev_b32_e32 v58, 16, v73
	v_and_b32_e32 v59, 0xffff0000, v73
	v_pk_mul_f32 v[78:79], v[78:79], v[58:59]
	v_pk_mul_f32 v[58:59], v[86:87], v[58:59]
	v_cvt_pk_bf16_f32 v73, v78, v79
	v_cvt_pk_bf16_f32 v77, v58, v59
	v_lshlrev_b32_e32 v58, 16, v74
	v_and_b32_e32 v59, 0xffff0000, v74
	v_pk_mul_f32 v[78:79], v[80:81], v[58:59]
	s_waitcnt lgkmcnt(0)
	v_pk_mul_f32 v[58:59], v[88:89], v[58:59]
	v_cvt_pk_bf16_f32 v74, v78, v79
	v_cvt_pk_bf16_f32 v78, v58, v59
	v_lshlrev_b32_e32 v58, 16, v75
	v_and_b32_e32 v59, 0xffff0000, v75
	v_pk_mul_f32 v[80:81], v[82:83], v[58:59]
	v_pk_mul_f32 v[58:59], v[90:91], v[58:59]
	v_cvt_pk_bf16_f32 v75, v80, v81
	v_cvt_pk_bf16_f32 v79, v58, v59
	s_nop 0
	v_mfma_f32_32x32x16_bf16 v[0:15], v[68:71], v[72:75], v[0:15]
	v_mfma_f32_32x32x16_bf16 v[16:31], v[68:71], v[76:79], v[16:31]
	ds_read_b128 v[68:71], v65 offset:320
	ds_read_b128 v[72:75], v66 offset:320
	ds_read_b128 v[76:79], v61 offset:640
	ds_read_b128 v[80:83], v61 offset:656
	ds_read_b128 v[84:87], v62 offset:640
	ds_read_b128 v[88:91], v62 offset:656
	s_waitcnt lgkmcnt(4)
	v_lshlrev_b32_e32 v58, 16, v72
	v_and_b32_e32 v59, 0xffff0000, v72
	s_waitcnt lgkmcnt(3)
	v_pk_mul_f32 v[76:77], v[76:77], v[58:59]
	s_waitcnt lgkmcnt(1)
	v_pk_mul_f32 v[58:59], v[84:85], v[58:59]
	v_cvt_pk_bf16_f32 v72, v76, v77
	v_cvt_pk_bf16_f32 v76, v58, v59
	v_lshlrev_b32_e32 v58, 16, v73
	v_and_b32_e32 v59, 0xffff0000, v73
	v_pk_mul_f32 v[78:79], v[78:79], v[58:59]
	v_pk_mul_f32 v[58:59], v[86:87], v[58:59]
	v_cvt_pk_bf16_f32 v73, v78, v79
	v_cvt_pk_bf16_f32 v77, v58, v59
	v_lshlrev_b32_e32 v58, 16, v74
	v_and_b32_e32 v59, 0xffff0000, v74
	v_pk_mul_f32 v[78:79], v[80:81], v[58:59]
	s_waitcnt lgkmcnt(0)
; #define LAS __attribute__((address_space(3)))
; #define MFMA32(a, b, c) __builtin_amdgcn_mfma_f32_32x32x16_bf16((a), (b), (c), 0, 0, 0)
; __device__ __forceinline__ unsigned pk2(float lo, float hi) { f32x2 v = {lo, hi}; bf16x2_t b = __builtin_convertvector(v, bf16x2_t); return __builtin_bit_cast(unsigned, b); }
; __device__ __forceinline__ short __attribute__((ext_vector_type(8))) scale8(const short __attribute__((ext_vector_type(8))) x, const f32x4 w0, const f32x4 w1) {
;     const u32x4 v = __builtin_bit_cast(u32x4, x); u32x4 o;
;     o.x = pk2(bflo(v.x) * w0.x, bfhi(v.x) * w0.y); o.y = pk2(bflo(v.y) * w0.z, bfhi(v.y) * w0.w); o.z = pk2(bflo(v.z) * w1.x, bfhi(v.z) * w1.y); o.w = pk2(bflo(v.w) * w1.z, bfhi(v.w) * w1.w);
;     return __builtin_bit_cast(short __attribute__((ext_vector_type(8))), o);
; __device__ __forceinline__ void ssd_chunk_states(const Args& a, LAS unsigned char* lds) {
;     ...
; #pragma unroll
;         for (int u = 0; u < 16; ++u) {
;             const bf16x8 A = *(const LAS bf16x8*)(ap + 32 * u), X = *(const LAS bf16x8*)(xp + 32 * u);
;             const f32x4 F0 = *(const LAS f32x4*)(wl + 16 * u + 8 * hh), F1 = *(const LAS f32x4*)(wl + 16 * u + 8 * hh + 4);
;             const f32x4 G0 = *(const LAS f32x4*)(wl + 256 + 16 * u + 8 * hh), G1 = *(const LAS f32x4*)(wl + 256 + 16 * u + 8 * hh + 4);
;             accf = MFMA32(A, scale8(X, F0, F1), accf); accb = MFMA32(A, scale8(X, G0, G1), accb);
	v_pk_mul_f32 v[58:59], v[88:89], v[58:59]
	v_cvt_pk_bf16_f32 v74, v78, v79
	v_cvt_pk_bf16_f32 v78, v58, v59
	v_lshlrev_b32_e32 v58, 16, v75
	v_and_b32_e32 v59, 0xffff0000, v75
	v_pk_mul_f32 v[80:81], v[82:83], v[58:59]
	v_pk_mul_f32 v[58:59], v[90:91], v[58:59]
	v_cvt_pk_bf16_f32 v75, v80, v81
	v_cvt_pk_bf16_f32 v79, v58, v59
	s_nop 0
	v_mfma_f32_32x32x16_bf16 v[0:15], v[68:71], v[72:75], v[0:15]
	v_mfma_f32_32x32x16_bf16 v[16:31], v[68:71], v[76:79], v[16:31]
	ds_read_b128 v[68:71], v65 offset:352
	ds_read_b128 v[72:75], v66 offset:352
	ds_read_b128 v[76:79], v61 offset:704
	ds_read_b128 v[80:83], v61 offset:720
	ds_read_b128 v[84:87], v62 offset:704
	ds_read_b128 v[88:91], v62 offset:720
	s_waitcnt lgkmcnt(4)
	v_lshlrev_b32_e32 v58, 16, v72
	v_and_b32_e32 v59, 0xffff0000, v72
	s_waitcnt lgkmcnt(3)
	v_pk_mul_f32 v[76:77], v[76:77], v[58:59]
	s_waitcnt lgkmcnt(1)
	v_pk_mul_f32 v[58:59], v[84:85], v[58:59]
	v_cvt_pk_bf16_f32 v72, v76, v77
	v_cvt_pk_bf16_f32 v76, v58, v59
	v_lshlrev_b32_e32 v58, 16, v73
	v_and_b32_e32 v59, 0xffff0000, v73
	v_pk_mul_f32 v[78:79], v[78:79], v[58:59]
	v_pk_mul_f32 v[58:59], v[86:87], v[58:59]
	v_cvt_pk_bf16_f32 v73, v78, v79
	v_cvt_pk_bf16_f32 v77, v58, v59
	v_lshlrev_b32_e32 v58, 16, v74
	v_and_b32_e32 v59, 0xffff0000, v74
	v_pk_mul_f32 v[78:79], v[80:81], v[58:59]
	s_waitcnt lgkmcnt(0)
	v_pk_mul_f32 v[58:59], v[88:89], v[58:59]
	v_cvt_pk_bf16_f32 v74, v78, v79
	v_cvt_pk_bf16_f32 v78, v58, v59
	v_lshlrev_b32_e32 v58, 16, v75
	v_and_b32_e32 v59, 0xffff0000, v75
	v_pk_mul_f32 v[80:81], v[82:83], v[58:59]
	v_pk_mul_f32 v[58:59], v[90:91], v[58:59]
	v_cvt_pk_bf16_f32 v75, v80, v81
	v_cvt_pk_bf16_f32 v79, v58, v59
	s_nop 0
	v_mfma_f32_32x32x16_bf16 v[0:15], v[68:71], v[72:75], v[0:15]
	v_mfma_f32_32x32x16_bf16 v[16:31], v[68:71], v[76:79], v[16:31]
	ds_read_b128 v[68:71], v65 offset:384
	ds_read_b128 v[72:75], v66 offset:384
	ds_read_b128 v[76:79], v61 offset:768
	ds_read_b128 v[80:83], v61 offset:784
	ds_read_b128 v[84:87], v62 offset:768
	ds_read_b128 v[88:91], v62 offset:784
	s_waitcnt lgkmcnt(4)
	v_lshlrev_b32_e32 v58, 16, v72
	v_and_b32_e32 v59, 0xffff0000, v72
	s_waitcnt lgkmcnt(3)
	v_pk_mul_f32 v[76:77], v[76:77], v[58:59]
	s_waitcnt lgkmcnt(1)
	v_pk_mul_f32 v[58:59], v[84:85], v[58:59]
	v_cvt_pk_bf16_f32 v72, v76, v77
	v_cvt_pk_bf16_f32 v76, v58, v59
	v_lshlrev_b32_e32 v58, 16, v73
	v_and_b32_e32 v59, 0xffff0000, v73
	v_pk_mul_f32 v[78:79], v[78:79], v[58:59]
	v_pk_mul_f32 v[58:59], v[86:87], v[58:59]
	v_cvt_pk_bf16_f32 v73, v78, v79
	v_cvt_pk_bf16_f32 v77, v58, v59
	v_lshlrev_b32_e32 v58, 16, v74
	v_and_b32_e32 v59, 0xffff0000, v74
	v_pk_mul_f32 v[78:79], v[80:81], v[58:59]
	s_waitcnt lgkmcnt(0)
	v_pk_mul_f32 v[58:59], v[88:89], v[58:59]
	v_cvt_pk_bf16_f32 v74, v78, v79
	v_cvt_pk_bf16_f32 v78, v58, v59
	v_lshlrev_b32_e32 v58, 16, v75
	v_and_b32_e32 v59, 0xffff0000, v75
	v_pk_mul_f32 v[80:81], v[82:83], v[58:59]
	v_pk_mul_f32 v[58:59], v[90:91], v[58:59]
	v_cvt_pk_bf16_f32 v75, v80, v81
	v_cvt_pk_bf16_f32 v79, v58, v59
	s_nop 0
	v_mfma_f32_32x32x16_bf16 v[0:15], v[68:71], v[72:75], v[0:15]
	v_mfma_f32_32x32x16_bf16 v[16:31], v[68:71], v[76:79], v[16:31]
	ds_read_b128 v[68:71], v65 offset:416
	ds_read_b128 v[72:75], v66 offset:416
	ds_read_b128 v[76:79], v61 offset:832
	ds_read_b128 v[80:83], v61 offset:848
	ds_read_b128 v[84:87], v62 offset:832
	ds_read_b128 v[88:91], v62 offset:848
	s_waitcnt lgkmcnt(4)
	v_lshlrev_b32_e32 v58, 16, v72
	v_and_b32_e32 v59, 0xffff0000, v72
	s_waitcnt lgkmcnt(3)
	v_pk_mul_f32 v[76:77], v[76:77], v[58:59]
	s_waitcnt lgkmcnt(1)
	v_pk_mul_f32 v[58:59], v[84:85], v[58:59]
	v_cvt_pk_bf16_f32 v72, v76, v77
	v_cvt_pk_bf16_f32 v76, v58, v59
	v_lshlrev_b32_e32 v58, 16, v73
	v_and_b32_e32 v59, 0xffff0000, v73
	v_pk_mul_f32 v[78:79], v[78:79], v[58:59]
	v_pk_mul_f32 v[58:59], v[86:87], v[58:59]
	v_cvt_pk_bf16_f32 v73, v78, v79
	v_cvt_pk_bf16_f32 v77, v58, v59
	v_lshlrev_b32_e32 v58, 16, v74
	v_and_b32_e32 v59, 0xffff0000, v74
	v_pk_mul_f32 v[78:79], v[80:81], v[58:59]
	s_waitcnt lgkmcnt(0)
; #define LAS __attribute__((address_space(3)))
; #define MFMA32(a, b, c) __builtin_amdgcn_mfma_f32_32x32x16_bf16((a), (b), (c), 0, 0, 0)
; __device__ __forceinline__ unsigned pk2(float lo, float hi) { f32x2 v = {lo, hi}; bf16x2_t b = __builtin_convertvector(v, bf16x2_t); return __builtin_bit_cast(unsigned, b); }
; __device__ __forceinline__ void ssd_chunk_states(const Args& a, LAS unsigned char* lds) {
;     ...
;         for (int u = 0; u < 16; ++u) {
;             const bf16x8 A = *(const LAS bf16x8*)(ap + 32 * u), X = *(const LAS bf16x8*)(xp + 32 * u);
;             const f32x4 F0 = *(const LAS f32x4*)(wl + 16 * u + 8 * hh), F1 = *(const LAS f32x4*)(wl + 16 * u + 8 * hh + 4);
;             const f32x4 G0 = *(const LAS f32x4*)(wl + 256 + 16 * u + 8 * hh), G1 = *(const LAS f32x4*)(wl + 256 + 16 * u + 8 * hh + 4);
;             accf = MFMA32(A, scale8(X, F0, F1), accf); accb = MFMA32(A, scale8(X, G0, G1), accb);
;         }
;         bf16* of = Sst + ((((size_t)(b * 8 + head) * 2 + 0) * 8 + qb) * 64 + 32 * pblk + r) * 128 + 32 * nblk + 4 * hh;
;         bf16* ob = of + (size_t)8 * 64 * 128;
; #pragma unroll
;         for (int g4 = 0; g4 < 4; ++g4) {
;             u32x2 v; v.x = pk2(accf[4 * g4], accf[4 * g4 + 1]); v.y = pk2(accf[4 * g4 + 2], accf[4 * g4 + 3]); *(u32x2*)(of + 8 * g4) = v;
;             u32x2 q; q.x = pk2(accb[4 * g4], accb[4 * g4 + 1]); q.y = pk2(accb[4 * g4 + 2], accb[4 * g4 + 3]); *(u32x2*)(ob + 8 * g4) = q; }
	v_pk_mul_f32 v[58:59], v[88:89], v[58:59]
	v_cvt_pk_bf16_f32 v74, v78, v79
	v_cvt_pk_bf16_f32 v78, v58, v59
	v_lshlrev_b32_e32 v58, 16, v75
	v_and_b32_e32 v59, 0xffff0000, v75
	v_pk_mul_f32 v[80:81], v[82:83], v[58:59]
	v_pk_mul_f32 v[58:59], v[90:91], v[58:59]
	v_cvt_pk_bf16_f32 v75, v80, v81
	v_cvt_pk_bf16_f32 v79, v58, v59
	s_nop 0
	v_mfma_f32_32x32x16_bf16 v[0:15], v[68:71], v[72:75], v[0:15]
	v_mfma_f32_32x32x16_bf16 v[16:31], v[68:71], v[76:79], v[16:31]
	ds_read_b128 v[68:71], v65 offset:448
	ds_read_b128 v[72:75], v66 offset:448
	ds_read_b128 v[76:79], v61 offset:896
	ds_read_b128 v[80:83], v61 offset:912
	ds_read_b128 v[84:87], v62 offset:896
	ds_read_b128 v[88:91], v62 offset:912
	s_waitcnt lgkmcnt(4)
	v_lshlrev_b32_e32 v58, 16, v72
	v_and_b32_e32 v59, 0xffff0000, v72
	s_waitcnt lgkmcnt(3)
	v_pk_mul_f32 v[76:77], v[76:77], v[58:59]
	s_waitcnt lgkmcnt(1)
	v_pk_mul_f32 v[58:59], v[84:85], v[58:59]
	v_cvt_pk_bf16_f32 v72, v76, v77
	v_cvt_pk_bf16_f32 v76, v58, v59
	v_lshlrev_b32_e32 v58, 16, v73
	v_and_b32_e32 v59, 0xffff0000, v73
	v_pk_mul_f32 v[78:79], v[78:79], v[58:59]
	v_pk_mul_f32 v[58:59], v[86:87], v[58:59]
	v_cvt_pk_bf16_f32 v73, v78, v79
	v_cvt_pk_bf16_f32 v77, v58, v59
	v_lshlrev_b32_e32 v58, 16, v74
	v_and_b32_e32 v59, 0xffff0000, v74
	v_pk_mul_f32 v[78:79], v[80:81], v[58:59]
	s_waitcnt lgkmcnt(0)
	v_pk_mul_f32 v[58:59], v[88:89], v[58:59]
	v_cvt_pk_bf16_f32 v74, v78, v79
	v_cvt_pk_bf16_f32 v78, v58, v59
	v_lshlrev_b32_e32 v58, 16, v75
	v_and_b32_e32 v59, 0xffff0000, v75
	v_pk_mul_f32 v[80:81], v[82:83], v[58:59]
	v_pk_mul_f32 v[58:59], v[90:91], v[58:59]
	v_cvt_pk_bf16_f32 v75, v80, v81
	v_cvt_pk_bf16_f32 v79, v58, v59
	s_nop 0
	v_mfma_f32_32x32x16_bf16 v[0:15], v[68:71], v[72:75], v[0:15]
	v_mfma_f32_32x32x16_bf16 v[16:31], v[68:71], v[76:79], v[16:31]
	ds_read_b128 v[68:71], v65 offset:480
	ds_read_b128 v[72:75], v66 offset:480
	ds_read_b128 v[76:79], v61 offset:960
	ds_read_b128 v[80:83], v61 offset:976
	ds_read_b128 v[84:87], v62 offset:960
	ds_read_b128 v[88:91], v62 offset:976
	s_waitcnt lgkmcnt(4)
	v_lshlrev_b32_e32 v58, 16, v72
	v_and_b32_e32 v59, 0xffff0000, v72
	s_waitcnt lgkmcnt(3)
	v_pk_mul_f32 v[76:77], v[76:77], v[58:59]
	s_waitcnt lgkmcnt(1)
	v_pk_mul_f32 v[58:59], v[84:85], v[58:59]
	v_cvt_pk_bf16_f32 v72, v76, v77
	v_cvt_pk_bf16_f32 v76, v58, v59
	v_lshlrev_b32_e32 v58, 16, v73
	v_and_b32_e32 v59, 0xffff0000, v73
	v_pk_mul_f32 v[78:79], v[78:79], v[58:59]
	v_pk_mul_f32 v[58:59], v[86:87], v[58:59]
	v_cvt_pk_bf16_f32 v73, v78, v79
	v_cvt_pk_bf16_f32 v77, v58, v59
	v_lshlrev_b32_e32 v58, 16, v74
	v_and_b32_e32 v59, 0xffff0000, v74
	v_pk_mul_f32 v[78:79], v[80:81], v[58:59]
	s_waitcnt lgkmcnt(0)
	v_pk_mul_f32 v[58:59], v[88:89], v[58:59]
	v_cvt_pk_bf16_f32 v74, v78, v79
	v_cvt_pk_bf16_f32 v78, v58, v59
	v_lshlrev_b32_e32 v58, 16, v75
	v_and_b32_e32 v59, 0xffff0000, v75
	v_pk_mul_f32 v[80:81], v[82:83], v[58:59]
	v_pk_mul_f32 v[58:59], v[90:91], v[58:59]
	v_cvt_pk_bf16_f32 v75, v80, v81
	v_cvt_pk_bf16_f32 v79, v58, v59
	v_lshl_add_u64 v[58:59], v[36:37], 0, s[10:11]
	v_mfma_f32_32x32x16_bf16 v[0:15], v[68:71], v[72:75], v[0:15]
	v_lshlrev_b64 v[58:59], 8, v[58:59]
	s_mov_b32 s10, 0x20000
	v_mfma_f32_32x32x16_bf16 v[16:31], v[68:71], v[76:79], v[16:31]
	v_lshl_add_u64 v[68:69], v[38:39], 0, s[20:21]
	v_lshl_add_u64 v[58:59], v[68:69], 0, v[58:59]
	s_nop 6
	v_cvt_pk_bf16_f32 v0, v0, v1
	v_cvt_pk_bf16_f32 v1, v2, v3
	v_add_co_u32_e32 v2, vcc, s10, v58
	global_store_dwordx2 v[58:59], v[0:1], off
	v_cvt_pk_bf16_f32 v0, v16, v17
	v_cvt_pk_bf16_f32 v1, v18, v19
	v_addc_co_u32_e32 v3, vcc, 0, v59, vcc
	global_store_dwordx2 v[2:3], v[0:1], off
	v_cvt_pk_bf16_f32 v0, v4, v5
	v_cvt_pk_bf16_f32 v1, v6, v7
	global_store_dwordx2 v[58:59], v[0:1], off offset:16
	v_cvt_pk_bf16_f32 v0, v20, v21
	v_cvt_pk_bf16_f32 v1, v22, v23
	global_store_dwordx2 v[2:3], v[0:1], off offset:16
	v_cvt_pk_bf16_f32 v0, v8, v9
	v_cvt_pk_bf16_f32 v1, v10, v11
	global_store_dwordx2 v[58:59], v[0:1], off offset:32
	v_cvt_pk_bf16_f32 v0, v24, v25
	v_cvt_pk_bf16_f32 v1, v26, v27
	global_store_dwordx2 v[2:3], v[0:1], off offset:32
	v_cvt_pk_bf16_f32 v0, v12, v13
	v_cvt_pk_bf16_f32 v1, v14, v15
	global_store_dwordx2 v[58:59], v[0:1], off offset:48
	v_cvt_pk_bf16_f32 v0, v28, v29
	v_cvt_pk_bf16_f32 v1, v30, v31
	global_store_dwordx2 v[2:3], v[0:1], off offset:48
	s_cbranch_scc1 .LBB0_457
	s_mov_b64 s[88:89], s[0:1]
	s_mov_b64 s[82:83], s[30:31]

; __device__ __forceinline__ unsigned xb_ld(unsigned* p)              { return __hip_atomic_load(p, __ATOMIC_RELAXED, __HIP_MEMORY_SCOPE_AGENT); }
; __device__ __forceinline__ unsigned xb_add(unsigned* p, unsigned v) { return __hip_atomic_fetch_add(p, v, __ATOMIC_RELAXED, __HIP_MEMORY_SCOPE_AGENT); }
; #define XB_SPIN(cond, bar) do { unsigned _sp = 0; while (cond) { __builtin_amdgcn_s_sleep(1); \
;     if ((++_sp & 255u) == 0u) { if (xb_ld(&(bar)[XB_TMO])) break; if (_sp > XB_SPIN_CAP) { atomicAdd(&(bar)[XB_TMO], 1u); break; } } } } while (0)
; __device__ __forceinline__ void xcd_barrier(const XcdBarrier& b) {
;     ...
;         if (old + 1u == (gen + 1u) * nloc) {
;             __builtin_amdgcn_fence(__ATOMIC_RELEASE, "agent");
;             asm volatile("s_waitcnt vmcnt(0)" ::: "memory");
;             const unsigned og = xb_add(&bar[XB_TOP], 1u);
;             const unsigned tg = og / nx;
;             if (og + 1u == (tg + 1u) * nx) xb_add(&bar[XB_TOPGEN], 1u);
;             else XB_SPIN(xb_ld(&bar[XB_TOPGEN]) == tg, bar);
;             __builtin_amdgcn_fence(__ATOMIC_ACQUIRE, "agent");
;             xb_add(&bar[XB_XGEN(b.x)], 1u);
.LBB0_491:
	s_andn2_saveexec_b64 s[20:21], s[20:21]
	s_cbranch_execz .LBB0_511
	s_mov_b64 s[20:21], exec
	buffer_wbl2 sc1
	s_waitcnt lgkmcnt(0)
	s_waitcnt vmcnt(0)
	v_mov_b32_e32 v3, 0x23030
	ds_read_b32 v3, v3
	s_waitcnt lgkmcnt(0)
	v_readfirstlane_b32 s100, v3
	s_nop 0
	s_cmp_lg_u32 s100, 0
	s_cbranch_scc1 .Lloc_4
	v_mbcnt_lo_u32_b32 v1, s20, 0
	v_mbcnt_hi_u32_b32 v1, s21, v1
	v_cmp_eq_u32_e32 vcc, 0, v1
	s_and_saveexec_b64 s[22:23], vcc
	s_cbranch_execz .LBB0_494
	s_bcnt1_i32_b64 s20, s[20:21]
	v_readlane_b32 s0, v240, 16
	v_mov_b32_e32 v2, 0
	v_mov_b32_e32 v3, s20
	v_readlane_b32 s1, v240, 17
	s_nop 4
	global_atomic_add v2, v2, v3, s[0:1] sc0

; __device__ __forceinline__ unsigned xb_add(unsigned* p, unsigned v) { return __hip_atomic_fetch_add(p, v, __ATOMIC_RELAXED, __HIP_MEMORY_SCOPE_AGENT); }
; __device__ __forceinline__ void xcd_barrier(const XcdBarrier& b) {
;     ...
;             xb_add(&bar[XB_XGEN(b.x)], 1u);
;             asm volatile("s_waitcnt vmcnt(0)" ::: "memory");
.Lloc_4:
	s_mov_b64 s[20:21], exec
	v_mbcnt_lo_u32_b32 v0, s20, 0
	v_mbcnt_hi_u32_b32 v0, s21, v0
	v_cmp_eq_u32_e32 vcc, 0, v0
	s_waitcnt vmcnt(0)
	s_and_saveexec_b64 s[22:23], vcc
	s_cbranch_execz .LBB0_510
	s_bcnt1_i32_b64 s20, s[20:21]
	v_readlane_b32 s0, v240, 14
	v_mov_b32_e32 v0, 0
	v_mov_b32_e32 v1, s20
	v_readlane_b32 s1, v240, 15
	s_nop 4
	global_atomic_add v0, v1, s[0:1]

; __device__ __forceinline__ int opaque_tid() { int t = threadIdx.x; asm volatile("" : "+v"(t)); return t; }
; #define LAS __attribute__((address_space(3)))
; __device__ __forceinline__ void p0b_mlp_weights(const Args& a, LAS unsigned char* lds) {
;     const int tid = opaque_tid(), lane = tid & 63, wave = tid >> 6;
;     LAS float* scr = (LAS float*)(lds + wave * 16640);
;     const int gw = blockIdx.x * NWAVES + wave, NGW = gridDim.x * NWAVES;
;     constexpr int I_UP = (D_ / 64) * (FF / 64), I_DN = (FF / 64) * (D_ / 64);
;     for (int it = gw; it < I_UP + I_DN; it += NGW) {
;         if (it < I_UP) transpose_item(a.w_up, D_, FF, (bf16*)(a.ws + WS_WUP), a.ln_mlp_g, scr, it, FF / 64, lane);
;         else transpose_item(a.w_dn, FF, D_, (bf16*)(a.ws + WS_WDN), nullptr, scr, it - I_UP, D_ / 64, lane);
;     }
; __global__ void __launch_bounds__(NTHREADS, 2) fwd_megakernel(Args a) {
;     ...
;         float mq = 0.f, mk = 0.f;
;         for (int i = 0; i < 96; ++i) { mq = fmaxf(mq, fabsf(a.q_norm_g[i])); mk = fmaxf(mk, fabsf(a.k_norm_g[i])); }
;         const float mb = fminf(96.f * mq * mk * 0.10206207261596577f * LOG2E, 80.f);
;         unsigned* s2cnt = (unsigned*)(ws + WS_BAR) + XCD_BAR_WORDS + 64;
;         p0b_mlp_weights(a, lds);
.LBB0_512:
	s_add_u32 s20, s72, s10
	s_addc_u32 s21, s73, s11
	global_load_dwordx4 v[2:5], v0, s[20:21] offset:32
	global_load_dwordx4 v[6:9], v0, s[20:21] offset:16
	global_load_dwordx4 v[10:13], v0, s[20:21]
	s_add_u32 s20, s74, s10
	s_addc_u32 s21, s75, s11
	global_load_dwordx4 v[14:17], v0, s[20:21]
	global_load_dwordx4 v[18:21], v0, s[20:21] offset:16
	global_load_dwordx4 v[22:25], v0, s[20:21] offset:32
	s_add_u32 s10, s10, 48
	s_addc_u32 s11, s11, 0
	s_cmpk_eq_i32 s10, 0x180
	s_waitcnt vmcnt(3)
	v_max3_f32 v1, v82, |v10|, |v11|
	v_max3_f32 v1, v1, |v12|, |v13|
	s_waitcnt vmcnt(2)
	v_max3_f32 v10, v83, |v14|, |v15|
	v_max3_f32 v1, v1, |v6|, |v7|
	v_max3_f32 v6, v10, |v16|, |v17|
	v_max3_f32 v1, v1, |v8|, |v9|
	s_waitcnt vmcnt(1)
	v_max3_f32 v6, v6, |v18|, |v19|
	v_max3_f32 v1, v1, |v2|, |v3|
	v_max3_f32 v2, v6, |v20|, |v21|
	v_max3_f32 v82, v1, |v4|, |v5|
	s_waitcnt vmcnt(0)
	v_max3_f32 v1, v2, |v22|, |v23|
	v_max3_f32 v83, v1, |v24|, |v25|
	s_cbranch_scc0 .LBB0_512
	s_add_u32 s10, s92, 0xf6a0000
	v_mov_b32_e32 v0, v210
	s_addc_u32 s11, s93, 0
	v_readlane_b32 s0, v241, 19
	v_ashrrev_i32_e32 v1, 6, v0
	s_add_u32 s50, s92, 0xeea0000
	v_add_u32_e32 v84, s0, v1
	v_add_u32_e32 v84, 0x400, v84
	s_movk_i32 s20, 0
	s_addc_u32 s51, s93, 0
	v_cmp_gt_i32_e32 vcc, s20, v84
	s_and_saveexec_b64 s[20:21], vcc
	v_readlane_b32 s64, v241, 2
	v_readlane_b32 s72, v241, 10
	v_readlane_b32 s73, v241, 11
	v_readlane_b32 s74, v241, 12
	v_readlane_b32 s75, v241, 13
	v_readlane_b32 s76, v241, 14
	v_readlane_b32 s77, v241, 15
	v_readlane_b32 s78, v241, 16
	v_readlane_b32 s79, v241, 17
	v_readlane_b32 s65, v241, 3
	v_readlane_b32 s66, v241, 4
	v_readlane_b32 s67, v241, 5
	v_readlane_b32 s68, v241, 6
	v_readlane_b32 s69, v241, 7
	v_readlane_b32 s70, v241, 8
	v_readlane_b32 s71, v241, 9
	s_cbranch_execz .LBB0_554
	s_movk_i32 s24, 0x4100
	v_mul_lo_u32 v2, v1, s24
	v_add_u32_e32 v3, 0, v2
	v_bfe_u32 v85, v0, 4, 2
	v_lshlrev_b32_e32 v2, 2, v0
	v_bfe_u32 v87, v0, 3, 3
	v_lshlrev_b32_e32 v0, 3, v0
	v_and_b32_e32 v6, 56, v0
	v_and_b32_e32 v86, 60, v2
	v_mul_u32_u24_e32 v0, 0x104, v6
	v_lshlrev_b32_e32 v7, 2, v87
	v_lshlrev_b32_e32 v2, 2, v86
	v_add3_u32 v88, v3, v0, v7
	v_mov_b32_e32 v0, 0
	v_readlane_b32 s0, v241, 18
	v_add_u32_e32 v4, v3, v2
	v_mul_u32_u24_e32 v5, 0x104, v85
	v_mov_b32_e32 v3, v0
	v_lshl_add_u32 v96, v1, 6, s0
	v_add_u32_e32 v96, 0x10000, v96
	v_lshlrev_b32_e32 v1, 2, v1
	s_cmp_lg_u64 s[72:73], 0
	v_lshl_add_u64 v[68:69], s[76:77], 0, v[2:3]
	v_lshl_add_u64 v[70:71], s[74:75], 0, v[2:3]
	v_lshlrev_b32_e32 v2, 1, v6
	v_lshl_add_u32 v1, s2, 5, v1
	v_add_u32_e32 v98, v4, v5
	s_mov_b64 s[22:23], 0
	s_cselect_b64 s[42:43], -1, 0
	v_or_b32_e32 v89, 8, v87
	v_or_b32_e32 v90, 16, v87
	v_or_b32_e32 v91, 24, v87
	v_or_b32_e32 v92, 32, v87
	v_or_b32_e32 v93, 40, v87
	v_or_b32_e32 v94, 48, v87
	v_or_b32_e32 v95, 56, v87
	v_lshl_add_u64 v[72:73], s[10:11], 0, v[2:3]
	v_lshl_add_u64 v[74:75], s[50:51], 0, v[2:3]
	v_add_u32_e32 v97, 0x40000, v1
	s_lshl_b32 s26, s94, 5
	v_add_u32_e32 v99, 0x410, v98
	v_add_u32_e32 v100, 0x418, v98
	v_add_u32_e32 v101, 0x820, v98
	v_add_u32_e32 v102, 0x828, v98
	v_add_u32_e32 v103, 0xc30, v98
	v_add_u32_e32 v104, 0xc38, v98
	v_add_u32_e32 v105, 0x1040, v98
	v_add_u32_e32 v106, 0x1048, v98
	v_add_u32_e32 v107, 0x1450, v98
	v_add_u32_e32 v108, 0x1458, v98
	v_add_u32_e32 v109, 0x1860, v98
	v_add_u32_e32 v110, 0x1868, v98
	v_add_u32_e32 v111, 0x1c70, v98
	v_add_u32_e32 v112, 0x1c78, v98
	v_add_u32_e32 v113, 0x2080, v98
	v_add_u32_e32 v114, 0x2088, v98
	v_add_u32_e32 v115, 0x2490, v98
	v_add_u32_e32 v116, 0x2498, v98
	v_add_u32_e32 v117, 0x28a0, v98
	v_add_u32_e32 v118, 0x28a8, v98
	v_add_u32_e32 v119, 0x2cb0, v98
	v_add_u32_e32 v120, 0x2cb8, v98
	v_add_u32_e32 v121, 0x30c0, v98
	v_add_u32_e32 v122, 0x30c8, v98
	v_add_u32_e32 v123, 0x34d0, v98
	s_branch .LBB0_517

; __device__ __forceinline__ int opaque_tid() { int t = threadIdx.x; asm volatile("" : "+v"(t)); return t; }
; __device__ __forceinline__ float ex2(float x) { return __builtin_amdgcn_exp2f(x); }
; __device__ __forceinline__ void ssd_state_scan(const Args& a) {
;     const int tid = opaque_tid();
;     const float* vec = (const float*)(a.ws + WS_VEC);
;     const size_t VS = (size_t)NB * 8 * S_;
;     const bf16* Sst = (const bf16*)a.out; bf16* Hst = (bf16*)a.out + HST_OFF;
;     for (int e = blockIdx.x * NTHREADS + tid; e < NB * 8 * 2 * 1024; e += gridDim.x * NTHREADS) {
;         const int seq = e >> 10, off = (e & 1023) * 8, dir = seq & 1, bh = seq >> 1;
;         const float* vb = vec + (size_t)bh * S_;
;         const size_t base = (size_t)seq * 8 * 8192 + off;
;         u32x4 sv[8]; float dec[8];
; #pragma unroll
;         for (int i = 0; i < 8; ++i) { const int qb = dir ? 7 - i : i; sv[i] = *(const u32x4*)(Sst + base + (size_t)qb * 8192);
;             const int L0 = qb * 256, L1 = L0 + 255;
;             if (dir == 0) dec[i] = ex2(vb[L1] - (qb ? vb[L0 - 1] : 0.f)); else dec[i] = ex2(vb[VS + L0] - (qb < 7 ? vb[VS + L1 + 1] : 0.f)); }
.Lgb4_done:
	v_mov_b32_e32 v0, v210
	v_readlane_b32 s0, v241, 18
	s_and_b32 s98, s2, 7
	s_lshl_b32 s98, s98, 5
	s_bfe_u32 s99, s2, 0x50003
	s_or_b32 s99, s99, s98
	s_cmp_eq_u32 s94, 0x100
	s_cselect_b32 s99, s99, s2
	s_lshl_b32 s0, s99, 9
	s_add_u32 s42, s78, 0x1000000
	s_barrier
	s_mov_b32 s20, 0x20000
	v_add_u32_e32 v33, s0, v0
	s_addc_u32 s43, s79, 0
	v_cmp_gt_i32_e32 vcc, s20, v33
	s_and_saveexec_b64 s[20:21], vcc
	v_readlane_b32 s70, v240, 35
	v_readlane_b32 s37, v240, 34
	v_readlane_b32 s71, v240, 36
	s_mov_b64 s[64:65], s[38:39]
	s_mov_b64 s[66:67], s[96:97]
	s_mov_b64 s[68:69], s[90:91]
	s_cbranch_execz .LBB0_557
	v_lshlrev_b32_e32 v0, 3, v0
	v_mov_b32_e32 v17, 0
	v_lshl_add_u32 v37, s99, 12, v0
	s_lshl_b32 s24, s94, 12
	s_mov_b64 s[22:23], 0
	v_mov_b32_e32 v41, 0x80000
	v_mov_b32_e32 v42, 0x3fc
	v_mov_b32_e32 v43, 0x80400
	v_mov_b32_e32 v44, 0x1c000
	v_mov_b32_e32 v46, v17
	v_mov_b32_e32 v47, v17
	v_mov_b32_e32 v48, v17
	v_mov_b32_e32 v49, v17
	s_mov_b32 s25, 0x1ffff

; __device__ __forceinline__ unsigned xb_ld(unsigned* p)              { return __hip_atomic_load(p, __ATOMIC_RELAXED, __HIP_MEMORY_SCOPE_AGENT); }
; __device__ __forceinline__ unsigned xb_add(unsigned* p, unsigned v) { return __hip_atomic_fetch_add(p, v, __ATOMIC_RELAXED, __HIP_MEMORY_SCOPE_AGENT); }
; #define XB_SPIN(cond, bar) do { unsigned _sp = 0; while (cond) { __builtin_amdgcn_s_sleep(1); \
;     if ((++_sp & 255u) == 0u) { if (xb_ld(&(bar)[XB_TMO])) break; if (_sp > XB_SPIN_CAP) { atomicAdd(&(bar)[XB_TMO], 1u); break; } } } } while (0)
; __device__ __forceinline__ void xcd_barrier(const XcdBarrier& b) {
;     asm volatile("s_waitcnt vmcnt(0)" ::: "memory");
;     __syncthreads();
;     if (threadIdx.x == 0) {
;         unsigned* bar = b.bar;
;         __builtin_amdgcn_s_waitcnt(0);
;         unsigned nloc = b.st[0], nx = b.st[1];
;         if (nloc == 0u) { xcd_barrier_complete(bar, b.x, nloc, nx); b.st[0] = nloc; b.st[1] = nx; }
;         const unsigned old = xb_add(&bar[XB_XSUB(b.x)], 1u);
;         const unsigned gen = old / nloc;
;         if (old + 1u == (gen + 1u) * nloc) {
;             __builtin_amdgcn_fence(__ATOMIC_RELEASE, "agent");
;             asm volatile("s_waitcnt vmcnt(0)" ::: "memory");
;             const unsigned og = xb_add(&bar[XB_TOP], 1u);
;             const unsigned tg = og / nx;
;             if (og + 1u == (tg + 1u) * nx) xb_add(&bar[XB_TOPGEN], 1u);
;             else XB_SPIN(xb_ld(&bar[XB_TOPGEN]) == tg, bar);
;             __builtin_amdgcn_fence(__ATOMIC_ACQUIRE, "agent");
;             xb_add(&bar[XB_XGEN(b.x)], 1u);
;             asm volatile("s_waitcnt vmcnt(0)" ::: "memory");
.LBB0_684:
	s_andn2_saveexec_b64 s[18:19], s[18:19]
	s_cbranch_execz .LBB0_704
	s_mov_b64 s[18:19], exec
	buffer_wbl2 sc1
	s_waitcnt lgkmcnt(0)
	s_waitcnt vmcnt(0)
	v_mov_b32_e32 v3, 0x23030
	ds_read_b32 v3, v3
	s_waitcnt lgkmcnt(0)
	v_readfirstlane_b32 s100, v3
	s_nop 0
	s_cmp_lg_u32 s100, 0
	s_cbranch_scc1 .Lloc_5
	v_mbcnt_lo_u32_b32 v1, s18, 0
	v_mbcnt_hi_u32_b32 v1, s19, v1
	v_cmp_eq_u32_e32 vcc, 0, v1
	s_and_saveexec_b64 s[20:21], vcc
	s_cbranch_execz .LBB0_687
	s_bcnt1_i32_b64 s18, s[18:19]
	v_readlane_b32 s4, v240, 16
	v_mov_b32_e32 v2, 0
	v_mov_b32_e32 v3, s18
	v_readlane_b32 s5, v240, 17
	s_nop 4
	global_atomic_add v2, v2, v3, s[4:5] sc0

; __device__ __forceinline__ unsigned xb_ld(unsigned* p)              { return __hip_atomic_load(p, __ATOMIC_RELAXED, __HIP_MEMORY_SCOPE_AGENT); }
; __device__ __forceinline__ unsigned xb_add(unsigned* p, unsigned v) { return __hip_atomic_fetch_add(p, v, __ATOMIC_RELAXED, __HIP_MEMORY_SCOPE_AGENT); }
; #define XB_SPIN(cond, bar) do { unsigned _sp = 0; while (cond) { __builtin_amdgcn_s_sleep(1); \
;     if ((++_sp & 255u) == 0u) { if (xb_ld(&(bar)[XB_TMO])) break; if (_sp > XB_SPIN_CAP) { atomicAdd(&(bar)[XB_TMO], 1u); break; } } } } while (0)
; __device__ __forceinline__ void xcd_barrier(const XcdBarrier& b) {
;     asm volatile("s_waitcnt vmcnt(0)" ::: "memory");
;     __syncthreads();
;     if (threadIdx.x == 0) {
;         unsigned* bar = b.bar;
;         __builtin_amdgcn_s_waitcnt(0);
;         unsigned nloc = b.st[0], nx = b.st[1];
;         if (nloc == 0u) { xcd_barrier_complete(bar, b.x, nloc, nx); b.st[0] = nloc; b.st[1] = nx; }
;         const unsigned old = xb_add(&bar[XB_XSUB(b.x)], 1u);
;         const unsigned gen = old / nloc;
;         if (old + 1u == (gen + 1u) * nloc) {
;             __builtin_amdgcn_fence(__ATOMIC_RELEASE, "agent");
;             asm volatile("s_waitcnt vmcnt(0)" ::: "memory");
;             const unsigned og = xb_add(&bar[XB_TOP], 1u);
;             const unsigned tg = og / nx;
;             if (og + 1u == (tg + 1u) * nx) xb_add(&bar[XB_TOPGEN], 1u);
;             else XB_SPIN(xb_ld(&bar[XB_TOPGEN]) == tg, bar);
;             __builtin_amdgcn_fence(__ATOMIC_ACQUIRE, "agent");
;             xb_add(&bar[XB_XGEN(b.x)], 1u);
;             asm volatile("s_waitcnt vmcnt(0)" ::: "memory");
.LBB0_797:
	s_andn2_saveexec_b64 s[8:9], s[8:9]
	s_cbranch_execz .LBB0_817
	s_mov_b64 s[8:9], exec
	buffer_wbl2 sc1
	s_waitcnt lgkmcnt(0)
	s_waitcnt vmcnt(0)
	v_mov_b32_e32 v3, 0x23030
	ds_read_b32 v3, v3
	s_waitcnt lgkmcnt(0)
	v_readfirstlane_b32 s100, v3
	s_nop 0
	s_cmp_lg_u32 s100, 0
	s_cbranch_scc1 .Lloc_6
	v_mbcnt_lo_u32_b32 v1, s8, 0
	v_mbcnt_hi_u32_b32 v1, s9, v1
	v_cmp_eq_u32_e32 vcc, 0, v1
	s_and_saveexec_b64 s[16:17], vcc
	s_cbranch_execz .LBB0_800
	s_bcnt1_i32_b64 s8, s[8:9]
	v_readlane_b32 s4, v240, 16
	v_mov_b32_e32 v2, 0
	v_mov_b32_e32 v3, s8
	v_readlane_b32 s5, v240, 17
	s_nop 4
	global_atomic_add v2, v2, v3, s[4:5] sc0

; __device__ __forceinline__ unsigned xb_ld(unsigned* p)              { return __hip_atomic_load(p, __ATOMIC_RELAXED, __HIP_MEMORY_SCOPE_AGENT); }
; __device__ __forceinline__ unsigned xb_add(unsigned* p, unsigned v) { return __hip_atomic_fetch_add(p, v, __ATOMIC_RELAXED, __HIP_MEMORY_SCOPE_AGENT); }
; #define XB_SPIN(cond, bar) do { unsigned _sp = 0; while (cond) { __builtin_amdgcn_s_sleep(1); \
;     if ((++_sp & 255u) == 0u) { if (xb_ld(&(bar)[XB_TMO])) break; if (_sp > XB_SPIN_CAP) { atomicAdd(&(bar)[XB_TMO], 1u); break; } } } } while (0)
; __device__ __forceinline__ void xcd_barrier(const XcdBarrier& b) {
;     asm volatile("s_waitcnt vmcnt(0)" ::: "memory");
;     __syncthreads();
;     if (threadIdx.x == 0) {
;         unsigned* bar = b.bar;
;         __builtin_amdgcn_s_waitcnt(0);
;         unsigned nloc = b.st[0], nx = b.st[1];
;         if (nloc == 0u) { xcd_barrier_complete(bar, b.x, nloc, nx); b.st[0] = nloc; b.st[1] = nx; }
;         const unsigned old = xb_add(&bar[XB_XSUB(b.x)], 1u);
;         const unsigned gen = old / nloc;
;         if (old + 1u == (gen + 1u) * nloc) {
;             __builtin_amdgcn_fence(__ATOMIC_RELEASE, "agent");
;             asm volatile("s_waitcnt vmcnt(0)" ::: "memory");
;             const unsigned og = xb_add(&bar[XB_TOP], 1u);
;             const unsigned tg = og / nx;
;             if (og + 1u == (tg + 1u) * nx) xb_add(&bar[XB_TOPGEN], 1u);
;             else XB_SPIN(xb_ld(&bar[XB_TOPGEN]) == tg, bar);
;             __builtin_amdgcn_fence(__ATOMIC_ACQUIRE, "agent");
;             xb_add(&bar[XB_XGEN(b.x)], 1u);
;             asm volatile("s_waitcnt vmcnt(0)" ::: "memory");
.LBB0_876:
	s_andn2_saveexec_b64 s[4:5], s[4:5]
	s_cbranch_execz .LBB0_896
	s_mov_b64 s[4:5], exec
	buffer_wbl2 sc1
	s_waitcnt lgkmcnt(0)
	s_waitcnt vmcnt(0)
	v_mov_b32_e32 v3, 0x23030
	ds_read_b32 v3, v3
	s_waitcnt lgkmcnt(0)
	v_readfirstlane_b32 s100, v3
	s_nop 0
	s_cmp_lg_u32 s100, 0
	s_cbranch_scc1 .Lloc_7
	v_mbcnt_lo_u32_b32 v1, s4, 0
	v_mbcnt_hi_u32_b32 v1, s5, v1
	v_cmp_eq_u32_e32 vcc, 0, v1
	s_and_saveexec_b64 s[6:7], vcc
	s_cbranch_execz .LBB0_879
	s_bcnt1_i32_b64 s4, s[4:5]
	v_mov_b32_e32 v3, s4
	v_readlane_b32 s4, v240, 16
	v_mov_b32_e32 v2, 0
	v_readlane_b32 s5, v240, 17
	s_nop 4
	global_atomic_add v2, v2, v3, s[4:5] sc0
